# baseline (speedup 1.0000x reference)
; __device__ __forceinline__ float siluf(float v) { return v * __builtin_amdgcn_rcpf(1.f + __expf(-v)); }
; __device__ __forceinline__ float sigmf(float v) { return __builtin_amdgcn_rcpf(1.f + __expf(-v)); }
; #define FOR_FRAG(ai, bj, m, n) _Pragma("unroll") for (int ai = 0; ai < 2; ++ai) _Pragma("unroll") for (int bj = 0; bj < 2; ++bj) \
;   _Pragma("unroll") for (int m = 0; m < 4; ++m) _Pragma("unroll") for (int n = 0; n < 2; ++n)
; __device__ __forceinline__ u32x2 pack4(float a, float b, float c, float d) { return u32x2{cvtpk(a, b), cvtpk(c, d)}; }
; __device__ __forceinline__ void phase2(const Params& p, char* shm) {
;     ...
;       } else if (pn < 28) {
;         const bool isk = pn < 24;
;         int bb, s0; if (isctx) { bb = pm; s0 = SEQ; } else { bb = brow >> 12; s0 = brow & 4095; }
;         dst = (isk ? Kb : Vb) + ((size_t)bb * SKV + s0) * AW + (isk ? pn - 20 : pn - 24) * 256;
;         FOR_FRAG(ai, bj, m, n) { const f32x4 v = acc[ai][bj][m][n]; *(u32x2*)(ctb + CT_OFF(ai, bj, m, n)) = pack4(v[0], v[1], v[2], v[3]); }
;       } else if (pn < 32) {
;         dst = Zb + (size_t)brow * AW + (pn - 28) * 256;
;         FOR_FRAG(ai, bj, m, n) { const f32x4 v = acc[ai][bj][m][n]; *(u32x2*)(ctb + CT_OFF(ai, bj, m, n)) = pack4(siluf(v[0]), siluf(v[1]), siluf(v[2]), siluf(v[3])); }
;       } else {
;         dst = Gates + (size_t)brow * 4096 + (pn - 32) * 256; ldd = 4096;
;         FOR_FRAG(ai, bj, m, n) { const f32x4 v = acc[ai][bj][m][n]; *(u32x2*)(ctb + CT_OFF(ai, bj, m, n)) = pack4(sigmf(v[0]), sigmf(v[1]), sigmf(v[2]), sigmf(v[3])); }
;       }
.LBB0_202:
	s_mov_b64 s[44:45], 0x400
	s_and_b64 vcc, exec, s[46:47]
	s_cbranch_vccz .LBB0_211
	s_cmp_gt_u32 s38, 27
	s_mov_b64 s[46:47], -1
	s_cbranch_scc0 .LBB0_209
	s_ashr_i32 s41, s40, 31
	s_cmp_gt_u32 s38, 31
	s_mov_b64 s[44:45], -1
	v_mul_f32_e32 v221, 0xbfb8aa3b, v122
	v_mul_f32_e32 v220, 0xbfb8aa3b, v123
	v_mul_f32_e32 v219, 0xbfb8aa3b, v124
	v_mul_f32_e32 v218, 0xbfb8aa3b, v125
	v_mul_f32_e32 v217, 0xbfb8aa3b, v110
	v_mul_f32_e32 v216, 0xbfb8aa3b, v111
	v_mul_f32_e32 v215, 0xbfb8aa3b, v112
	v_mul_f32_e32 v214, 0xbfb8aa3b, v113
	v_mul_f32_e32 v213, 0xbfb8aa3b, v106
	v_mul_f32_e32 v212, 0xbfb8aa3b, v107
	v_mul_f32_e32 v211, 0xbfb8aa3b, v108
	v_mul_f32_e32 v210, 0xbfb8aa3b, v109
	v_mul_f32_e32 v209, 0xbfb8aa3b, v94
	v_mul_f32_e32 v208, 0xbfb8aa3b, v95
	v_mul_f32_e32 v207, 0xbfb8aa3b, v96
	v_mul_f32_e32 v206, 0xbfb8aa3b, v97
	v_mul_f32_e32 v205, 0xbfb8aa3b, v90
	v_mul_f32_e32 v204, 0xbfb8aa3b, v91
	v_mul_f32_e32 v203, 0xbfb8aa3b, v92
	v_mul_f32_e32 v202, 0xbfb8aa3b, v93
	v_mul_f32_e32 v201, 0xbfb8aa3b, v74
	v_mul_f32_e32 v200, 0xbfb8aa3b, v75
	v_mul_f32_e32 v199, 0xbfb8aa3b, v76
	v_mul_f32_e32 v198, 0xbfb8aa3b, v77
	v_mul_f32_e32 v197, 0xbfb8aa3b, v66
	v_mul_f32_e32 v196, 0xbfb8aa3b, v67
	v_mul_f32_e32 v195, 0xbfb8aa3b, v68
	v_mul_f32_e32 v194, 0xbfb8aa3b, v69
	v_mul_f32_e32 v193, 0xbfb8aa3b, v50
	v_mul_f32_e32 v192, 0xbfb8aa3b, v51
	v_mul_f32_e32 v191, 0xbfb8aa3b, v52
	v_mul_f32_e32 v190, 0xbfb8aa3b, v53
	v_mul_f32_e32 v189, 0xbfb8aa3b, v126
	v_mul_f32_e32 v188, 0xbfb8aa3b, v127
	v_mul_f32_e32 v187, 0xbfb8aa3b, v128
	v_mul_f32_e32 v185, 0xbfb8aa3b, v129
	v_mul_f32_e32 v184, 0xbfb8aa3b, v114
	v_mul_f32_e32 v183, 0xbfb8aa3b, v115
	v_mul_f32_e32 v182, 0xbfb8aa3b, v116
	v_mul_f32_e32 v181, 0xbfb8aa3b, v117
	v_mul_f32_e32 v180, 0xbfb8aa3b, v98
	v_mul_f32_e32 v179, 0xbfb8aa3b, v99
	v_mul_f32_e32 v178, 0xbfb8aa3b, v100
	v_mul_f32_e32 v177, 0xbfb8aa3b, v101
	v_mul_f32_e32 v176, 0xbfb8aa3b, v82
	v_mul_f32_e32 v175, 0xbfb8aa3b, v83
	v_mul_f32_e32 v174, 0xbfb8aa3b, v84
	v_mul_f32_e32 v173, 0xbfb8aa3b, v85
	v_mul_f32_e32 v172, 0xbfb8aa3b, v70
	v_mul_f32_e32 v162, 0xbfb8aa3b, v71
	v_mul_f32_e32 v161, 0xbfb8aa3b, v72
	v_mul_f32_e32 v160, 0xbfb8aa3b, v73
	v_mul_f32_e32 v159, 0xbfb8aa3b, v46
	v_mul_f32_e32 v158, 0xbfb8aa3b, v47
	v_mul_f32_e32 v157, 0xbfb8aa3b, v48
	v_mul_f32_e32 v156, 0xbfb8aa3b, v49
	v_mul_f32_e32 v155, 0xbfb8aa3b, v42
	v_mul_f32_e32 v154, 0xbfb8aa3b, v43
	v_mul_f32_e32 v153, 0xbfb8aa3b, v44
	v_mul_f32_e32 v152, 0xbfb8aa3b, v45
	v_mul_f32_e32 v151, 0xbfb8aa3b, v30
	v_mul_f32_e32 v150, 0xbfb8aa3b, v31
	v_mul_f32_e32 v149, 0xbfb8aa3b, v32
	v_mul_f32_e32 v148, 0xbfb8aa3b, v33
	v_mul_f32_e32 v147, 0xbfb8aa3b, v26
	v_mul_f32_e32 v146, 0xbfb8aa3b, v27
	v_mul_f32_e32 v145, 0xbfb8aa3b, v28
	v_mul_f32_e32 v144, 0xbfb8aa3b, v29
	v_mul_f32_e32 v143, 0xbfb8aa3b, v14
	v_mul_f32_e32 v142, 0xbfb8aa3b, v15
	v_mul_f32_e32 v141, 0xbfb8aa3b, v16
	v_mul_f32_e32 v140, 0xbfb8aa3b, v17
	v_mul_f32_e32 v139, 0xbfb8aa3b, v10
	v_mul_f32_e32 v138, 0xbfb8aa3b, v11
	s_waitcnt vmcnt(0)
	v_mul_f32_e32 v137, 0xbfb8aa3b, v12
	v_mul_f32_e32 v136, 0xbfb8aa3b, v13
	v_mul_f32_e32 v135, 0xbfb8aa3b, v2
	v_mul_f32_e32 v134, 0xbfb8aa3b, v3
	v_mul_f32_e32 v133, 0xbfb8aa3b, v4
	v_mul_f32_e32 v132, 0xbfb8aa3b, v5
	v_mul_f32_e32 v131, 0xbfb8aa3b, v78
	v_mul_f32_e32 v130, 0xbfb8aa3b, v79
	s_cbranch_scc0 .LBB0_206
	v_exp_f32_e32 v222, v221
	v_exp_f32_e32 v223, v220
	v_exp_f32_e32 v224, v219
	v_exp_f32_e32 v225, v218
	v_exp_f32_e32 v226, v217
	v_add_f32_e32 v222, 1.0, v222
	v_add_f32_e32 v223, 1.0, v223
	v_add_f32_e32 v224, 1.0, v224
	v_rcp_f32_e32 v222, v222
	v_rcp_f32_e32 v223, v223
	v_rcp_f32_e32 v224, v224
	v_add_f32_e32 v225, 1.0, v225
	v_rcp_f32_e32 v225, v225
	s_nop 0
	v_cvt_pk_bf16_f32 v222, v222, v223
	s_nop 0
	v_cvt_pk_bf16_f32 v223, v224, v225
	v_exp_f32_e32 v224, v216
	v_add_f32_e32 v225, 1.0, v226
	v_exp_f32_e32 v226, v215
	v_exp_f32_e32 v227, v214
	v_add_f32_e32 v224, 1.0, v224
	v_rcp_f32_e32 v224, v224
	v_add_f32_e32 v226, 1.0, v226
	v_add_f32_e32 v227, 1.0, v227
	v_rcp_f32_e32 v225, v225
	v_rcp_f32_e32 v226, v226
	v_rcp_f32_e32 v227, v227
	ds_write_b64 v171, v[222:223]
	s_nop 0
	v_cvt_pk_bf16_f32 v222, v225, v224
	v_exp_f32_e32 v224, v212
	v_exp_f32_e32 v228, v213
	s_nop 0
	v_cvt_pk_bf16_f32 v223, v226, v227
	v_exp_f32_e32 v226, v211
	v_exp_f32_e32 v227, v210
	v_add_f32_e32 v224, 1.0, v224
	v_add_f32_e32 v225, 1.0, v228
	v_rcp_f32_e32 v224, v224
	v_add_f32_e32 v226, 1.0, v226
	v_add_f32_e32 v227, 1.0, v227
	v_rcp_f32_e32 v225, v225
	v_rcp_f32_e32 v226, v226
	v_rcp_f32_e32 v227, v227
	ds_write_b64 v171, v[222:223] offset:32
	s_nop 0
	v_cvt_pk_bf16_f32 v222, v225, v224
	v_exp_f32_e32 v224, v208
	v_exp_f32_e32 v228, v209
	s_nop 0
	v_cvt_pk_bf16_f32 v223, v226, v227
	v_exp_f32_e32 v226, v207
	v_exp_f32_e32 v227, v206
	v_add_f32_e32 v224, 1.0, v224
	v_add_f32_e32 v225, 1.0, v228
	v_rcp_f32_e32 v224, v224
	v_add_f32_e32 v226, 1.0, v226
	v_add_f32_e32 v227, 1.0, v227
	v_rcp_f32_e32 v225, v225
	v_rcp_f32_e32 v226, v226
	v_rcp_f32_e32 v227, v227
	ds_write_b64 v171, v[222:223] offset:8448
	s_nop 0
	v_cvt_pk_bf16_f32 v222, v225, v224
	v_exp_f32_e32 v224, v204
	v_exp_f32_e32 v228, v205
	s_nop 0
	v_cvt_pk_bf16_f32 v223, v226, v227
	v_exp_f32_e32 v226, v203
	v_exp_f32_e32 v227, v202
	v_add_f32_e32 v224, 1.0, v224
	v_add_f32_e32 v225, 1.0, v228
	v_rcp_f32_e32 v224, v224
	v_add_f32_e32 v226, 1.0, v226
	v_add_f32_e32 v227, 1.0, v227
	v_rcp_f32_e32 v225, v225
	v_rcp_f32_e32 v226, v226
	v_rcp_f32_e32 v227, v227
	ds_write_b64 v171, v[222:223] offset:8480
	s_nop 0
	v_cvt_pk_bf16_f32 v222, v225, v224
	v_exp_f32_e32 v224, v200
	v_exp_f32_e32 v228, v201
	s_nop 0
	v_cvt_pk_bf16_f32 v223, v226, v227
; __device__ __forceinline__ float sigmf(float v) { return __builtin_amdgcn_rcpf(1.f + __expf(-v)); }
; #define FOR_FRAG(ai, bj, m, n) _Pragma("unroll") for (int ai = 0; ai < 2; ++ai) _Pragma("unroll") for (int bj = 0; bj < 2; ++bj) \
;   _Pragma("unroll") for (int m = 0; m < 4; ++m) _Pragma("unroll") for (int n = 0; n < 2; ++n)
; __device__ __forceinline__ u32x2 pack4(float a, float b, float c, float d) { return u32x2{cvtpk(a, b), cvtpk(c, d)}; }
; __device__ __forceinline__ void phase2(const Params& p, char* shm) {
;     ...
;       } else {
;         dst = Gates + (size_t)brow * 4096 + (pn - 32) * 256; ldd = 4096;
;         FOR_FRAG(ai, bj, m, n) { const f32x4 v = acc[ai][bj][m][n]; *(u32x2*)(ctb + CT_OFF(ai, bj, m, n)) = pack4(sigmf(v[0]), sigmf(v[1]), sigmf(v[2]), sigmf(v[3])); }
	v_exp_f32_e32 v226, v199
	v_exp_f32_e32 v227, v198
	v_add_f32_e32 v224, 1.0, v224
	v_add_f32_e32 v225, 1.0, v228
	v_rcp_f32_e32 v224, v224
	v_add_f32_e32 v226, 1.0, v226
	v_add_f32_e32 v227, 1.0, v227
	v_rcp_f32_e32 v225, v225
	v_rcp_f32_e32 v226, v226
	v_rcp_f32_e32 v227, v227
	ds_write_b64 v171, v[222:223] offset:16896
	s_nop 0
	v_cvt_pk_bf16_f32 v222, v225, v224
	v_exp_f32_e32 v224, v196
	v_exp_f32_e32 v228, v197
	s_nop 0
	v_cvt_pk_bf16_f32 v223, v226, v227
	v_exp_f32_e32 v226, v195
	v_exp_f32_e32 v227, v194
	v_add_f32_e32 v224, 1.0, v224
	v_add_f32_e32 v225, 1.0, v228
	v_rcp_f32_e32 v224, v224
	v_add_f32_e32 v226, 1.0, v226
	v_add_f32_e32 v227, 1.0, v227
	v_rcp_f32_e32 v225, v225
	v_rcp_f32_e32 v226, v226
	v_rcp_f32_e32 v227, v227
	ds_write_b64 v171, v[222:223] offset:16928
	v_exp_f32_e32 v228, v193
	s_nop 0
	v_cvt_pk_bf16_f32 v222, v225, v224
	v_exp_f32_e32 v224, v192
	s_nop 0
	v_cvt_pk_bf16_f32 v223, v226, v227
	v_exp_f32_e32 v226, v191
	v_exp_f32_e32 v227, v190
	v_add_f32_e32 v225, 1.0, v228
	v_add_f32_e32 v224, 1.0, v224
	v_rcp_f32_e32 v225, v225
	v_rcp_f32_e32 v224, v224
	v_add_f32_e32 v226, 1.0, v226
	v_add_f32_e32 v227, 1.0, v227
	ds_write_b64 v171, v[222:223] offset:25344
	s_nop 0
	v_cvt_pk_bf16_f32 v222, v225, v224
	v_rcp_f32_e32 v226, v226
	v_rcp_f32_e32 v227, v227
	v_exp_f32_e32 v224, v189
	s_nop 0
	v_cvt_pk_bf16_f32 v223, v226, v227
	ds_write_b64 v171, v[222:223] offset:25376
	v_exp_f32_e32 v222, v188
	v_add_f32_e32 v223, 1.0, v224
	v_rcp_f32_e32 v223, v223
	v_exp_f32_e32 v224, v187
	v_add_f32_e32 v222, 1.0, v222
	v_rcp_f32_e32 v222, v222
	v_exp_f32_e32 v225, v185
	s_nop 0
	v_cvt_pk_bf16_f32 v222, v223, v222
	v_mul_f32_e32 v223, 0xbfb8aa3b, v118
	v_exp_f32_e32 v226, v223
	v_mul_f32_e32 v223, 0xbfb8aa3b, v119
	v_exp_f32_e32 v227, v223
	v_add_f32_e32 v224, 1.0, v224
	v_add_f32_e32 v225, 1.0, v225
	v_rcp_f32_e32 v224, v224
	v_rcp_f32_e32 v225, v225
	s_nop 0
	v_cvt_pk_bf16_f32 v223, v224, v225
	v_add_f32_e32 v224, 1.0, v226
	v_add_f32_e32 v225, 1.0, v227
	v_mul_f32_e32 v226, 0xbfb8aa3b, v120
	v_mul_f32_e32 v227, 0xbfb8aa3b, v121
	v_exp_f32_e32 v226, v226
	v_exp_f32_e32 v227, v227
	v_rcp_f32_e32 v224, v224
	v_rcp_f32_e32 v225, v225
	v_add_f32_e32 v226, 1.0, v226
	v_add_f32_e32 v227, 1.0, v227
	ds_write_b64 v171, v[222:223] offset:256
	s_nop 0
	v_cvt_pk_bf16_f32 v222, v224, v225
	v_rcp_f32_e32 v226, v226
	v_rcp_f32_e32 v227, v227
	v_exp_f32_e32 v224, v184
	s_nop 0
	v_cvt_pk_bf16_f32 v223, v226, v227
	ds_write_b64 v171, v[222:223] offset:288
	v_exp_f32_e32 v222, v183
	v_add_f32_e32 v223, 1.0, v224
	v_rcp_f32_e32 v223, v223
	v_exp_f32_e32 v224, v182
	v_add_f32_e32 v222, 1.0, v222
	v_rcp_f32_e32 v222, v222
	v_exp_f32_e32 v225, v181
	s_nop 0
	v_cvt_pk_bf16_f32 v222, v223, v222
	v_mul_f32_e32 v223, 0xbfb8aa3b, v102
	v_exp_f32_e32 v226, v223
	v_mul_f32_e32 v223, 0xbfb8aa3b, v103
	v_exp_f32_e32 v227, v223
	v_add_f32_e32 v224, 1.0, v224
	v_add_f32_e32 v225, 1.0, v225
	v_rcp_f32_e32 v224, v224
	v_rcp_f32_e32 v225, v225
	s_nop 0
	v_cvt_pk_bf16_f32 v223, v224, v225
	v_add_f32_e32 v224, 1.0, v226
	v_add_f32_e32 v225, 1.0, v227
	v_mul_f32_e32 v226, 0xbfb8aa3b, v104
	v_mul_f32_e32 v227, 0xbfb8aa3b, v105
	v_exp_f32_e32 v226, v226
	v_exp_f32_e32 v227, v227
	v_rcp_f32_e32 v224, v224
	v_rcp_f32_e32 v225, v225
	v_add_f32_e32 v226, 1.0, v226
	v_add_f32_e32 v227, 1.0, v227
	ds_write_b64 v171, v[222:223] offset:8704
	s_nop 0
	v_cvt_pk_bf16_f32 v222, v224, v225
	v_rcp_f32_e32 v226, v226
	v_rcp_f32_e32 v227, v227
	v_exp_f32_e32 v224, v180
	s_nop 0
	v_cvt_pk_bf16_f32 v223, v226, v227
	ds_write_b64 v171, v[222:223] offset:8736
	v_exp_f32_e32 v222, v179
	v_add_f32_e32 v223, 1.0, v224
	v_rcp_f32_e32 v223, v223
	v_exp_f32_e32 v224, v178
	v_add_f32_e32 v222, 1.0, v222
	v_rcp_f32_e32 v222, v222
	v_exp_f32_e32 v225, v177
	s_nop 0
	v_cvt_pk_bf16_f32 v222, v223, v222
	v_mul_f32_e32 v223, 0xbfb8aa3b, v86
	v_exp_f32_e32 v226, v223
	v_mul_f32_e32 v223, 0xbfb8aa3b, v87
	v_exp_f32_e32 v227, v223
	v_add_f32_e32 v224, 1.0, v224
	v_add_f32_e32 v225, 1.0, v225
	v_rcp_f32_e32 v224, v224
	v_rcp_f32_e32 v225, v225
	s_nop 0
	v_cvt_pk_bf16_f32 v223, v224, v225
	v_add_f32_e32 v224, 1.0, v226
	v_add_f32_e32 v225, 1.0, v227
	v_mul_f32_e32 v226, 0xbfb8aa3b, v88
	v_mul_f32_e32 v227, 0xbfb8aa3b, v89
	v_exp_f32_e32 v226, v226
	v_exp_f32_e32 v227, v227
	v_rcp_f32_e32 v224, v224
	v_rcp_f32_e32 v225, v225
	v_add_f32_e32 v226, 1.0, v226
	v_add_f32_e32 v227, 1.0, v227
	ds_write_b64 v171, v[222:223] offset:17152
	s_nop 0
	v_cvt_pk_bf16_f32 v222, v224, v225
	v_rcp_f32_e32 v226, v226
	v_rcp_f32_e32 v227, v227
	v_exp_f32_e32 v224, v176
	s_nop 0
	v_cvt_pk_bf16_f32 v223, v226, v227
	ds_write_b64 v171, v[222:223] offset:17184
	v_exp_f32_e32 v222, v175
	v_mul_f32_e32 v226, 0xbfb8aa3b, v62
	v_exp_f32_e32 v226, v226
	v_mul_f32_e32 v227, 0xbfb8aa3b, v63
	v_exp_f32_e32 v227, v227
	v_add_f32_e32 v223, 1.0, v224
	v_add_f32_e32 v222, 1.0, v222
	v_rcp_f32_e32 v223, v223
	v_rcp_f32_e32 v222, v222
	s_nop 0
	v_cvt_pk_bf16_f32 v222, v223, v222
	v_add_f32_e32 v223, 1.0, v226
	v_rcp_f32_e32 v226, v223
	v_add_f32_e32 v223, 1.0, v227
	v_mul_f32_e32 v227, 0xbfb8aa3b, v64
	v_exp_f32_e32 v227, v227
	v_mul_f32_e32 v228, 0xbfb8aa3b, v65
	v_exp_f32_e32 v224, v174
	v_exp_f32_e32 v225, v173
	v_exp_f32_e32 v228, v228
	v_rcp_f32_e32 v229, v223
	v_add_f32_e32 v223, 1.0, v227
	v_add_f32_e32 v224, 1.0, v224
	v_add_f32_e32 v225, 1.0, v225
	v_rcp_f32_e32 v227, v223
	v_add_f32_e32 v223, 1.0, v228
	v_rcp_f32_e32 v224, v224
	v_rcp_f32_e32 v225, v225
	v_rcp_f32_e32 v228, v223
	s_nop 0
	v_cvt_pk_bf16_f32 v223, v224, v225
	ds_write_b64 v171, v[222:223] offset:25600
	s_nop 0
	v_cvt_pk_bf16_f32 v222, v226, v229
	s_nop 0
; __device__ __forceinline__ float sigmf(float v) { return __builtin_amdgcn_rcpf(1.f + __expf(-v)); }
; #define FOR_FRAG(ai, bj, m, n) _Pragma("unroll") for (int ai = 0; ai < 2; ++ai) _Pragma("unroll") for (int bj = 0; bj < 2; ++bj) \
;   _Pragma("unroll") for (int m = 0; m < 4; ++m) _Pragma("unroll") for (int n = 0; n < 2; ++n)
; __device__ __forceinline__ u32x2 pack4(float a, float b, float c, float d) { return u32x2{cvtpk(a, b), cvtpk(c, d)}; }
; __device__ __forceinline__ void phase2(const Params& p, char* shm) {
;     ...
;       } else {
;         dst = Gates + (size_t)brow * 4096 + (pn - 32) * 256; ldd = 4096;
;         FOR_FRAG(ai, bj, m, n) { const f32x4 v = acc[ai][bj][m][n]; *(u32x2*)(ctb + CT_OFF(ai, bj, m, n)) = pack4(sigmf(v[0]), sigmf(v[1]), sigmf(v[2]), sigmf(v[3])); }
	v_cvt_pk_bf16_f32 v223, v227, v228
	v_exp_f32_e32 v224, v172
	ds_write_b64 v171, v[222:223] offset:25632
	v_exp_f32_e32 v222, v162
	v_exp_f32_e32 v228, v157
	v_add_f32_e32 v223, 1.0, v224
	v_rcp_f32_e32 v223, v223
	v_add_f32_e32 v222, 1.0, v222
	v_rcp_f32_e32 v222, v222
	s_nop 0
	v_cvt_pk_bf16_f32 v222, v223, v222
	v_exp_f32_e32 v223, v158
	v_exp_f32_e32 v224, v161
	v_exp_f32_e32 v226, v160
	v_exp_f32_e32 v227, v159
	v_exp_f32_e32 v229, v156
	v_add_f32_e32 v223, 1.0, v223
	v_add_f32_e32 v224, 1.0, v224
	v_rcp_f32_e32 v230, v223
	v_add_f32_e32 v223, 1.0, v228
	v_add_u32_e32 v225, 0x10800, v171
	v_rcp_f32_e32 v224, v224
	v_add_f32_e32 v226, 1.0, v226
	v_add_f32_e32 v227, 1.0, v227
	v_rcp_f32_e32 v228, v223
	v_add_f32_e32 v223, 1.0, v229
	v_rcp_f32_e32 v226, v226
	v_rcp_f32_e32 v227, v227
	v_rcp_f32_e32 v229, v223
	s_nop 0
	v_cvt_pk_bf16_f32 v223, v224, v226
	ds_write_b64 v225, v[222:223]
	s_nop 0
	v_cvt_pk_bf16_f32 v222, v227, v230
	v_add_u32_e32 v224, 0x10820, v171
	s_nop 0
	v_cvt_pk_bf16_f32 v223, v228, v229
	v_exp_f32_e32 v225, v155
	ds_write_b64 v224, v[222:223]
	v_exp_f32_e32 v222, v154
	v_exp_f32_e32 v228, v149
	v_add_f32_e32 v223, 1.0, v225
	v_rcp_f32_e32 v223, v223
	v_add_f32_e32 v222, 1.0, v222
	v_rcp_f32_e32 v222, v222
	s_nop 0
	v_cvt_pk_bf16_f32 v222, v223, v222
	v_exp_f32_e32 v223, v150
	v_exp_f32_e32 v225, v153
	v_exp_f32_e32 v226, v152
	v_exp_f32_e32 v227, v151
	v_exp_f32_e32 v229, v148
	v_add_f32_e32 v223, 1.0, v223
	v_rcp_f32_e32 v230, v223
	v_add_f32_e32 v223, 1.0, v228
	v_add_u32_e32 v224, 0x12900, v171
	v_add_f32_e32 v225, 1.0, v225
	v_add_f32_e32 v226, 1.0, v226
	v_add_f32_e32 v227, 1.0, v227
	v_rcp_f32_e32 v228, v223
	v_add_f32_e32 v223, 1.0, v229
	v_rcp_f32_e32 v225, v225
	v_rcp_f32_e32 v226, v226
	v_rcp_f32_e32 v227, v227
	v_rcp_f32_e32 v229, v223
	s_nop 0
	v_cvt_pk_bf16_f32 v223, v225, v226
	ds_write_b64 v224, v[222:223]
	s_nop 0
	v_cvt_pk_bf16_f32 v222, v227, v230
	v_add_u32_e32 v224, 0x12920, v171
	s_nop 0
	v_cvt_pk_bf16_f32 v223, v228, v229
	v_exp_f32_e32 v225, v147
	ds_write_b64 v224, v[222:223]
	v_exp_f32_e32 v222, v146
	v_exp_f32_e32 v228, v141
	v_add_f32_e32 v223, 1.0, v225
	v_rcp_f32_e32 v223, v223
	v_add_f32_e32 v222, 1.0, v222
	v_rcp_f32_e32 v222, v222
	s_nop 0
	v_cvt_pk_bf16_f32 v222, v223, v222
	v_exp_f32_e32 v223, v142
	v_exp_f32_e32 v225, v145
	v_exp_f32_e32 v226, v144
	v_exp_f32_e32 v227, v143
	v_exp_f32_e32 v229, v140
	v_add_f32_e32 v223, 1.0, v223
	v_rcp_f32_e32 v230, v223
	v_add_f32_e32 v223, 1.0, v228
	v_add_u32_e32 v224, 0x14a00, v171
	v_add_f32_e32 v225, 1.0, v225
	v_add_f32_e32 v226, 1.0, v226
	v_add_f32_e32 v227, 1.0, v227
	v_rcp_f32_e32 v228, v223
	v_add_f32_e32 v223, 1.0, v229
	v_rcp_f32_e32 v225, v225
	v_rcp_f32_e32 v226, v226
	v_rcp_f32_e32 v227, v227
	v_rcp_f32_e32 v229, v223
	s_nop 0
	v_cvt_pk_bf16_f32 v223, v225, v226
	ds_write_b64 v224, v[222:223]
	s_nop 0
	v_cvt_pk_bf16_f32 v222, v227, v230
	v_add_u32_e32 v224, 0x14a20, v171
	s_nop 0
	v_cvt_pk_bf16_f32 v223, v228, v229
	v_exp_f32_e32 v225, v139
	ds_write_b64 v224, v[222:223]
	v_exp_f32_e32 v222, v138
	v_exp_f32_e32 v228, v133
	v_add_f32_e32 v223, 1.0, v225
	v_rcp_f32_e32 v223, v223
	v_add_f32_e32 v222, 1.0, v222
	v_rcp_f32_e32 v222, v222
	s_nop 0
	v_cvt_pk_bf16_f32 v222, v223, v222
	v_exp_f32_e32 v223, v134
	v_exp_f32_e32 v225, v137
	v_exp_f32_e32 v226, v136
	v_exp_f32_e32 v227, v135
	v_exp_f32_e32 v229, v132
	v_add_f32_e32 v223, 1.0, v223
	v_rcp_f32_e32 v230, v223
	v_add_f32_e32 v223, 1.0, v228
	v_add_u32_e32 v224, 0x16b00, v171
	v_add_f32_e32 v225, 1.0, v225
	v_add_f32_e32 v226, 1.0, v226
	v_add_f32_e32 v227, 1.0, v227
	v_rcp_f32_e32 v228, v223
	v_add_f32_e32 v223, 1.0, v229
	v_rcp_f32_e32 v225, v225
	v_rcp_f32_e32 v226, v226
	v_rcp_f32_e32 v227, v227
	v_rcp_f32_e32 v229, v223
	s_nop 0
	v_cvt_pk_bf16_f32 v223, v225, v226
	ds_write_b64 v224, v[222:223]
	s_nop 0
	v_cvt_pk_bf16_f32 v222, v227, v230
	v_add_u32_e32 v224, 0x16b20, v171
	s_nop 0
	v_cvt_pk_bf16_f32 v223, v228, v229
	v_exp_f32_e32 v225, v131
	ds_write_b64 v224, v[222:223]
	v_exp_f32_e32 v222, v130
	v_mul_f32_e32 v227, 0xbfb8aa3b, v58
	v_exp_f32_e32 v227, v227
	v_mul_f32_e32 v228, 0xbfb8aa3b, v59
	v_exp_f32_e32 v228, v228
	v_add_f32_e32 v223, 1.0, v225
	v_add_f32_e32 v222, 1.0, v222
	v_rcp_f32_e32 v223, v223
	v_rcp_f32_e32 v222, v222
	s_nop 0
	v_cvt_pk_bf16_f32 v222, v223, v222
	v_add_f32_e32 v223, 1.0, v227
	v_rcp_f32_e32 v227, v223
	v_add_f32_e32 v223, 1.0, v228
	v_mul_f32_e32 v228, 0xbfb8aa3b, v60
	v_mul_f32_e32 v225, 0xbfb8aa3b, v80
	v_mul_f32_e32 v226, 0xbfb8aa3b, v81
	v_exp_f32_e32 v228, v228
	v_mul_f32_e32 v229, 0xbfb8aa3b, v61
	v_exp_f32_e32 v225, v225
	v_exp_f32_e32 v226, v226
	v_exp_f32_e32 v229, v229
	v_rcp_f32_e32 v230, v223
	v_add_f32_e32 v223, 1.0, v228
	v_add_f32_e32 v225, 1.0, v225
	v_add_f32_e32 v226, 1.0, v226
	v_rcp_f32_e32 v228, v223
	v_add_f32_e32 v223, 1.0, v229
	v_add_u32_e32 v224, 0x10900, v171
	v_rcp_f32_e32 v225, v225
	v_rcp_f32_e32 v226, v226
	v_rcp_f32_e32 v229, v223
	s_nop 0
	v_cvt_pk_bf16_f32 v223, v225, v226
	ds_write_b64 v224, v[222:223]
	s_nop 0
	v_cvt_pk_bf16_f32 v222, v227, v230
	s_nop 0
	v_cvt_pk_bf16_f32 v223, v228, v229
	v_add_u32_e32 v224, 0x10920, v171
	ds_write_b64 v224, v[222:223]
	v_mul_f32_e32 v222, 0xbfb8aa3b, v54
	v_mul_f32_e32 v223, 0xbfb8aa3b, v55
	v_exp_f32_e32 v222, v222
	v_exp_f32_e32 v223, v223
	v_mul_f32_e32 v227, 0xbfb8aa3b, v38
	v_exp_f32_e32 v227, v227
	v_mul_f32_e32 v228, 0xbfb8aa3b, v39
	v_exp_f32_e32 v228, v228
	v_add_f32_e32 v222, 1.0, v222
	v_add_f32_e32 v223, 1.0, v223
	v_rcp_f32_e32 v222, v222
	v_rcp_f32_e32 v223, v223
	s_nop 0
	v_cvt_pk_bf16_f32 v222, v222, v223
	v_add_f32_e32 v223, 1.0, v227
	v_rcp_f32_e32 v227, v223
; __device__ __forceinline__ float siluf(float v) { return v * __builtin_amdgcn_rcpf(1.f + __expf(-v)); }
; __device__ __forceinline__ float sigmf(float v) { return __builtin_amdgcn_rcpf(1.f + __expf(-v)); }
; #define FOR_FRAG(ai, bj, m, n) _Pragma("unroll") for (int ai = 0; ai < 2; ++ai) _Pragma("unroll") for (int bj = 0; bj < 2; ++bj) \
;   _Pragma("unroll") for (int m = 0; m < 4; ++m) _Pragma("unroll") for (int n = 0; n < 2; ++n)
; __device__ __forceinline__ u32x2 pack4(float a, float b, float c, float d) { return u32x2{cvtpk(a, b), cvtpk(c, d)}; }
; __device__ __forceinline__ void phase2(const Params& p, char* shm) {
;     ...
;       } else if (pn < 32) {
;         dst = Zb + (size_t)brow * AW + (pn - 28) * 256;
;         FOR_FRAG(ai, bj, m, n) { const f32x4 v = acc[ai][bj][m][n]; *(u32x2*)(ctb + CT_OFF(ai, bj, m, n)) = pack4(siluf(v[0]), siluf(v[1]), siluf(v[2]), siluf(v[3])); }
;       } else {
;         dst = Gates + (size_t)brow * 4096 + (pn - 32) * 256; ldd = 4096;
;         FOR_FRAG(ai, bj, m, n) { const f32x4 v = acc[ai][bj][m][n]; *(u32x2*)(ctb + CT_OFF(ai, bj, m, n)) = pack4(sigmf(v[0]), sigmf(v[1]), sigmf(v[2]), sigmf(v[3])); }
;       }
	v_add_f32_e32 v223, 1.0, v228
	v_mul_f32_e32 v228, 0xbfb8aa3b, v40
	v_mul_f32_e32 v225, 0xbfb8aa3b, v56
	v_mul_f32_e32 v226, 0xbfb8aa3b, v57
	v_exp_f32_e32 v228, v228
	v_mul_f32_e32 v229, 0xbfb8aa3b, v41
	v_exp_f32_e32 v225, v225
	v_exp_f32_e32 v226, v226
	v_exp_f32_e32 v229, v229
	v_rcp_f32_e32 v230, v223
	v_add_f32_e32 v223, 1.0, v228
	v_add_f32_e32 v225, 1.0, v225
	v_add_f32_e32 v226, 1.0, v226
	v_rcp_f32_e32 v228, v223
	v_add_f32_e32 v223, 1.0, v229
	v_add_u32_e32 v224, 0x12a00, v171
	v_rcp_f32_e32 v225, v225
	v_rcp_f32_e32 v226, v226
	v_rcp_f32_e32 v229, v223
	s_nop 0
	v_cvt_pk_bf16_f32 v223, v225, v226
	ds_write_b64 v224, v[222:223]
	s_nop 0
	v_cvt_pk_bf16_f32 v222, v227, v230
	s_nop 0
	v_cvt_pk_bf16_f32 v223, v228, v229
	v_add_u32_e32 v224, 0x12a20, v171
	ds_write_b64 v224, v[222:223]
	v_mul_f32_e32 v222, 0xbfb8aa3b, v34
	v_mul_f32_e32 v223, 0xbfb8aa3b, v35
	v_exp_f32_e32 v222, v222
	v_exp_f32_e32 v223, v223
	v_mul_f32_e32 v227, 0xbfb8aa3b, v22
	v_exp_f32_e32 v227, v227
	v_mul_f32_e32 v228, 0xbfb8aa3b, v23
	v_exp_f32_e32 v228, v228
	v_add_f32_e32 v222, 1.0, v222
	v_add_f32_e32 v223, 1.0, v223
	v_rcp_f32_e32 v222, v222
	v_rcp_f32_e32 v223, v223
	s_nop 0
	v_cvt_pk_bf16_f32 v222, v222, v223
	v_add_f32_e32 v223, 1.0, v227
	v_rcp_f32_e32 v227, v223
	v_add_f32_e32 v223, 1.0, v228
	v_mul_f32_e32 v228, 0xbfb8aa3b, v24
	v_mul_f32_e32 v225, 0xbfb8aa3b, v36
	v_mul_f32_e32 v226, 0xbfb8aa3b, v37
	v_exp_f32_e32 v228, v228
	v_mul_f32_e32 v229, 0xbfb8aa3b, v25
	v_exp_f32_e32 v225, v225
	v_exp_f32_e32 v226, v226
	v_exp_f32_e32 v229, v229
	v_rcp_f32_e32 v230, v223
	v_add_f32_e32 v223, 1.0, v228
	v_add_f32_e32 v225, 1.0, v225
	v_add_f32_e32 v226, 1.0, v226
	v_rcp_f32_e32 v228, v223
	v_add_f32_e32 v223, 1.0, v229
	v_add_u32_e32 v224, 0x14b00, v171
	v_rcp_f32_e32 v225, v225
	v_rcp_f32_e32 v226, v226
	v_rcp_f32_e32 v229, v223
	s_nop 0
	v_cvt_pk_bf16_f32 v223, v225, v226
	ds_write_b64 v224, v[222:223]
	s_nop 0
	v_cvt_pk_bf16_f32 v222, v227, v230
	s_nop 0
	v_cvt_pk_bf16_f32 v223, v228, v229
	v_add_u32_e32 v224, 0x14b20, v171
	ds_write_b64 v224, v[222:223]
	v_mul_f32_e32 v222, 0xbfb8aa3b, v18
	v_mul_f32_e32 v223, 0xbfb8aa3b, v19
	v_exp_f32_e32 v222, v222
	v_exp_f32_e32 v223, v223
	v_mul_f32_e32 v227, 0xbfb8aa3b, v6
	v_exp_f32_e32 v227, v227
	v_mul_f32_e32 v228, 0xbfb8aa3b, v7
	v_exp_f32_e32 v228, v228
	v_add_f32_e32 v222, 1.0, v222
	v_add_f32_e32 v223, 1.0, v223
	v_rcp_f32_e32 v222, v222
	v_rcp_f32_e32 v223, v223
	s_nop 0
	v_cvt_pk_bf16_f32 v222, v222, v223
	v_add_f32_e32 v223, 1.0, v227
	v_rcp_f32_e32 v227, v223
	v_add_f32_e32 v223, 1.0, v228
	v_mul_f32_e32 v228, 0xbfb8aa3b, v8
	v_mul_f32_e32 v225, 0xbfb8aa3b, v20
	v_mul_f32_e32 v226, 0xbfb8aa3b, v21
	v_exp_f32_e32 v228, v228
	v_mul_f32_e32 v229, 0xbfb8aa3b, v9
	v_exp_f32_e32 v225, v225
	v_exp_f32_e32 v226, v226
	v_exp_f32_e32 v229, v229
	s_lshl_b32 s16, s38, 8
	s_lshl_b64 s[0:1], s[40:41], 13
	s_addk_i32 s16, 0xe000
	v_rcp_f32_e32 v230, v223
	v_add_f32_e32 v223, 1.0, v228
	s_add_u32 s18, s24, s0
	v_add_u32_e32 v224, 0x16c00, v171
	v_add_f32_e32 v225, 1.0, v225
	v_add_f32_e32 v226, 1.0, v226
	v_rcp_f32_e32 v228, v223
	v_add_f32_e32 v223, 1.0, v229
	s_addc_u32 s39, s25, s1
	s_lshl_b64 s[0:1], s[16:17], 9
	v_rcp_f32_e32 v225, v225
	v_rcp_f32_e32 v226, v226
	v_rcp_f32_e32 v229, v223
	s_nop 0
	v_cvt_pk_bf16_f32 v223, v225, v226
	ds_write_b64 v224, v[222:223]
	v_add_u32_e32 v224, 0x16c20, v171
	s_add_u32 s0, s18, s0
	s_nop 0
	v_cvt_pk_bf16_f32 v222, v227, v230
	s_nop 0
	v_cvt_pk_bf16_f32 v223, v228, v229
	ds_write_b64 v224, v[222:223]
	s_addc_u32 s1, s39, s1
	s_mov_b64 s[44:45], 0
.LBB0_206:
	s_andn2_b64 vcc, exec, s[44:45]
	s_mov_b64 s[44:45], 0x100
	s_cbranch_vccnz .LBB0_208
	v_exp_f32_e32 v221, v221
	v_exp_f32_e32 v220, v220
	v_exp_f32_e32 v219, v219
	v_exp_f32_e32 v218, v218
	v_exp_f32_e32 v217, v217
	v_exp_f32_e32 v216, v216
	v_exp_f32_e32 v215, v215
	v_exp_f32_e32 v214, v214
	v_exp_f32_e32 v213, v213
	v_exp_f32_e32 v212, v212
	v_exp_f32_e32 v211, v211
	v_exp_f32_e32 v210, v210
	v_exp_f32_e32 v209, v209
	v_exp_f32_e32 v208, v208
	v_exp_f32_e32 v207, v207
	v_exp_f32_e32 v206, v206
	v_add_f32_e32 v221, 1.0, v221
	v_add_f32_e32 v220, 1.0, v220
	v_add_f32_e32 v219, 1.0, v219
	v_add_f32_e32 v218, 1.0, v218
	v_exp_f32_e32 v205, v205
	v_exp_f32_e32 v204, v204
	v_exp_f32_e32 v203, v203
	v_exp_f32_e32 v202, v202
	v_rcp_f32_e32 v221, v221
	v_rcp_f32_e32 v220, v220
	v_rcp_f32_e32 v219, v219
	v_rcp_f32_e32 v218, v218
	v_add_f32_e32 v217, 1.0, v217
	v_add_f32_e32 v216, 1.0, v216
	v_add_f32_e32 v215, 1.0, v215
	v_add_f32_e32 v214, 1.0, v214
	v_exp_f32_e32 v201, v201
	v_exp_f32_e32 v200, v200
	v_exp_f32_e32 v199, v199
	v_exp_f32_e32 v198, v198
	v_rcp_f32_e32 v217, v217
	v_rcp_f32_e32 v216, v216
	v_rcp_f32_e32 v215, v215
	v_rcp_f32_e32 v214, v214
	v_add_f32_e32 v213, 1.0, v213
	v_add_f32_e32 v212, 1.0, v212
	v_add_f32_e32 v211, 1.0, v211
	v_add_f32_e32 v210, 1.0, v210
	v_exp_f32_e32 v197, v197
	v_exp_f32_e32 v196, v196
	v_exp_f32_e32 v195, v195
	v_exp_f32_e32 v194, v194
	v_exp_f32_e32 v191, v191
	v_exp_f32_e32 v189, v189
	v_exp_f32_e32 v188, v188
	v_rcp_f32_e32 v213, v213
	v_rcp_f32_e32 v212, v212
	v_rcp_f32_e32 v211, v211
	v_rcp_f32_e32 v210, v210
	v_add_f32_e32 v209, 1.0, v209
	v_add_f32_e32 v208, 1.0, v208
	v_add_f32_e32 v207, 1.0, v207
	v_add_f32_e32 v206, 1.0, v206
	v_exp_f32_e32 v193, v193
	v_exp_f32_e32 v192, v192
	v_exp_f32_e32 v190, v190
	v_exp_f32_e32 v187, v187
	v_exp_f32_e32 v185, v185
	v_rcp_f32_e32 v209, v209
	v_rcp_f32_e32 v208, v208
	v_rcp_f32_e32 v207, v207
	v_rcp_f32_e32 v206, v206
	v_add_f32_e32 v205, 1.0, v205
	v_add_f32_e32 v204, 1.0, v204
	v_add_f32_e32 v203, 1.0, v203
	v_add_f32_e32 v202, 1.0, v202
; __device__ __forceinline__ float siluf(float v) { return v * __builtin_amdgcn_rcpf(1.f + __expf(-v)); }
; #define FOR_FRAG(ai, bj, m, n) _Pragma("unroll") for (int ai = 0; ai < 2; ++ai) _Pragma("unroll") for (int bj = 0; bj < 2; ++bj) \
;   _Pragma("unroll") for (int m = 0; m < 4; ++m) _Pragma("unroll") for (int n = 0; n < 2; ++n)
; __device__ __forceinline__ u32x2 pack4(float a, float b, float c, float d) { return u32x2{cvtpk(a, b), cvtpk(c, d)}; }
; __device__ __forceinline__ void phase2(const Params& p, char* shm) {
;     ...
;         dst = Zb + (size_t)brow * AW + (pn - 28) * 256;
;         FOR_FRAG(ai, bj, m, n) { const f32x4 v = acc[ai][bj][m][n]; *(u32x2*)(ctb + CT_OFF(ai, bj, m, n)) = pack4(siluf(v[0]), siluf(v[1]), siluf(v[2]), siluf(v[3])); }
	v_mul_f32_e32 v221, v122, v221
	v_mul_f32_e32 v220, v123, v220
	v_mul_f32_e32 v219, v124, v219
	v_mul_f32_e32 v222, v125, v218
	s_nop 0
	v_cvt_pk_bf16_f32 v218, v221, v220
	v_rcp_f32_e32 v205, v205
	v_rcp_f32_e32 v204, v204
	v_rcp_f32_e32 v203, v203
	v_rcp_f32_e32 v202, v202
	v_add_f32_e32 v201, 1.0, v201
	v_add_f32_e32 v200, 1.0, v200
	v_add_f32_e32 v199, 1.0, v199
	v_add_f32_e32 v198, 1.0, v198
	s_nop 0
	v_cvt_pk_bf16_f32 v219, v219, v222
	ds_write_b64 v171, v[218:219]
	v_mul_f32_e32 v217, v110, v217
	v_mul_f32_e32 v216, v111, v216
	v_mul_f32_e32 v215, v112, v215
	v_mul_f32_e32 v218, v113, v214
	s_nop 0
	v_cvt_pk_bf16_f32 v214, v217, v216
	v_rcp_f32_e32 v201, v201
	v_rcp_f32_e32 v200, v200
	v_rcp_f32_e32 v199, v199
	v_rcp_f32_e32 v198, v198
	v_add_f32_e32 v197, 1.0, v197
	v_add_f32_e32 v196, 1.0, v196
	v_add_f32_e32 v195, 1.0, v195
	v_add_f32_e32 v194, 1.0, v194
	v_add_f32_e32 v191, 1.0, v191
	v_add_f32_e32 v189, 1.0, v189
	v_add_f32_e32 v188, 1.0, v188
	s_nop 0
	v_cvt_pk_bf16_f32 v215, v215, v218
	ds_write_b64 v171, v[214:215] offset:32
	v_mul_f32_e32 v213, v106, v213
	v_mul_f32_e32 v212, v107, v212
	v_mul_f32_e32 v211, v108, v211
	v_mul_f32_e32 v214, v109, v210
	s_nop 0
	v_cvt_pk_bf16_f32 v210, v213, v212
	v_rcp_f32_e32 v197, v197
	v_rcp_f32_e32 v196, v196
	v_rcp_f32_e32 v195, v195
	v_rcp_f32_e32 v194, v194
	v_add_f32_e32 v193, 1.0, v193
	v_add_f32_e32 v192, 1.0, v192
	v_rcp_f32_e32 v191, v191
	v_add_f32_e32 v190, 1.0, v190
	v_rcp_f32_e32 v189, v189
	v_rcp_f32_e32 v188, v188
	v_add_f32_e32 v187, 1.0, v187
	v_add_f32_e32 v185, 1.0, v185
	s_nop 0
	v_cvt_pk_bf16_f32 v211, v211, v214
	ds_write_b64 v171, v[210:211] offset:8448
	v_mul_f32_e32 v209, v94, v209
	v_mul_f32_e32 v208, v95, v208
	v_mul_f32_e32 v207, v96, v207
	v_mul_f32_e32 v210, v97, v206
	s_nop 0
	v_cvt_pk_bf16_f32 v206, v209, v208
	v_rcp_f32_e32 v193, v193
	v_rcp_f32_e32 v192, v192
	v_rcp_f32_e32 v190, v190
	v_rcp_f32_e32 v187, v187
	v_rcp_f32_e32 v185, v185
	s_nop 0
	v_cvt_pk_bf16_f32 v207, v207, v210
	ds_write_b64 v171, v[206:207] offset:8480
	v_mul_f32_e32 v205, v90, v205
	v_mul_f32_e32 v204, v91, v204
	v_mul_f32_e32 v203, v92, v203
	v_mul_f32_e32 v206, v93, v202
	s_nop 0
	v_cvt_pk_bf16_f32 v202, v205, v204
	s_nop 0
	v_cvt_pk_bf16_f32 v203, v203, v206
	ds_write_b64 v171, v[202:203] offset:16896
	v_mul_f32_e32 v201, v74, v201
	v_mul_f32_e32 v200, v75, v200
	v_mul_f32_e32 v199, v76, v199
	v_mul_f32_e32 v202, v77, v198
	s_nop 0
	v_cvt_pk_bf16_f32 v198, v201, v200
	s_nop 0
	v_cvt_pk_bf16_f32 v199, v199, v202
	ds_write_b64 v171, v[198:199] offset:16928
	v_mul_f32_e32 v197, v66, v197
	v_mul_f32_e32 v196, v67, v196
	v_mul_f32_e32 v195, v68, v195
	v_mul_f32_e32 v198, v69, v194
	s_nop 0
	v_cvt_pk_bf16_f32 v194, v197, v196
	v_mul_f32_e32 v191, v52, v191
	v_mul_f32_e32 v189, v126, v189
	v_mul_f32_e32 v188, v127, v188
	s_nop 0
	v_cvt_pk_bf16_f32 v195, v195, v198
	ds_write_b64 v171, v[194:195] offset:25344
	v_mul_f32_e32 v193, v50, v193
	v_mul_f32_e32 v192, v51, v192
	v_mul_f32_e32 v194, v53, v190
	s_nop 0
	v_cvt_pk_bf16_f32 v190, v193, v192
	s_nop 0
	v_cvt_pk_bf16_f32 v191, v191, v194
	ds_write_b64 v171, v[190:191] offset:25376
	v_mul_f32_e32 v187, v128, v187
	v_mul_f32_e32 v185, v129, v185
	s_nop 0
	v_cvt_pk_bf16_f32 v188, v189, v188
	s_nop 0
	v_cvt_pk_bf16_f32 v189, v187, v185
	v_mul_f32_e32 v185, 0xbfb8aa3b, v118
	ds_write_b64 v171, v[188:189] offset:256
	v_mul_f32_e32 v189, 0xbfb8aa3b, v121
	v_exp_f32_e32 v185, v185
	v_mul_f32_e32 v187, 0xbfb8aa3b, v119
	v_mul_f32_e32 v188, 0xbfb8aa3b, v120
	v_exp_f32_e32 v189, v189
	v_exp_f32_e32 v184, v184
	v_exp_f32_e32 v187, v187
	v_exp_f32_e32 v188, v188
	v_exp_f32_e32 v183, v183
	v_exp_f32_e32 v182, v182
	v_add_f32_e32 v185, 1.0, v185
	v_add_f32_e32 v189, 1.0, v189
	v_add_f32_e32 v184, 1.0, v184
	v_exp_f32_e32 v181, v181
	v_rcp_f32_e32 v185, v185
	v_add_f32_e32 v187, 1.0, v187
	v_add_f32_e32 v188, 1.0, v188
	v_rcp_f32_e32 v189, v189
	v_rcp_f32_e32 v184, v184
	v_add_f32_e32 v183, 1.0, v183
	v_add_f32_e32 v182, 1.0, v182
	v_rcp_f32_e32 v187, v187
	v_rcp_f32_e32 v188, v188
	v_rcp_f32_e32 v183, v183
	v_rcp_f32_e32 v182, v182
	v_add_f32_e32 v181, 1.0, v181
	v_mul_f32_e32 v185, v118, v185
	v_mul_f32_e32 v189, v121, v189
	v_rcp_f32_e32 v181, v181
	v_mul_f32_e32 v184, v114, v184
	v_mul_f32_e32 v187, v119, v187
	v_mul_f32_e32 v190, v120, v188
	s_nop 0
	v_cvt_pk_bf16_f32 v188, v185, v187
	s_nop 0
	v_cvt_pk_bf16_f32 v189, v190, v189
	ds_write_b64 v171, v[188:189] offset:288
	v_mul_f32_e32 v183, v115, v183
	v_mul_f32_e32 v185, v116, v182
	s_nop 0
	v_cvt_pk_bf16_f32 v182, v184, v183
	v_mul_f32_e32 v184, 0xbfb8aa3b, v103
	v_exp_f32_e32 v184, v184
	v_mul_f32_e32 v181, v117, v181
	s_nop 0
	v_cvt_pk_bf16_f32 v183, v185, v181
	v_mul_f32_e32 v181, 0xbfb8aa3b, v102
	ds_write_b64 v171, v[182:183] offset:8704
	v_mul_f32_e32 v183, 0xbfb8aa3b, v104
	v_exp_f32_e32 v181, v181
	v_add_f32_e32 v182, 1.0, v184
	v_exp_f32_e32 v183, v183
	v_mul_f32_e32 v184, 0xbfb8aa3b, v105
	v_exp_f32_e32 v180, v180
	v_exp_f32_e32 v184, v184
	v_exp_f32_e32 v179, v179
	v_exp_f32_e32 v178, v178
	v_add_f32_e32 v181, 1.0, v181
	v_add_f32_e32 v183, 1.0, v183
	v_add_f32_e32 v180, 1.0, v180
	v_exp_f32_e32 v177, v177
	v_rcp_f32_e32 v181, v181
	v_rcp_f32_e32 v182, v182
	v_rcp_f32_e32 v183, v183
	v_add_f32_e32 v184, 1.0, v184
	v_rcp_f32_e32 v180, v180
	v_add_f32_e32 v179, 1.0, v179
	v_add_f32_e32 v178, 1.0, v178
	v_rcp_f32_e32 v184, v184
	v_rcp_f32_e32 v179, v179
	v_rcp_f32_e32 v178, v178
	v_add_f32_e32 v177, 1.0, v177
	v_mul_f32_e32 v181, v102, v181
	v_mul_f32_e32 v182, v103, v182
	v_mul_f32_e32 v183, v104, v183
	v_rcp_f32_e32 v177, v177
	v_mul_f32_e32 v180, v98, v180
	v_mul_f32_e32 v184, v105, v184
; __device__ __forceinline__ float siluf(float v) { return v * __builtin_amdgcn_rcpf(1.f + __expf(-v)); }
; #define FOR_FRAG(ai, bj, m, n) _Pragma("unroll") for (int ai = 0; ai < 2; ++ai) _Pragma("unroll") for (int bj = 0; bj < 2; ++bj) \
;   _Pragma("unroll") for (int m = 0; m < 4; ++m) _Pragma("unroll") for (int n = 0; n < 2; ++n)
; __device__ __forceinline__ u32x2 pack4(float a, float b, float c, float d) { return u32x2{cvtpk(a, b), cvtpk(c, d)}; }
; __device__ __forceinline__ void phase2(const Params& p, char* shm) {
;     ...
;         dst = Zb + (size_t)brow * AW + (pn - 28) * 256;
;         FOR_FRAG(ai, bj, m, n) { const f32x4 v = acc[ai][bj][m][n]; *(u32x2*)(ctb + CT_OFF(ai, bj, m, n)) = pack4(siluf(v[0]), siluf(v[1]), siluf(v[2]), siluf(v[3])); }
	s_nop 0
	v_cvt_pk_bf16_f32 v182, v181, v182
	s_nop 0
	v_cvt_pk_bf16_f32 v183, v183, v184
	ds_write_b64 v171, v[182:183] offset:8736
	v_mul_f32_e32 v179, v99, v179
	v_mul_f32_e32 v181, v100, v178
	s_nop 0
	v_cvt_pk_bf16_f32 v178, v180, v179
	v_mul_f32_e32 v180, 0xbfb8aa3b, v87
	v_exp_f32_e32 v180, v180
	v_mul_f32_e32 v177, v101, v177
	s_nop 0
	v_cvt_pk_bf16_f32 v179, v181, v177
	v_mul_f32_e32 v177, 0xbfb8aa3b, v86
	ds_write_b64 v171, v[178:179] offset:17152
	v_mul_f32_e32 v179, 0xbfb8aa3b, v88
	v_exp_f32_e32 v177, v177
	v_add_f32_e32 v178, 1.0, v180
	v_exp_f32_e32 v179, v179
	v_mul_f32_e32 v180, 0xbfb8aa3b, v89
	v_exp_f32_e32 v176, v176
	v_exp_f32_e32 v180, v180
	v_exp_f32_e32 v175, v175
	v_exp_f32_e32 v174, v174
	v_add_f32_e32 v177, 1.0, v177
	v_add_f32_e32 v179, 1.0, v179
	v_add_f32_e32 v176, 1.0, v176
	v_exp_f32_e32 v173, v173
	v_rcp_f32_e32 v177, v177
	v_rcp_f32_e32 v178, v178
	v_rcp_f32_e32 v179, v179
	v_add_f32_e32 v180, 1.0, v180
	v_rcp_f32_e32 v176, v176
	v_add_f32_e32 v175, 1.0, v175
	v_add_f32_e32 v174, 1.0, v174
	v_rcp_f32_e32 v180, v180
	v_rcp_f32_e32 v175, v175
	v_rcp_f32_e32 v174, v174
	v_add_f32_e32 v173, 1.0, v173
	v_mul_f32_e32 v177, v86, v177
	v_mul_f32_e32 v178, v87, v178
	v_mul_f32_e32 v179, v88, v179
	v_rcp_f32_e32 v173, v173
	v_mul_f32_e32 v176, v82, v176
	v_mul_f32_e32 v180, v89, v180
	s_nop 0
	v_cvt_pk_bf16_f32 v178, v177, v178
	s_nop 0
	v_cvt_pk_bf16_f32 v179, v179, v180
	ds_write_b64 v171, v[178:179] offset:17184
	v_mul_f32_e32 v175, v83, v175
	v_mul_f32_e32 v177, v84, v174
	s_nop 0
	v_cvt_pk_bf16_f32 v174, v176, v175
	v_mul_f32_e32 v176, 0xbfb8aa3b, v63
	v_exp_f32_e32 v176, v176
	v_mul_f32_e32 v173, v85, v173
	s_nop 0
	v_cvt_pk_bf16_f32 v175, v177, v173
	v_mul_f32_e32 v173, 0xbfb8aa3b, v62
	ds_write_b64 v171, v[174:175] offset:25600
	v_mul_f32_e32 v175, 0xbfb8aa3b, v64
	v_exp_f32_e32 v173, v173
	v_add_f32_e32 v174, 1.0, v176
	v_exp_f32_e32 v175, v175
	v_mul_f32_e32 v176, 0xbfb8aa3b, v65
	v_exp_f32_e32 v176, v176
	v_exp_f32_e32 v172, v172
	v_exp_f32_e32 v162, v162
	v_exp_f32_e32 v161, v161
	v_exp_f32_e32 v160, v160
	v_exp_f32_e32 v158, v158
	v_exp_f32_e32 v157, v157
	v_exp_f32_e32 v159, v159
	v_exp_f32_e32 v156, v156
	v_exp_f32_e32 v155, v155
	v_exp_f32_e32 v154, v154
	v_exp_f32_e32 v153, v153
	v_exp_f32_e32 v152, v152
	v_exp_f32_e32 v150, v150
	v_exp_f32_e32 v149, v149
	v_add_f32_e32 v173, 1.0, v173
	v_rcp_f32_e32 v174, v174
	v_add_f32_e32 v175, 1.0, v175
	v_exp_f32_e32 v151, v151
	v_exp_f32_e32 v148, v148
	v_rcp_f32_e32 v173, v173
	v_rcp_f32_e32 v175, v175
	v_add_f32_e32 v176, 1.0, v176
	v_add_f32_e32 v172, 1.0, v172
	v_add_f32_e32 v162, 1.0, v162
	v_add_f32_e32 v161, 1.0, v161
	v_add_f32_e32 v160, 1.0, v160
	v_add_f32_e32 v158, 1.0, v158
	v_add_f32_e32 v157, 1.0, v157
	v_exp_f32_e32 v147, v147
	v_exp_f32_e32 v146, v146
	v_exp_f32_e32 v145, v145
	v_exp_f32_e32 v144, v144
	v_exp_f32_e32 v142, v142
	v_exp_f32_e32 v141, v141
	v_rcp_f32_e32 v176, v176
	v_rcp_f32_e32 v172, v172
	v_rcp_f32_e32 v162, v162
	v_rcp_f32_e32 v161, v161
	v_rcp_f32_e32 v160, v160
	v_add_f32_e32 v159, 1.0, v159
	v_rcp_f32_e32 v158, v158
	v_rcp_f32_e32 v157, v157
	v_add_f32_e32 v156, 1.0, v156
	v_exp_f32_e32 v143, v143
	v_exp_f32_e32 v140, v140
	v_rcp_f32_e32 v159, v159
	v_rcp_f32_e32 v156, v156
	v_add_f32_e32 v155, 1.0, v155
	v_add_f32_e32 v154, 1.0, v154
	v_add_f32_e32 v153, 1.0, v153
	v_add_f32_e32 v152, 1.0, v152
	v_add_f32_e32 v150, 1.0, v150
	v_add_f32_e32 v149, 1.0, v149
	v_exp_f32_e32 v139, v139
	v_exp_f32_e32 v138, v138
	v_exp_f32_e32 v137, v137
	v_exp_f32_e32 v136, v136
	v_exp_f32_e32 v134, v134
	v_exp_f32_e32 v133, v133
	v_mul_f32_e32 v174, v63, v174
	v_rcp_f32_e32 v155, v155
	v_rcp_f32_e32 v154, v154
	v_rcp_f32_e32 v153, v153
	v_rcp_f32_e32 v152, v152
	v_add_f32_e32 v151, 1.0, v151
	v_rcp_f32_e32 v150, v150
	v_rcp_f32_e32 v149, v149
	v_add_f32_e32 v148, 1.0, v148
	v_exp_f32_e32 v135, v135
	v_exp_f32_e32 v132, v132
	v_mul_f32_e32 v173, v62, v173
	v_mul_f32_e32 v175, v64, v175
	s_nop 0
	v_cvt_pk_bf16_f32 v174, v173, v174
	v_rcp_f32_e32 v151, v151
	v_rcp_f32_e32 v148, v148
	v_add_f32_e32 v147, 1.0, v147
	v_add_f32_e32 v146, 1.0, v146
	v_add_f32_e32 v145, 1.0, v145
	v_add_f32_e32 v144, 1.0, v144
	v_add_f32_e32 v142, 1.0, v142
	v_add_f32_e32 v141, 1.0, v141
	v_mul_f32_e32 v176, v65, v176
	s_nop 0
	v_cvt_pk_bf16_f32 v175, v175, v176
	ds_write_b64 v171, v[174:175] offset:25632
	v_add_u32_e32 v173, 0x10800, v171
	v_mul_f32_e32 v172, v70, v172
	v_mul_f32_e32 v162, v71, v162
	v_mul_f32_e32 v161, v72, v161
	v_mul_f32_e32 v174, v73, v160
	s_nop 0
	v_cvt_pk_bf16_f32 v160, v172, v162
	v_mul_f32_e32 v158, v47, v158
	v_mul_f32_e32 v157, v48, v157
	v_rcp_f32_e32 v147, v147
	v_rcp_f32_e32 v146, v146
	v_rcp_f32_e32 v145, v145
	v_rcp_f32_e32 v144, v144
	v_add_f32_e32 v143, 1.0, v143
	v_rcp_f32_e32 v142, v142
	v_rcp_f32_e32 v141, v141
	v_add_f32_e32 v140, 1.0, v140
	s_nop 0
	v_cvt_pk_bf16_f32 v161, v161, v174
	ds_write_b64 v173, v[160:161]
	v_mul_f32_e32 v159, v46, v159
	v_mul_f32_e32 v160, v49, v156
	s_nop 0
	v_cvt_pk_bf16_f32 v156, v159, v158
	s_nop 0
	v_cvt_pk_bf16_f32 v157, v157, v160
	v_add_u32_e32 v158, 0x10820, v171
	v_rcp_f32_e32 v143, v143
	v_rcp_f32_e32 v140, v140
	v_add_f32_e32 v139, 1.0, v139
	v_add_f32_e32 v138, 1.0, v138
	v_add_f32_e32 v137, 1.0, v137
	v_add_f32_e32 v136, 1.0, v136
	v_add_f32_e32 v134, 1.0, v134
	v_add_f32_e32 v133, 1.0, v133
	ds_write_b64 v158, v[156:157]
	v_add_u32_e32 v156, 0x12900, v171
	v_mul_f32_e32 v155, v42, v155
	v_mul_f32_e32 v154, v43, v154
	v_mul_f32_e32 v153, v44, v153
	v_mul_f32_e32 v157, v45, v152
	s_nop 0
	v_cvt_pk_bf16_f32 v152, v155, v154
	v_mul_f32_e32 v150, v31, v150
	v_mul_f32_e32 v149, v32, v149
; __device__ __forceinline__ float siluf(float v) { return v * __builtin_amdgcn_rcpf(1.f + __expf(-v)); }
; #define FOR_FRAG(ai, bj, m, n) _Pragma("unroll") for (int ai = 0; ai < 2; ++ai) _Pragma("unroll") for (int bj = 0; bj < 2; ++bj) \
;   _Pragma("unroll") for (int m = 0; m < 4; ++m) _Pragma("unroll") for (int n = 0; n < 2; ++n)
; __device__ __forceinline__ u32x2 pack4(float a, float b, float c, float d) { return u32x2{cvtpk(a, b), cvtpk(c, d)}; }
; __device__ __forceinline__ void phase2(const Params& p, char* shm) {
;     ...
;         dst = Zb + (size_t)brow * AW + (pn - 28) * 256;
;         FOR_FRAG(ai, bj, m, n) { const f32x4 v = acc[ai][bj][m][n]; *(u32x2*)(ctb + CT_OFF(ai, bj, m, n)) = pack4(siluf(v[0]), siluf(v[1]), siluf(v[2]), siluf(v[3])); }
	v_rcp_f32_e32 v139, v139
	v_rcp_f32_e32 v138, v138
	v_rcp_f32_e32 v137, v137
	v_rcp_f32_e32 v136, v136
	v_add_f32_e32 v135, 1.0, v135
	v_rcp_f32_e32 v134, v134
	v_rcp_f32_e32 v133, v133
	v_add_f32_e32 v132, 1.0, v132
	s_nop 0
	v_cvt_pk_bf16_f32 v153, v153, v157
	ds_write_b64 v156, v[152:153]
	v_mul_f32_e32 v151, v30, v151
	v_mul_f32_e32 v152, v33, v148
	s_nop 0
	v_cvt_pk_bf16_f32 v148, v151, v150
	s_nop 0
	v_cvt_pk_bf16_f32 v149, v149, v152
	v_add_u32_e32 v150, 0x12920, v171
	v_rcp_f32_e32 v135, v135
	v_rcp_f32_e32 v132, v132
	ds_write_b64 v150, v[148:149]
	v_add_u32_e32 v148, 0x14a00, v171
	v_mul_f32_e32 v147, v26, v147
	v_mul_f32_e32 v146, v27, v146
	v_mul_f32_e32 v145, v28, v145
	v_mul_f32_e32 v149, v29, v144
	s_nop 0
	v_cvt_pk_bf16_f32 v144, v147, v146
	v_mul_f32_e32 v142, v15, v142
	v_mul_f32_e32 v141, v16, v141
	s_nop 0
	v_cvt_pk_bf16_f32 v145, v145, v149
	ds_write_b64 v148, v[144:145]
	v_mul_f32_e32 v143, v14, v143
	v_mul_f32_e32 v144, v17, v140
	s_nop 0
	v_cvt_pk_bf16_f32 v140, v143, v142
	s_nop 0
	v_cvt_pk_bf16_f32 v141, v141, v144
	v_add_u32_e32 v142, 0x14a20, v171
	ds_write_b64 v142, v[140:141]
	v_add_u32_e32 v140, 0x16b00, v171
	v_mul_f32_e32 v139, v10, v139
	v_mul_f32_e32 v138, v11, v138
	v_mul_f32_e32 v137, v12, v137
	v_mul_f32_e32 v141, v13, v136
	s_nop 0
	v_cvt_pk_bf16_f32 v136, v139, v138
	v_mul_f32_e32 v134, v3, v134
	v_mul_f32_e32 v133, v4, v133
	s_nop 0
	v_cvt_pk_bf16_f32 v137, v137, v141
	ds_write_b64 v140, v[136:137]
	v_mul_f32_e32 v135, v2, v135
	v_mul_f32_e32 v136, v5, v132
	s_nop 0
	v_cvt_pk_bf16_f32 v132, v135, v134
	s_nop 0
	v_cvt_pk_bf16_f32 v133, v133, v136
	v_add_u32_e32 v134, 0x16b20, v171
	ds_write_b64 v134, v[132:133]
	v_mul_f32_e32 v133, 0xbfb8aa3b, v80
	v_exp_f32_e32 v131, v131
	v_exp_f32_e32 v130, v130
	v_exp_f32_e32 v133, v133
	v_mul_f32_e32 v134, 0xbfb8aa3b, v81
	v_exp_f32_e32 v134, v134
	v_add_f32_e32 v131, 1.0, v131
	v_add_f32_e32 v130, 1.0, v130
	v_add_f32_e32 v133, 1.0, v133
	v_rcp_f32_e32 v131, v131
	v_rcp_f32_e32 v130, v130
	v_rcp_f32_e32 v133, v133
	v_add_f32_e32 v134, 1.0, v134
	v_rcp_f32_e32 v134, v134
	v_mul_f32_e32 v131, v78, v131
	v_mul_f32_e32 v130, v79, v130
	v_mul_f32_e32 v133, v80, v133
	v_mul_f32_e32 v134, v81, v134
	s_nop 0
	v_cvt_pk_bf16_f32 v130, v131, v130
	s_nop 0
	v_cvt_pk_bf16_f32 v131, v133, v134
	v_mul_f32_e32 v133, 0xbfb8aa3b, v58
	v_exp_f32_e32 v133, v133
	v_add_u32_e32 v132, 0x10900, v171
	v_mul_f32_e32 v134, 0xbfb8aa3b, v59
	ds_write_b64 v132, v[130:131]
	v_mul_f32_e32 v132, 0xbfb8aa3b, v60
	v_exp_f32_e32 v134, v134
	v_add_f32_e32 v130, 1.0, v133
	v_exp_f32_e32 v132, v132
	v_mul_f32_e32 v133, 0xbfb8aa3b, v61
	v_exp_f32_e32 v133, v133
	v_add_f32_e32 v131, 1.0, v134
	v_add_f32_e32 v132, 1.0, v132
	v_rcp_f32_e32 v130, v130
	v_rcp_f32_e32 v131, v131
	v_rcp_f32_e32 v132, v132
	v_add_f32_e32 v133, 1.0, v133
	v_rcp_f32_e32 v133, v133
	v_mul_f32_e32 v130, v58, v130
	v_mul_f32_e32 v131, v59, v131
	v_mul_f32_e32 v132, v60, v132
	v_mul_f32_e32 v133, v61, v133
	s_nop 0
	v_cvt_pk_bf16_f32 v130, v130, v131
	s_nop 0
	v_cvt_pk_bf16_f32 v131, v132, v133
	v_add_u32_e32 v132, 0x10920, v171
	ds_write_b64 v132, v[130:131]
	v_mul_f32_e32 v130, 0xbfb8aa3b, v54
	v_mul_f32_e32 v131, 0xbfb8aa3b, v55
	v_mul_f32_e32 v133, 0xbfb8aa3b, v56
	v_exp_f32_e32 v130, v130
	v_exp_f32_e32 v131, v131
	v_exp_f32_e32 v133, v133
	v_mul_f32_e32 v134, 0xbfb8aa3b, v57
	v_exp_f32_e32 v134, v134
	v_add_f32_e32 v130, 1.0, v130
	v_add_f32_e32 v131, 1.0, v131
	v_add_f32_e32 v133, 1.0, v133
	v_rcp_f32_e32 v130, v130
	v_rcp_f32_e32 v131, v131
	v_rcp_f32_e32 v133, v133
	v_add_f32_e32 v134, 1.0, v134
	v_rcp_f32_e32 v134, v134
	v_mul_f32_e32 v130, v54, v130
	v_mul_f32_e32 v131, v55, v131
	v_mul_f32_e32 v133, v56, v133
	v_mul_f32_e32 v134, v57, v134
	s_nop 0
	v_cvt_pk_bf16_f32 v130, v130, v131
	s_nop 0
	v_cvt_pk_bf16_f32 v131, v133, v134
	v_mul_f32_e32 v133, 0xbfb8aa3b, v38
	v_exp_f32_e32 v133, v133
	v_add_u32_e32 v132, 0x12a00, v171
	v_mul_f32_e32 v134, 0xbfb8aa3b, v39
; __device__ __forceinline__ float siluf(float v) { return v * __builtin_amdgcn_rcpf(1.f + __expf(-v)); }
; #define FOR_FRAG(ai, bj, m, n) _Pragma("unroll") for (int ai = 0; ai < 2; ++ai) _Pragma("unroll") for (int bj = 0; bj < 2; ++bj) \
;   _Pragma("unroll") for (int m = 0; m < 4; ++m) _Pragma("unroll") for (int n = 0; n < 2; ++n)
; __device__ __forceinline__ u32x2 pack4(float a, float b, float c, float d) { return u32x2{cvtpk(a, b), cvtpk(c, d)}; }
; __device__ __forceinline__ void phase2(const Params& p, char* shm) {
;     ...
;         dst = Zb + (size_t)brow * AW + (pn - 28) * 256;
;         FOR_FRAG(ai, bj, m, n) { const f32x4 v = acc[ai][bj][m][n]; *(u32x2*)(ctb + CT_OFF(ai, bj, m, n)) = pack4(siluf(v[0]), siluf(v[1]), siluf(v[2]), siluf(v[3])); }
	ds_write_b64 v132, v[130:131]
	v_mul_f32_e32 v132, 0xbfb8aa3b, v40
	v_exp_f32_e32 v134, v134
	v_add_f32_e32 v130, 1.0, v133
	v_exp_f32_e32 v132, v132
	v_mul_f32_e32 v133, 0xbfb8aa3b, v41
	v_exp_f32_e32 v133, v133
	v_add_f32_e32 v131, 1.0, v134
	v_add_f32_e32 v132, 1.0, v132
	v_rcp_f32_e32 v130, v130
	v_rcp_f32_e32 v131, v131
	v_rcp_f32_e32 v132, v132
	v_add_f32_e32 v133, 1.0, v133
	v_rcp_f32_e32 v133, v133
	v_mul_f32_e32 v130, v38, v130
	v_mul_f32_e32 v131, v39, v131
	v_mul_f32_e32 v132, v40, v132
	v_mul_f32_e32 v133, v41, v133
	s_nop 0
	v_cvt_pk_bf16_f32 v130, v130, v131
	s_nop 0
	v_cvt_pk_bf16_f32 v131, v132, v133
	v_add_u32_e32 v132, 0x12a20, v171
	ds_write_b64 v132, v[130:131]
	v_mul_f32_e32 v130, 0xbfb8aa3b, v34
	v_mul_f32_e32 v131, 0xbfb8aa3b, v35
	v_mul_f32_e32 v133, 0xbfb8aa3b, v36
	v_exp_f32_e32 v130, v130
	v_exp_f32_e32 v131, v131
	v_exp_f32_e32 v133, v133
	v_mul_f32_e32 v134, 0xbfb8aa3b, v37
	v_exp_f32_e32 v134, v134
	v_add_f32_e32 v130, 1.0, v130
	v_add_f32_e32 v131, 1.0, v131
	v_add_f32_e32 v133, 1.0, v133
	v_rcp_f32_e32 v130, v130
	v_rcp_f32_e32 v131, v131
	v_rcp_f32_e32 v133, v133
	v_add_f32_e32 v134, 1.0, v134
	v_rcp_f32_e32 v134, v134
	v_mul_f32_e32 v130, v34, v130
	v_mul_f32_e32 v131, v35, v131
	v_mul_f32_e32 v133, v36, v133
	v_mul_f32_e32 v134, v37, v134
	s_nop 0
	v_cvt_pk_bf16_f32 v130, v130, v131
	s_nop 0
	v_cvt_pk_bf16_f32 v131, v133, v134
	v_mul_f32_e32 v133, 0xbfb8aa3b, v22
	v_exp_f32_e32 v133, v133
	v_add_u32_e32 v132, 0x14b00, v171
	v_mul_f32_e32 v134, 0xbfb8aa3b, v23
	ds_write_b64 v132, v[130:131]
	v_mul_f32_e32 v132, 0xbfb8aa3b, v24
	v_exp_f32_e32 v134, v134
	v_add_f32_e32 v130, 1.0, v133
	v_exp_f32_e32 v132, v132
	v_mul_f32_e32 v133, 0xbfb8aa3b, v25
	v_exp_f32_e32 v133, v133
	v_add_f32_e32 v131, 1.0, v134
	v_add_f32_e32 v132, 1.0, v132
	v_rcp_f32_e32 v130, v130
	v_rcp_f32_e32 v131, v131
	v_rcp_f32_e32 v132, v132
	v_add_f32_e32 v133, 1.0, v133
	v_rcp_f32_e32 v133, v133
	v_mul_f32_e32 v130, v22, v130
	v_mul_f32_e32 v131, v23, v131
	v_mul_f32_e32 v132, v24, v132
	v_mul_f32_e32 v133, v25, v133
	s_nop 0
	v_cvt_pk_bf16_f32 v130, v130, v131
	s_nop 0
	v_cvt_pk_bf16_f32 v131, v132, v133
	v_add_u32_e32 v132, 0x14b20, v171
	ds_write_b64 v132, v[130:131]
	v_mul_f32_e32 v130, 0xbfb8aa3b, v18
	v_mul_f32_e32 v131, 0xbfb8aa3b, v19
	v_mul_f32_e32 v133, 0xbfb8aa3b, v20
	v_exp_f32_e32 v130, v130
	v_exp_f32_e32 v131, v131
	v_exp_f32_e32 v133, v133
	v_mul_f32_e32 v134, 0xbfb8aa3b, v21
	v_exp_f32_e32 v134, v134
	v_add_f32_e32 v130, 1.0, v130
	v_add_f32_e32 v131, 1.0, v131
	v_add_f32_e32 v133, 1.0, v133
	v_rcp_f32_e32 v130, v130
	v_rcp_f32_e32 v131, v131
	v_rcp_f32_e32 v133, v133
	v_add_f32_e32 v134, 1.0, v134
	v_rcp_f32_e32 v134, v134
	v_mul_f32_e32 v130, v18, v130
	v_mul_f32_e32 v131, v19, v131
	v_mul_f32_e32 v133, v20, v133
	v_mul_f32_e32 v134, v21, v134
	s_nop 0
	v_cvt_pk_bf16_f32 v130, v130, v131
	s_nop 0
	v_cvt_pk_bf16_f32 v131, v133, v134
	v_mul_f32_e32 v133, 0xbfb8aa3b, v6
	v_exp_f32_e32 v133, v133
	v_add_u32_e32 v132, 0x16c00, v171
	v_mul_f32_e32 v134, 0xbfb8aa3b, v7
	ds_write_b64 v132, v[130:131]
	v_mul_f32_e32 v132, 0xbfb8aa3b, v8
	v_exp_f32_e32 v134, v134
	v_add_f32_e32 v130, 1.0, v133
	v_exp_f32_e32 v132, v132
	v_mul_f32_e32 v133, 0xbfb8aa3b, v9
	v_exp_f32_e32 v133, v133
	s_lshl_b64 s[0:1], s[40:41], 11
	v_add_f32_e32 v131, 1.0, v134
	v_add_f32_e32 v132, 1.0, v132
	s_add_u32 s0, s26, s0
	v_rcp_f32_e32 v130, v130
	v_rcp_f32_e32 v131, v131
	v_rcp_f32_e32 v132, v132
	v_add_f32_e32 v133, 1.0, v133
	s_addc_u32 s1, s27, s1
	s_lshl_b32 s16, s38, 9
	v_rcp_f32_e32 v133, v133
	s_add_u32 s0, s0, s16
	s_addc_u32 s1, s1, 0
	v_mul_f32_e32 v130, v6, v130
	v_mul_f32_e32 v131, v7, v131
	v_mul_f32_e32 v132, v8, v132
	s_add_u32 s0, s0, 0x25034900
	v_mul_f32_e32 v133, v9, v133
	s_nop 0
	v_cvt_pk_bf16_f32 v130, v130, v131
	s_nop 0
	v_cvt_pk_bf16_f32 v131, v132, v133
	v_add_u32_e32 v132, 0x16c20, v171
	s_addc_u32 s1, s1, 0
	s_mov_b64 s[44:45], 0x400
	ds_write_b64 v132, v[130:131]

; #define ACC_ZERO(acc) _Pragma("unroll") for (int a_ = 0; a_ < 2; ++a_) _Pragma("unroll") for (int b_ = 0; b_ < 2; ++b_) \
;   _Pragma("unroll") for (int m_ = 0; m_ < 4; ++m_) _Pragma("unroll") for (int n_ = 0; n_ < 2; ++n_) acc[a_][b_][m_][n_] = f32x4{0.f, 0.f, 0.f, 0.f}
; __device__ __forceinline__ void phase4(const Params& p, char* shm) {
;   const u16* Ain = (const u16*)(p.ws + OFF_AIN); const u16* Bin = (const u16*)(p.ws + OFF_BIN);
;   const u16* Wa = (const u16*)(p.ws + OFF_WTOA); const u16* Wb = (const u16*)(p.ws + OFF_WTOB);
;   const u16* Gates = (const u16*)p.out; u16* Mg = (u16*)(p.ws + OFF_H);
;   for (int tile = blockIdx.x; tile < 1024; tile += gridDim.x) {
;     const int r = tile >> 8, l = tile & 255, xcd = l & 7, off = l >> 3;
;     const int pm = r * 32 + xcd * 4 + (off & 3), pn = off >> 2;
;     const size_t brow = (size_t)pm * 256; const int bcol = pn * 256;
;     f32x4 acc[2][2][4][2]; ACC_ZERO(acc);
.LBB0_445:
	s_cmp_lt_i32 s10, 5
	s_cselect_b64 s[0:1], -1, 0
	s_and_b64 s[4:5], s[0:1], s[4:5]
	s_andn2_b64 vcc, exec, s[4:5]
	s_cbranch_vccnz .LBB0_467
	s_cmpk_gt_i32 s2, 0x3ff
	s_cbranch_scc1 .LBB0_467
	s_add_u32 s3, s26, 0x4038100
	s_waitcnt lgkmcnt(0)
	s_addc_u32 s38, s27, 0
	v_and_b32_e32 v1, 0x3ff, v0
	s_lshl_b32 s39, s2, 3
	s_lshl_b32 s40, s33, 3
	s_lshl_b32 s41, s2, 2
	s_lshl_b32 s42, s33, 2
	v_mov_b32_e32 v3, 0
	s_mov_b32 s43, 0x14838100
	s_mov_b32 s44, 0x3038100
	s_movk_i32 s45, 0x2000
	s_add_i32 s46, 0, 0x18000
	s_add_i32 s47, 0, 0x1c000
	s_movk_i32 s48, 0x3c0
	s_mov_b32 s49, 0x100000
	s_movk_i32 s50, 0x100
	s_mov_b32 s51, 0x3fffffc0
	s_movk_i32 s52, 0x104
	s_movk_i32 s53, 0x600
	s_mov_b32 s54, 0x1fffffc0
	s_movk_i32 s55, 0x108
	s_mov_b64 s[4:5], 0x100000
	s_movk_i32 s56, 0x5ff
	s_movk_i32 s57, 0x17ff
	s_mov_b32 s61, s2
	s_branch .LBB0_449

; #define ACC_ZERO(acc) _Pragma("unroll") for (int a_ = 0; a_ < 2; ++a_) _Pragma("unroll") for (int b_ = 0; b_ < 2; ++b_) \
;   _Pragma("unroll") for (int m_ = 0; m_ < 4; ++m_) _Pragma("unroll") for (int n_ = 0; n_ < 2; ++n_) acc[a_][b_][m_][n_] = f32x4{0.f, 0.f, 0.f, 0.f}
; __device__ __forceinline__ void phase4(const Params& p, char* shm) {
;     ...
;   for (int tile = blockIdx.x; tile < 1024; tile += gridDim.x) {
;     const int r = tile >> 8, l = tile & 255, xcd = l & 7, off = l >> 3;
;     const int pm = r * 32 + xcd * 4 + (off & 3), pn = off >> 2;
;     const size_t brow = (size_t)pm * 256; const int bcol = pn * 256;
;     f32x4 acc[2][2][4][2]; ACC_ZERO(acc);
.LBB0_449:
	s_lshl_b32 s6, s39, 11
	s_and_b32 s62, s6, 0x380000
	s_ashr_i32 s6, s61, 3
	s_and_b32 s17, s6, 0xffffffe0
	s_lshl_b32 s6, s61, 2
	s_and_b32 s6, s6, 28
	s_or_b32 s6, s17, s6
	s_bfe_u32 s18, s61, 0x20003
	s_or_b32 s6, s6, s18
	s_lshl_b32 s8, s61, 3
	s_ashr_i32 s7, s6, 31
	s_and_b32 s16, s41, 28
	s_and_b32 s63, s8, 0x700
	s_lshl_b64 s[8:9], s[6:7], 19
	s_add_u32 s64, s26, s8
	s_addc_u32 s65, s27, s9
	s_lshl_b32 s8, s63, 11
	s_add_u32 s66, s26, s8
	s_addc_u32 s67, s27, 0
	s_lshl_b32 s8, s63, 9
	s_add_u32 s12, s24, s8
	s_addc_u32 s13, s25, 0
	s_lshl_b64 s[8:9], s[6:7], 21
	s_add_u32 s12, s12, s8
	s_addc_u32 s13, s13, s9
	s_add_u32 s14, s12, 0x10000
	s_addc_u32 s15, s13, 0
	s_or_b32 s16, s17, s16
	s_or_b32 s16, s16, s18
	v_mov_b32_e32 v4, v3
	v_mov_b32_e32 v5, v3
	s_ashr_i32 s17, s16, 31
	v_mov_b32_e32 v2, v3
	v_mov_b64_e32 v[8:9], v[4:5]
	v_mov_b64_e32 v[12:13], v[4:5]
	v_mov_b64_e32 v[16:17], v[4:5]
	v_mov_b64_e32 v[20:21], v[4:5]
	v_mov_b64_e32 v[24:25], v[4:5]
	v_mov_b64_e32 v[28:29], v[4:5]
	v_mov_b64_e32 v[32:33], v[4:5]
	v_mov_b64_e32 v[36:37], v[4:5]
	v_mov_b64_e32 v[40:41], v[4:5]
	v_mov_b64_e32 v[44:45], v[4:5]
	v_mov_b64_e32 v[48:49], v[4:5]
	v_mov_b64_e32 v[52:53], v[4:5]
	v_mov_b64_e32 v[56:57], v[4:5]
	v_mov_b64_e32 v[60:61], v[4:5]
	v_mov_b64_e32 v[64:65], v[4:5]
	v_mov_b64_e32 v[68:69], v[4:5]
	v_mov_b64_e32 v[72:73], v[4:5]
	v_mov_b64_e32 v[76:77], v[4:5]
	v_mov_b64_e32 v[80:81], v[4:5]
	v_mov_b64_e32 v[84:85], v[4:5]
	v_mov_b64_e32 v[88:89], v[4:5]
	v_mov_b64_e32 v[92:93], v[4:5]
	v_mov_b64_e32 v[96:97], v[4:5]
	v_mov_b64_e32 v[100:101], v[4:5]
	v_mov_b64_e32 v[104:105], v[4:5]
	v_mov_b64_e32 v[108:109], v[4:5]
	v_mov_b64_e32 v[112:113], v[4:5]
	v_mov_b64_e32 v[116:117], v[4:5]
	v_mov_b64_e32 v[120:121], v[4:5]
	v_mov_b64_e32 v[124:125], v[4:5]
	v_mov_b64_e32 v[128:129], v[4:5]
	v_mov_b64_e32 v[132:133], v[4:5]
	s_lshl_b64 s[16:17], s[16:17], 19
	v_mov_b64_e32 v[6:7], v[2:3]
	v_mov_b64_e32 v[10:11], v[2:3]
	v_mov_b64_e32 v[14:15], v[2:3]
	v_mov_b64_e32 v[18:19], v[2:3]
	v_mov_b64_e32 v[22:23], v[2:3]
	v_mov_b64_e32 v[26:27], v[2:3]
	v_mov_b64_e32 v[30:31], v[2:3]
	v_mov_b64_e32 v[34:35], v[2:3]
	v_mov_b64_e32 v[38:39], v[2:3]
	v_mov_b64_e32 v[42:43], v[2:3]
	v_mov_b64_e32 v[46:47], v[2:3]
	v_mov_b64_e32 v[50:51], v[2:3]
	v_mov_b64_e32 v[54:55], v[2:3]
	v_mov_b64_e32 v[58:59], v[2:3]
	v_mov_b64_e32 v[62:63], v[2:3]
	v_mov_b64_e32 v[66:67], v[2:3]
	v_mov_b64_e32 v[70:71], v[2:3]
	v_mov_b64_e32 v[74:75], v[2:3]
	v_mov_b64_e32 v[78:79], v[2:3]
	v_mov_b64_e32 v[82:83], v[2:3]
	v_mov_b64_e32 v[86:87], v[2:3]
	v_mov_b64_e32 v[90:91], v[2:3]
	v_mov_b64_e32 v[94:95], v[2:3]
	v_mov_b64_e32 v[98:99], v[2:3]
	v_mov_b64_e32 v[102:103], v[2:3]
	v_mov_b64_e32 v[106:107], v[2:3]
	v_mov_b64_e32 v[110:111], v[2:3]
	v_mov_b64_e32 v[114:115], v[2:3]
	v_mov_b64_e32 v[118:119], v[2:3]
	v_mov_b64_e32 v[122:123], v[2:3]
	v_mov_b64_e32 v[126:127], v[2:3]
	v_mov_b64_e32 v[130:131], v[2:3]
	s_mov_b64 s[20:21], -1
	s_branch .LBB0_451

; __device__ __forceinline__ float bflo(unsigned v) { return __uint_as_float(v << 16); }
; __device__ __forceinline__ float bfhi(unsigned v) { return __uint_as_float(v & 0xffff0000u); }
; __device__ __forceinline__ void phase4(const Params& p, char* shm) {
;     ...
;       if (half == 0) {
; #pragma unroll
;     for (int ai = 0; ai < 2; ++ai) {
;       GEMM_IDS;
;       char* const cfb = CF_BASE(shm);
;       const u16* gsrc = Gates + (brow + ai * 128) * 4096 + bcol;
; #pragma unroll
;       for (int b8 = 0; b8 < 2; ++b8) {
;         u32x2 ga[8], gb[8];
; #pragma unroll
;         for (int i = 0; i < 8; ++i) { const int id = tid + (b8 * 8 + i) * NTHR, row = id >> 6, c = id & 63;
;           ga[i] = *reinterpret_cast<const u32x2*>(gsrc + (size_t)row * 4096 + c * 4);
;           gb[i] = *reinterpret_cast<const u32x2*>(gsrc + (size_t)row * 4096 + 2048 + c * 4); }
; #pragma unroll
;         for (int i = 0; i < 8; ++i) { const int id = tid + (b8 * 8 + i) * NTHR, row = id >> 6, c = id & 63;
;           f32x4 rt = { bflo(ga[i][0]) * __builtin_amdgcn_rcpf(bflo(gb[i][0])), bfhi(ga[i][0]) * __builtin_amdgcn_rcpf(bfhi(gb[i][0])),
;                        bflo(ga[i][1]) * __builtin_amdgcn_rcpf(bflo(gb[i][1])), bfhi(ga[i][1]) * __builtin_amdgcn_rcpf(bfhi(gb[i][1])) };
;           *reinterpret_cast<f32x4*>(shm + (row * CF_LD + c * 4) * 4) = rt; }
;       }
.LBB0_457:
	s_or_b64 exec, exec, s[30:31]
	s_andn2_b64 vcc, exec, s[20:21]
	s_barrier
	s_cbranch_vccnz .LBB0_450
	v_mov_b32_e32 v187, v1
	s_nop 0
	v_and_b32_e32 v2, 15, v187
	v_lshrrev_b32_e32 v4, 2, v187
	v_and_or_b32 v2, v4, s51, v2
	v_mul_lo_u32 v5, v2, s52
	v_lshrrev_b32_e32 v2, 1, v187
	v_ashrrev_i32_e32 v140, 6, v187
	v_and_b32_e32 v134, 0x60, v2
	v_lshlrev_b32_e32 v2, 2, v187
	v_ashrrev_i32_e32 v141, 31, v140
	v_and_b32_e32 v4, 0xfc, v2
	v_lshlrev_b64 v[136:137], 9, v[140:141]
	v_lshl_add_u64 v[136:137], s[12:13], 0, v[136:137]
	v_lshlrev_b32_e32 v2, 1, v4
	v_lshl_add_u64 v[136:137], v[136:137], 0, v[2:3]
	v_add_co_u32_e32 v138, vcc, s49, v136
	v_add_u32_e32 v141, 0x600, v187
	s_nop 0
	v_addc_co_u32_e32 v139, vcc, 0, v137, vcc
	global_load_dwordx2 v[142:143], v[136:137], off
	s_nop 0
	global_load_dwordx2 v[136:137], v[138:139], off
	v_add_u32_e32 v138, 0x200, v187
	v_ashrrev_i32_e32 v144, 6, v138
	v_ashrrev_i32_e32 v145, 31, v144
	v_lshlrev_b64 v[138:139], 9, v[144:145]
	v_lshl_add_u64 v[138:139], s[12:13], 0, v[138:139]
	v_lshl_add_u64 v[138:139], v[138:139], 0, v[2:3]
	v_add_co_u32_e32 v146, vcc, s49, v138
	v_ashrrev_i32_e32 v154, 6, v141
	s_nop 0
	v_addc_co_u32_e32 v147, vcc, 0, v139, vcc
	global_load_dwordx2 v[148:149], v[138:139], off
	s_nop 0
	global_load_dwordx2 v[146:147], v[146:147], off
	v_add_u32_e32 v138, 0x400, v187
	v_ashrrev_i32_e32 v150, 6, v138
	v_ashrrev_i32_e32 v151, 31, v150
	v_lshlrev_b64 v[138:139], 9, v[150:151]
	v_lshl_add_u64 v[138:139], s[12:13], 0, v[138:139]
	v_ashrrev_i32_e32 v155, 31, v154
	v_lshl_add_u64 v[138:139], v[138:139], 0, v[2:3]
	v_lshlrev_b64 v[156:157], 9, v[154:155]
	v_add_co_u32_e32 v152, vcc, s49, v138
	v_lshl_add_u64 v[156:157], s[12:13], 0, v[156:157]
	s_nop 0
	v_addc_co_u32_e32 v153, vcc, 0, v139, vcc
	v_lshl_add_u64 v[156:157], v[156:157], 0, v[2:3]
	v_add_co_u32_e32 v158, vcc, s49, v156
	v_add_u32_e32 v141, 0xa00, v187
	s_nop 0
	v_addc_co_u32_e32 v159, vcc, 0, v157, vcc
	global_load_dwordx2 v[160:161], v[138:139], off
	s_nop 0
	global_load_dwordx2 v[152:153], v[152:153], off
	s_nop 0
	global_load_dwordx2 v[156:157], v[156:157], off
	s_nop 0
	global_load_dwordx2 v[158:159], v[158:159], off
	v_add_u32_e32 v138, 0x800, v187
	v_ashrrev_i32_e32 v162, 6, v138
	v_ashrrev_i32_e32 v163, 31, v162
	v_lshlrev_b64 v[138:139], 9, v[162:163]
	v_ashrrev_i32_e32 v166, 6, v141
	v_lshl_add_u64 v[138:139], s[12:13], 0, v[138:139]
	v_ashrrev_i32_e32 v167, 31, v166
	v_lshl_add_u64 v[138:139], v[138:139], 0, v[2:3]
	v_lshlrev_b64 v[168:169], 9, v[166:167]
	v_add_co_u32_e32 v164, vcc, s49, v138
	v_lshl_add_u64 v[168:169], s[12:13], 0, v[168:169]
	s_nop 0
	v_addc_co_u32_e32 v165, vcc, 0, v139, vcc
	v_lshl_add_u64 v[168:169], v[168:169], 0, v[2:3]
	v_add_co_u32_e32 v170, vcc, s49, v168
	v_add_u32_e32 v141, 0xe00, v187
	s_nop 0
	v_addc_co_u32_e32 v171, vcc, 0, v169, vcc
	global_load_dwordx2 v[172:173], v[138:139], off
	s_nop 0
	global_load_dwordx2 v[164:165], v[164:165], off
	s_nop 0
	global_load_dwordx2 v[168:169], v[168:169], off
	s_nop 0
	global_load_dwordx2 v[170:171], v[170:171], off
	v_add_u32_e32 v138, 0xc00, v187
	v_ashrrev_i32_e32 v174, 6, v138
	v_ashrrev_i32_e32 v175, 31, v174
	v_lshlrev_b64 v[138:139], 9, v[174:175]
	v_ashrrev_i32_e32 v178, 6, v141
	v_lshl_add_u64 v[138:139], s[12:13], 0, v[138:139]
	v_ashrrev_i32_e32 v179, 31, v178
	v_lshl_add_u64 v[138:139], v[138:139], 0, v[2:3]
	v_lshlrev_b64 v[180:181], 9, v[178:179]
	v_add_co_u32_e32 v176, vcc, s49, v138
	v_lshl_add_u64 v[180:181], s[12:13], 0, v[180:181]
	s_nop 0
	v_addc_co_u32_e32 v177, vcc, 0, v139, vcc
	v_lshl_add_u64 v[180:181], v[180:181], 0, v[2:3]
	v_add_co_u32_e32 v182, vcc, s49, v180
	v_mad_u64_u32 v[140:141], s[20:21], v140, s52, v[4:5]
	s_nop 0
	v_addc_co_u32_e32 v183, vcc, 0, v181, vcc
	global_load_dwordx2 v[184:185], v[138:139], off
	s_nop 0
	global_load_dwordx2 v[176:177], v[176:177], off
	s_nop 0
	global_load_dwordx2 v[180:181], v[180:181], off
	s_nop 0
	global_load_dwordx2 v[182:183], v[182:183], off
	v_lshl_add_u32 v140, v140, 2, 0
	v_and_b32_e32 v135, 48, v187
	s_waitcnt vmcnt(15)
	v_lshlrev_b32_e32 v188, 16, v142
	s_waitcnt vmcnt(14)
	v_lshlrev_b32_e32 v138, 16, v136
	v_and_b32_e32 v136, 0xffff0000, v136
	v_rcp_f32_e32 v139, v136
	v_lshlrev_b32_e32 v136, 16, v137
	v_rcp_f32_e32 v138, v138
	v_rcp_f32_e32 v190, v136
	v_and_b32_e32 v136, 0xffff0000, v137
	v_rcp_f32_e32 v191, v136
	v_and_b32_e32 v189, 0xffff0000, v142
	v_pk_mul_f32 v[136:137], v[138:139], v[188:189]
	v_lshlrev_b32_e32 v138, 16, v143
	v_and_b32_e32 v139, 0xffff0000, v143
	v_pk_mul_f32 v[138:139], v[190:191], v[138:139]
	ds_write_b128 v140, v[136:139]
	s_waitcnt vmcnt(12)
	v_lshlrev_b32_e32 v136, 16, v146
	v_and_b32_e32 v137, 0xffff0000, v146
	v_rcp_f32_e32 v136, v136
	v_rcp_f32_e32 v137, v137
	v_lshlrev_b32_e32 v140, 16, v147
	v_and_b32_e32 v141, 0xffff0000, v147
	v_rcp_f32_e32 v140, v140
	v_rcp_f32_e32 v141, v141
	v_lshlrev_b32_e32 v138, 16, v148
	v_and_b32_e32 v139, 0xffff0000, v148
	v_pk_mul_f32 v[136:137], v[136:137], v[138:139]
	v_lshlrev_b32_e32 v138, 16, v149
	v_and_b32_e32 v139, 0xffff0000, v149
	v_pk_mul_f32 v[138:139], v[140:141], v[138:139]
	v_mad_u64_u32 v[140:141], s[20:21], v144, s52, v[4:5]
	v_lshl_add_u32 v140, v140, 2, 0
	ds_write_b128 v140, v[136:139]
	s_waitcnt vmcnt(10)
	v_lshlrev_b32_e32 v136, 16, v152
	v_and_b32_e32 v137, 0xffff0000, v152
	v_rcp_f32_e32 v136, v136
	v_rcp_f32_e32 v137, v137
	v_lshlrev_b32_e32 v140, 16, v153
	v_and_b32_e32 v141, 0xffff0000, v153
	v_rcp_f32_e32 v140, v140
	v_rcp_f32_e32 v141, v141
	v_lshlrev_b32_e32 v138, 16, v160
	v_and_b32_e32 v139, 0xffff0000, v160
	v_pk_mul_f32 v[136:137], v[136:137], v[138:139]
	v_lshlrev_b32_e32 v138, 16, v161
	v_and_b32_e32 v139, 0xffff0000, v161
	v_pk_mul_f32 v[138:139], v[140:141], v[138:139]
	v_mad_u64_u32 v[140:141], s[20:21], v150, s52, v[4:5]
	v_lshl_add_u32 v140, v140, 2, 0
	ds_write_b128 v140, v[136:139]
	s_waitcnt vmcnt(8)
; __device__ __forceinline__ float bflo(unsigned v) { return __uint_as_float(v << 16); }
; __device__ __forceinline__ float bfhi(unsigned v) { return __uint_as_float(v & 0xffff0000u); }
; __device__ __forceinline__ void phase4(const Params& p, char* shm) {
;     ...
;       for (int b8 = 0; b8 < 2; ++b8) {
;         u32x2 ga[8], gb[8];
; #pragma unroll
;         for (int i = 0; i < 8; ++i) { const int id = tid + (b8 * 8 + i) * NTHR, row = id >> 6, c = id & 63;
;           ga[i] = *reinterpret_cast<const u32x2*>(gsrc + (size_t)row * 4096 + c * 4);
;           gb[i] = *reinterpret_cast<const u32x2*>(gsrc + (size_t)row * 4096 + 2048 + c * 4); }
; #pragma unroll
;         for (int i = 0; i < 8; ++i) { const int id = tid + (b8 * 8 + i) * NTHR, row = id >> 6, c = id & 63;
;           f32x4 rt = { bflo(ga[i][0]) * __builtin_amdgcn_rcpf(bflo(gb[i][0])), bfhi(ga[i][0]) * __builtin_amdgcn_rcpf(bfhi(gb[i][0])),
;                        bflo(ga[i][1]) * __builtin_amdgcn_rcpf(bflo(gb[i][1])), bfhi(ga[i][1]) * __builtin_amdgcn_rcpf(bfhi(gb[i][1])) };
;           *reinterpret_cast<f32x4*>(shm + (row * CF_LD + c * 4) * 4) = rt; }
;       }
	v_lshlrev_b32_e32 v136, 16, v158
	v_and_b32_e32 v137, 0xffff0000, v158
	v_rcp_f32_e32 v136, v136
	v_rcp_f32_e32 v137, v137
	v_lshlrev_b32_e32 v140, 16, v159
	v_and_b32_e32 v141, 0xffff0000, v159
	v_rcp_f32_e32 v140, v140
	v_rcp_f32_e32 v141, v141
	v_lshlrev_b32_e32 v138, 16, v156
	v_and_b32_e32 v139, 0xffff0000, v156
	v_pk_mul_f32 v[136:137], v[136:137], v[138:139]
	v_lshlrev_b32_e32 v138, 16, v157
	v_and_b32_e32 v139, 0xffff0000, v157
	v_pk_mul_f32 v[138:139], v[140:141], v[138:139]
	v_mad_u64_u32 v[140:141], s[20:21], v154, s52, v[4:5]
	v_lshl_add_u32 v140, v140, 2, 0
	ds_write_b128 v140, v[136:139]
	s_waitcnt vmcnt(6)
	v_lshlrev_b32_e32 v136, 16, v164
	v_and_b32_e32 v137, 0xffff0000, v164
	v_rcp_f32_e32 v136, v136
	v_rcp_f32_e32 v137, v137
	v_lshlrev_b32_e32 v140, 16, v165
	v_and_b32_e32 v141, 0xffff0000, v165
	v_rcp_f32_e32 v140, v140
	v_rcp_f32_e32 v141, v141
	v_lshlrev_b32_e32 v138, 16, v172
	v_and_b32_e32 v139, 0xffff0000, v172
	v_pk_mul_f32 v[136:137], v[136:137], v[138:139]
	v_lshlrev_b32_e32 v138, 16, v173
	v_and_b32_e32 v139, 0xffff0000, v173
	v_pk_mul_f32 v[138:139], v[140:141], v[138:139]
	v_mad_u64_u32 v[140:141], s[20:21], v162, s52, v[4:5]
	v_lshl_add_u32 v140, v140, 2, 0
	ds_write_b128 v140, v[136:139]
	s_waitcnt vmcnt(4)
	v_lshlrev_b32_e32 v136, 16, v170
	v_and_b32_e32 v137, 0xffff0000, v170
	v_rcp_f32_e32 v136, v136
	v_rcp_f32_e32 v137, v137
	v_lshlrev_b32_e32 v140, 16, v171
	v_and_b32_e32 v141, 0xffff0000, v171
	v_rcp_f32_e32 v140, v140
	v_rcp_f32_e32 v141, v141
	v_lshlrev_b32_e32 v138, 16, v168
	v_and_b32_e32 v139, 0xffff0000, v168
	v_pk_mul_f32 v[136:137], v[136:137], v[138:139]
	v_lshlrev_b32_e32 v138, 16, v169
	v_and_b32_e32 v139, 0xffff0000, v169
	v_pk_mul_f32 v[138:139], v[140:141], v[138:139]
	v_mad_u64_u32 v[140:141], s[20:21], v166, s52, v[4:5]
	v_lshl_add_u32 v140, v140, 2, 0
	ds_write_b128 v140, v[136:139]
	s_waitcnt vmcnt(2)
	v_lshlrev_b32_e32 v136, 16, v176
	v_and_b32_e32 v137, 0xffff0000, v176
	v_rcp_f32_e32 v136, v136
	v_rcp_f32_e32 v137, v137
	v_lshlrev_b32_e32 v140, 16, v177
	v_and_b32_e32 v141, 0xffff0000, v177
	v_rcp_f32_e32 v140, v140
	v_rcp_f32_e32 v141, v141
	v_lshlrev_b32_e32 v138, 16, v184
	v_and_b32_e32 v139, 0xffff0000, v184
	v_pk_mul_f32 v[136:137], v[136:137], v[138:139]
	v_lshlrev_b32_e32 v138, 16, v185
	v_and_b32_e32 v139, 0xffff0000, v185
	v_pk_mul_f32 v[138:139], v[140:141], v[138:139]
	v_mad_u64_u32 v[140:141], s[20:21], v174, s52, v[4:5]
	v_lshl_add_u32 v140, v140, 2, 0
	ds_write_b128 v140, v[136:139]
	s_waitcnt vmcnt(0)
	v_lshlrev_b32_e32 v136, 16, v182
	v_and_b32_e32 v137, 0xffff0000, v182
	v_rcp_f32_e32 v136, v136
	v_rcp_f32_e32 v137, v137
	v_lshlrev_b32_e32 v140, 16, v183
	v_and_b32_e32 v141, 0xffff0000, v183
	v_rcp_f32_e32 v140, v140
	v_rcp_f32_e32 v141, v141
	v_lshlrev_b32_e32 v138, 16, v180
	v_and_b32_e32 v139, 0xffff0000, v180
	v_pk_mul_f32 v[136:137], v[136:137], v[138:139]
	v_lshlrev_b32_e32 v138, 16, v181
	v_and_b32_e32 v139, 0xffff0000, v181
	v_pk_mul_f32 v[138:139], v[140:141], v[138:139]
	v_mad_u64_u32 v[140:141], s[20:21], v178, s52, v[4:5]
	v_lshl_add_u32 v140, v140, 2, 0
	ds_write_b128 v140, v[136:139]
	v_add_u32_e32 v136, 0x1000, v187
	v_ashrrev_i32_e32 v140, 6, v136
	v_ashrrev_i32_e32 v141, 31, v140
	v_lshlrev_b64 v[136:137], 9, v[140:141]
	v_lshl_add_u64 v[136:137], s[12:13], 0, v[136:137]
	v_lshl_add_u64 v[136:137], v[136:137], 0, v[2:3]
	v_add_co_u32_e32 v138, vcc, s49, v136
	v_add_u32_e32 v141, 0x1600, v187
	s_nop 0
	v_addc_co_u32_e32 v139, vcc, 0, v137, vcc
	global_load_dwordx2 v[142:143], v[136:137], off
	s_nop 0
	global_load_dwordx2 v[136:137], v[138:139], off
	v_add_u32_e32 v138, 0x1200, v187
	v_ashrrev_i32_e32 v144, 6, v138
	v_ashrrev_i32_e32 v145, 31, v144
	v_lshlrev_b64 v[138:139], 9, v[144:145]
	v_lshl_add_u64 v[138:139], s[12:13], 0, v[138:139]
	v_lshl_add_u64 v[138:139], v[138:139], 0, v[2:3]
	v_add_co_u32_e32 v146, vcc, s49, v138
	v_ashrrev_i32_e32 v154, 6, v141
	s_nop 0
	v_addc_co_u32_e32 v147, vcc, 0, v139, vcc
	global_load_dwordx2 v[148:149], v[138:139], off
	s_nop 0
	global_load_dwordx2 v[146:147], v[146:147], off
	v_add_u32_e32 v138, 0x1400, v187
	v_ashrrev_i32_e32 v150, 6, v138
	v_ashrrev_i32_e32 v151, 31, v150
	v_lshlrev_b64 v[138:139], 9, v[150:151]
	v_lshl_add_u64 v[138:139], s[12:13], 0, v[138:139]
	v_ashrrev_i32_e32 v155, 31, v154
	v_lshl_add_u64 v[138:139], v[138:139], 0, v[2:3]
	v_lshlrev_b64 v[156:157], 9, v[154:155]
	v_add_co_u32_e32 v152, vcc, s49, v138
	v_lshl_add_u64 v[156:157], s[12:13], 0, v[156:157]
	s_nop 0
	v_addc_co_u32_e32 v153, vcc, 0, v139, vcc
	v_lshl_add_u64 v[156:157], v[156:157], 0, v[2:3]
	v_add_co_u32_e32 v158, vcc, s49, v156
	v_add_u32_e32 v141, 0x1a00, v187
	s_nop 0
	v_addc_co_u32_e32 v159, vcc, 0, v157, vcc
	global_load_dwordx2 v[160:161], v[138:139], off
	s_nop 0
	global_load_dwordx2 v[152:153], v[152:153], off
	s_nop 0
	global_load_dwordx2 v[156:157], v[156:157], off
	s_nop 0
	global_load_dwordx2 v[158:159], v[158:159], off
	v_add_u32_e32 v138, 0x1800, v187
	v_ashrrev_i32_e32 v162, 6, v138
	v_ashrrev_i32_e32 v163, 31, v162
	v_lshlrev_b64 v[138:139], 9, v[162:163]
	v_ashrrev_i32_e32 v166, 6, v141
	v_lshl_add_u64 v[138:139], s[12:13], 0, v[138:139]
	v_ashrrev_i32_e32 v167, 31, v166
	v_lshl_add_u64 v[138:139], v[138:139], 0, v[2:3]
	v_lshlrev_b64 v[168:169], 9, v[166:167]
	v_add_co_u32_e32 v164, vcc, s49, v138
	v_lshl_add_u64 v[168:169], s[12:13], 0, v[168:169]
	s_nop 0
	v_addc_co_u32_e32 v165, vcc, 0, v139, vcc
	v_lshl_add_u64 v[168:169], v[168:169], 0, v[2:3]
	v_add_co_u32_e32 v170, vcc, s49, v168
	v_add_u32_e32 v141, 0x1e00, v187
	s_nop 0
	v_addc_co_u32_e32 v171, vcc, 0, v169, vcc
	global_load_dwordx2 v[172:173], v[138:139], off
	s_nop 0
	global_load_dwordx2 v[164:165], v[164:165], off
	s_nop 0
	global_load_dwordx2 v[168:169], v[168:169], off
	s_nop 0
	global_load_dwordx2 v[170:171], v[170:171], off
	v_add_u32_e32 v138, 0x1c00, v187
	v_ashrrev_i32_e32 v174, 6, v138
	v_ashrrev_i32_e32 v175, 31, v174
	v_lshlrev_b64 v[138:139], 9, v[174:175]
	v_ashrrev_i32_e32 v178, 6, v141
	v_lshl_add_u64 v[138:139], s[12:13], 0, v[138:139]
	v_ashrrev_i32_e32 v179, 31, v178
	v_lshl_add_u64 v[138:139], v[138:139], 0, v[2:3]
	v_lshlrev_b64 v[180:181], 9, v[178:179]
	v_add_co_u32_e32 v176, vcc, s49, v138
	v_lshl_add_u64 v[180:181], s[12:13], 0, v[180:181]
	s_nop 0
	v_addc_co_u32_e32 v177, vcc, 0, v139, vcc
	v_lshl_add_u64 v[180:181], v[180:181], 0, v[2:3]
	v_add_co_u32_e32 v182, vcc, s49, v180
	v_mad_u64_u32 v[140:141], s[20:21], v140, s52, v[4:5]
	s_nop 0
	v_addc_co_u32_e32 v183, vcc, 0, v181, vcc
	global_load_dwordx2 v[184:185], v[138:139], off
	s_nop 0
	global_load_dwordx2 v[176:177], v[176:177], off
	s_nop 0
	global_load_dwordx2 v[180:181], v[180:181], off
	s_nop 0
	global_load_dwordx2 v[182:183], v[182:183], off
	v_mov_b32_e32 v187, v1
	s_waitcnt vmcnt(15)
; __device__ __forceinline__ float bflo(unsigned v) { return __uint_as_float(v << 16); }
; __device__ __forceinline__ float bfhi(unsigned v) { return __uint_as_float(v & 0xffff0000u); }
; __device__ __forceinline__ void phase4(const Params& p, char* shm) {
;     ...
;         for (int i = 0; i < 8; ++i) { const int id = tid + (b8 * 8 + i) * NTHR, row = id >> 6, c = id & 63;
;           f32x4 rt = { bflo(ga[i][0]) * __builtin_amdgcn_rcpf(bflo(gb[i][0])), bfhi(ga[i][0]) * __builtin_amdgcn_rcpf(bfhi(gb[i][0])),
;                        bflo(ga[i][1]) * __builtin_amdgcn_rcpf(bflo(gb[i][1])), bfhi(ga[i][1]) * __builtin_amdgcn_rcpf(bfhi(gb[i][1])) };
;           *reinterpret_cast<f32x4*>(shm + (row * CF_LD + c * 4) * 4) = rt; }
;       }
;       __syncthreads();
	v_lshlrev_b32_e32 v188, 16, v142
	s_waitcnt vmcnt(14)
	v_lshlrev_b32_e32 v2, 16, v136
	v_rcp_f32_e32 v138, v2
	v_and_b32_e32 v2, 0xffff0000, v136
	v_rcp_f32_e32 v139, v2
	v_lshlrev_b32_e32 v2, 16, v137
	v_rcp_f32_e32 v190, v2
	v_and_b32_e32 v2, 0xffff0000, v137
	v_rcp_f32_e32 v191, v2
	v_and_b32_e32 v189, 0xffff0000, v142
	v_pk_mul_f32 v[136:137], v[138:139], v[188:189]
	v_lshlrev_b32_e32 v138, 16, v143
	v_and_b32_e32 v139, 0xffff0000, v143
	v_pk_mul_f32 v[138:139], v[190:191], v[138:139]
	v_lshl_add_u32 v2, v140, 2, 0
	ds_write_b128 v2, v[136:139]
	s_waitcnt vmcnt(12)
	v_lshlrev_b32_e32 v2, 16, v146
	v_rcp_f32_e32 v136, v2
	v_and_b32_e32 v2, 0xffff0000, v146
	v_rcp_f32_e32 v137, v2
	v_lshlrev_b32_e32 v2, 16, v147
	v_rcp_f32_e32 v140, v2
	v_and_b32_e32 v2, 0xffff0000, v147
	v_rcp_f32_e32 v141, v2
	v_lshlrev_b32_e32 v138, 16, v148
	v_and_b32_e32 v139, 0xffff0000, v148
	v_pk_mul_f32 v[136:137], v[136:137], v[138:139]
	v_lshlrev_b32_e32 v138, 16, v149
	v_and_b32_e32 v139, 0xffff0000, v149
	v_pk_mul_f32 v[138:139], v[140:141], v[138:139]
	v_mad_u64_u32 v[140:141], s[20:21], v144, s52, v[4:5]
	v_lshl_add_u32 v2, v140, 2, 0
	ds_write_b128 v2, v[136:139]
	s_waitcnt vmcnt(10)
	v_lshlrev_b32_e32 v2, 16, v152
	v_rcp_f32_e32 v136, v2
	v_and_b32_e32 v2, 0xffff0000, v152
	v_rcp_f32_e32 v137, v2
	v_lshlrev_b32_e32 v2, 16, v153
	v_rcp_f32_e32 v140, v2
	v_and_b32_e32 v2, 0xffff0000, v153
	v_rcp_f32_e32 v141, v2
	v_lshlrev_b32_e32 v138, 16, v160
	v_and_b32_e32 v139, 0xffff0000, v160
	v_pk_mul_f32 v[136:137], v[136:137], v[138:139]
	v_lshlrev_b32_e32 v138, 16, v161
	v_and_b32_e32 v139, 0xffff0000, v161
	v_pk_mul_f32 v[138:139], v[140:141], v[138:139]
	v_mad_u64_u32 v[140:141], s[20:21], v150, s52, v[4:5]
	v_lshl_add_u32 v2, v140, 2, 0
	ds_write_b128 v2, v[136:139]
	s_waitcnt vmcnt(8)
	v_lshlrev_b32_e32 v2, 16, v158
	v_rcp_f32_e32 v136, v2
	v_and_b32_e32 v2, 0xffff0000, v158
	v_rcp_f32_e32 v137, v2
	v_lshlrev_b32_e32 v2, 16, v159
	v_rcp_f32_e32 v140, v2
	v_and_b32_e32 v2, 0xffff0000, v159
	v_rcp_f32_e32 v141, v2
	v_lshlrev_b32_e32 v138, 16, v156
	v_and_b32_e32 v139, 0xffff0000, v156
	v_pk_mul_f32 v[136:137], v[136:137], v[138:139]
	v_lshlrev_b32_e32 v138, 16, v157
	v_and_b32_e32 v139, 0xffff0000, v157
	v_pk_mul_f32 v[138:139], v[140:141], v[138:139]
	v_mad_u64_u32 v[140:141], s[20:21], v154, s52, v[4:5]
	v_lshl_add_u32 v2, v140, 2, 0
	ds_write_b128 v2, v[136:139]
	s_waitcnt vmcnt(6)
	v_lshlrev_b32_e32 v2, 16, v164
	v_rcp_f32_e32 v136, v2
	v_and_b32_e32 v2, 0xffff0000, v164
	v_rcp_f32_e32 v137, v2
	v_lshlrev_b32_e32 v2, 16, v165
	v_rcp_f32_e32 v140, v2
	v_and_b32_e32 v2, 0xffff0000, v165
	v_rcp_f32_e32 v141, v2
	v_lshlrev_b32_e32 v138, 16, v172
	v_and_b32_e32 v139, 0xffff0000, v172
	v_pk_mul_f32 v[136:137], v[136:137], v[138:139]
	v_lshlrev_b32_e32 v138, 16, v173
	v_and_b32_e32 v139, 0xffff0000, v173
	v_pk_mul_f32 v[138:139], v[140:141], v[138:139]
	v_mad_u64_u32 v[140:141], s[20:21], v162, s52, v[4:5]
	v_lshl_add_u32 v2, v140, 2, 0
	ds_write_b128 v2, v[136:139]
	s_waitcnt vmcnt(4)
	v_lshlrev_b32_e32 v2, 16, v170
	v_rcp_f32_e32 v136, v2
	v_and_b32_e32 v2, 0xffff0000, v170
	v_rcp_f32_e32 v137, v2
	v_lshlrev_b32_e32 v2, 16, v171
	v_rcp_f32_e32 v140, v2
	v_and_b32_e32 v2, 0xffff0000, v171
	v_rcp_f32_e32 v141, v2
	v_lshlrev_b32_e32 v138, 16, v168
	v_and_b32_e32 v139, 0xffff0000, v168
	v_pk_mul_f32 v[136:137], v[136:137], v[138:139]
	v_lshlrev_b32_e32 v138, 16, v169
	v_and_b32_e32 v139, 0xffff0000, v169
	v_pk_mul_f32 v[138:139], v[140:141], v[138:139]
	v_mad_u64_u32 v[140:141], s[20:21], v166, s52, v[4:5]
	v_lshl_add_u32 v2, v140, 2, 0
	ds_write_b128 v2, v[136:139]
	s_waitcnt vmcnt(2)
	v_lshlrev_b32_e32 v2, 16, v176
	v_rcp_f32_e32 v136, v2
	v_and_b32_e32 v2, 0xffff0000, v176
	v_rcp_f32_e32 v137, v2
	v_lshlrev_b32_e32 v2, 16, v177
	v_rcp_f32_e32 v140, v2
	v_and_b32_e32 v2, 0xffff0000, v177
	v_rcp_f32_e32 v141, v2
	v_lshlrev_b32_e32 v138, 16, v184
	v_and_b32_e32 v139, 0xffff0000, v184
	v_pk_mul_f32 v[136:137], v[136:137], v[138:139]
	v_lshlrev_b32_e32 v138, 16, v185
	v_and_b32_e32 v139, 0xffff0000, v185
	v_pk_mul_f32 v[138:139], v[140:141], v[138:139]
	v_mad_u64_u32 v[140:141], s[20:21], v174, s52, v[4:5]
	v_lshl_add_u32 v2, v140, 2, 0
	ds_write_b128 v2, v[136:139]
	s_waitcnt vmcnt(0)
	v_lshlrev_b32_e32 v2, 16, v182
	v_rcp_f32_e32 v136, v2
	v_and_b32_e32 v2, 0xffff0000, v182
	v_rcp_f32_e32 v137, v2
	v_lshlrev_b32_e32 v2, 16, v183
	v_rcp_f32_e32 v140, v2
	v_and_b32_e32 v2, 0xffff0000, v183
	v_rcp_f32_e32 v141, v2
	v_lshlrev_b32_e32 v138, 16, v180
	v_and_b32_e32 v139, 0xffff0000, v180
	v_pk_mul_f32 v[136:137], v[136:137], v[138:139]
	v_lshlrev_b32_e32 v138, 16, v181
	v_and_b32_e32 v139, 0xffff0000, v181
	v_pk_mul_f32 v[138:139], v[140:141], v[138:139]
	v_mad_u64_u32 v[140:141], s[20:21], v178, s52, v[4:5]
	v_lshl_add_u32 v2, v140, 2, 0
	ds_write_b128 v2, v[136:139]
	v_add_lshl_u32 v2, v5, v134, 2
	v_add3_u32 v2, 0, v135, v2
	s_waitcnt lgkmcnt(0)
	s_barrier
; __device__ __forceinline__ float bflo(unsigned v) { return __uint_as_float(v << 16); }
; __device__ __forceinline__ float bfhi(unsigned v) { return __uint_as_float(v & 0xffff0000u); }
; __device__ __forceinline__ void phase4(const Params& p, char* shm) {
;     ...
;       const u16* gsrc = Gates + (brow + ai * 128) * 4096 + bcol;
; #pragma unroll
;       for (int b8 = 0; b8 < 2; ++b8) {
;         u32x2 ga[8], gb[8];
; #pragma unroll
;         for (int i = 0; i < 8; ++i) { const int id = tid + (b8 * 8 + i) * NTHR, row = id >> 6, c = id & 63;
;           ga[i] = *reinterpret_cast<const u32x2*>(gsrc + (size_t)row * 4096 + c * 4);
;           gb[i] = *reinterpret_cast<const u32x2*>(gsrc + (size_t)row * 4096 + 2048 + c * 4); }
; #pragma unroll
;         for (int i = 0; i < 8; ++i) { const int id = tid + (b8 * 8 + i) * NTHR, row = id >> 6, c = id & 63;
;           f32x4 rt = { bflo(ga[i][0]) * __builtin_amdgcn_rcpf(bflo(gb[i][0])), bfhi(ga[i][0]) * __builtin_amdgcn_rcpf(bfhi(gb[i][0])),
;                        bflo(ga[i][1]) * __builtin_amdgcn_rcpf(bflo(gb[i][1])), bfhi(ga[i][1]) * __builtin_amdgcn_rcpf(bfhi(gb[i][1])) };
;           *reinterpret_cast<f32x4*>(shm + (row * CF_LD + c * 4) * 4) = rt; }
;     ...
; #pragma unroll
;       for (int bj = 0; bj < 2; ++bj)
; #pragma unroll
;         for (int m = 0; m < 4; ++m)
; #pragma unroll
;           for (int n = 0; n < 2; ++n) acc[ai][bj][m][n] *= *(const f32x4*)(cfb + CF_OFF(bj, m, n));
;       __syncthreads();
	ds_read_b128 v[134:137], v2
	ds_read_b128 v[138:141], v2 offset:64
	ds_read_b128 v[142:145], v2 offset:16640
	ds_read_b128 v[146:149], v2 offset:33792
	s_waitcnt lgkmcnt(3)
	v_pk_mul_f32 v[132:133], v[132:133], v[136:137]
	v_pk_mul_f32 v[130:131], v[130:131], v[134:135]
	s_waitcnt lgkmcnt(2)
	v_pk_mul_f32 v[128:129], v[128:129], v[140:141]
	ds_read_b128 v[134:137], v2 offset:16704
	v_pk_mul_f32 v[126:127], v[126:127], v[138:139]
	ds_read_b128 v[138:141], v2 offset:33280
	s_waitcnt lgkmcnt(3)
	v_pk_mul_f32 v[124:125], v[124:125], v[144:145]
	v_pk_mul_f32 v[122:123], v[122:123], v[142:143]
	s_waitcnt lgkmcnt(1)
	v_pk_mul_f32 v[120:121], v[120:121], v[136:137]
	ds_read_b128 v[142:145], v2 offset:33344
	v_pk_mul_f32 v[118:119], v[118:119], v[134:135]
	s_waitcnt lgkmcnt(1)
	v_pk_mul_f32 v[116:117], v[116:117], v[140:141]
	ds_read_b128 v[134:137], v2 offset:49920
	v_pk_mul_f32 v[114:115], v[114:115], v[138:139]
	ds_read_b128 v[138:141], v2 offset:49984
	s_waitcnt lgkmcnt(2)
	v_pk_mul_f32 v[112:113], v[112:113], v[144:145]
	v_pk_mul_f32 v[110:111], v[110:111], v[142:143]
	ds_read_b128 v[142:145], v2 offset:512
	s_waitcnt lgkmcnt(2)
	v_pk_mul_f32 v[108:109], v[108:109], v[136:137]
	s_waitcnt lgkmcnt(1)
	v_pk_mul_f32 v[104:105], v[104:105], v[140:141]
	v_pk_mul_f32 v[102:103], v[102:103], v[138:139]
	ds_read_b128 v[138:141], v2 offset:17152
	v_pk_mul_f32 v[106:107], v[106:107], v[134:135]
	ds_read_b128 v[134:137], v2 offset:576
	s_waitcnt lgkmcnt(2)
	v_pk_mul_f32 v[100:101], v[100:101], v[144:145]
	v_pk_mul_f32 v[98:99], v[98:99], v[142:143]
	ds_read_b128 v[142:145], v2 offset:17216
	s_waitcnt lgkmcnt(2)
	v_pk_mul_f32 v[92:93], v[92:93], v[140:141]
	v_pk_mul_f32 v[90:91], v[90:91], v[138:139]
	ds_read_b128 v[138:141], v2 offset:33856
	s_waitcnt lgkmcnt(2)
	v_pk_mul_f32 v[96:97], v[96:97], v[136:137]
	v_pk_mul_f32 v[94:95], v[94:95], v[134:135]
	ds_read_b128 v[134:137], v2 offset:50432
	v_pk_mul_f32 v[82:83], v[82:83], v[146:147]
	s_waitcnt lgkmcnt(1)
	v_pk_mul_f32 v[80:81], v[80:81], v[140:141]
	v_pk_mul_f32 v[78:79], v[78:79], v[138:139]
	ds_read_b128 v[138:141], v2 offset:50496
	s_waitcnt lgkmcnt(0)
	s_barrier
	v_pk_mul_f32 v[76:77], v[76:77], v[136:137]
	v_and_b32_e32 v2, 15, v187
	v_lshrrev_b32_e32 v4, 2, v187
	v_and_or_b32 v2, v4, s51, v2
	v_mul_lo_u32 v5, v2, s52
	v_lshrrev_b32_e32 v2, 1, v187
	v_ashrrev_i32_e32 v146, 6, v187
	v_and_b32_e32 v136, 0x60, v2
	v_lshlrev_b32_e32 v2, 2, v187
	v_ashrrev_i32_e32 v147, 31, v146
	v_pk_mul_f32 v[86:87], v[86:87], v[142:143]
	v_and_b32_e32 v4, 0xfc, v2
	v_lshlrev_b64 v[142:143], 9, v[146:147]
	v_lshl_add_u64 v[142:143], s[14:15], 0, v[142:143]
	v_lshlrev_b32_e32 v2, 1, v4
	v_lshl_add_u64 v[142:143], v[142:143], 0, v[2:3]
	v_pk_mul_f32 v[88:89], v[88:89], v[144:145]
	v_add_co_u32_e32 v144, vcc, s49, v142
	v_pk_mul_f32 v[84:85], v[84:85], v[148:149]
	s_nop 0
	v_addc_co_u32_e32 v145, vcc, 0, v143, vcc
	global_load_dwordx2 v[148:149], v[142:143], off
	s_nop 0
	global_load_dwordx2 v[142:143], v[144:145], off
	v_add_u32_e32 v144, 0x200, v187
	v_ashrrev_i32_e32 v150, 6, v144
	v_ashrrev_i32_e32 v151, 31, v150
	v_lshlrev_b64 v[144:145], 9, v[150:151]
	v_lshl_add_u64 v[144:145], s[14:15], 0, v[144:145]
	v_lshl_add_u64 v[144:145], v[144:145], 0, v[2:3]
	v_add_co_u32_e32 v152, vcc, s49, v144
	v_add_u32_e32 v147, 0x600, v187
	s_nop 0
	v_addc_co_u32_e32 v153, vcc, 0, v145, vcc
	global_load_dwordx2 v[154:155], v[144:145], off
	s_nop 0
	global_load_dwordx2 v[152:153], v[152:153], off
	v_add_u32_e32 v144, 0x400, v187
	v_ashrrev_i32_e32 v156, 6, v144
	v_ashrrev_i32_e32 v157, 31, v156
	v_lshlrev_b64 v[144:145], 9, v[156:157]
	v_ashrrev_i32_e32 v160, 6, v147
	v_lshl_add_u64 v[144:145], s[14:15], 0, v[144:145]
	v_ashrrev_i32_e32 v161, 31, v160
	v_lshl_add_u64 v[144:145], v[144:145], 0, v[2:3]
	v_lshlrev_b64 v[162:163], 9, v[160:161]
	v_add_co_u32_e32 v158, vcc, s49, v144
	v_lshl_add_u64 v[162:163], s[14:15], 0, v[162:163]
	s_nop 0
	v_addc_co_u32_e32 v159, vcc, 0, v145, vcc
	v_lshl_add_u64 v[162:163], v[162:163], 0, v[2:3]
	v_add_co_u32_e32 v164, vcc, s49, v162
	v_add_u32_e32 v147, 0xa00, v187
	s_nop 0
	v_addc_co_u32_e32 v165, vcc, 0, v163, vcc
	global_load_dwordx2 v[166:167], v[144:145], off
	s_nop 0
	global_load_dwordx2 v[158:159], v[158:159], off
	s_nop 0
	global_load_dwordx2 v[162:163], v[162:163], off
	s_nop 0
	global_load_dwordx2 v[164:165], v[164:165], off
	v_add_u32_e32 v144, 0x800, v187
	v_ashrrev_i32_e32 v168, 6, v144
	v_ashrrev_i32_e32 v169, 31, v168
	v_lshlrev_b64 v[144:145], 9, v[168:169]
	v_ashrrev_i32_e32 v172, 6, v147
	v_lshl_add_u64 v[144:145], s[14:15], 0, v[144:145]
	v_ashrrev_i32_e32 v173, 31, v172
	v_lshl_add_u64 v[144:145], v[144:145], 0, v[2:3]
	v_lshlrev_b64 v[174:175], 9, v[172:173]
	v_add_co_u32_e32 v170, vcc, s49, v144
	v_lshl_add_u64 v[174:175], s[14:15], 0, v[174:175]
	s_nop 0
	v_addc_co_u32_e32 v171, vcc, 0, v145, vcc
	v_lshl_add_u64 v[174:175], v[174:175], 0, v[2:3]
	v_add_co_u32_e32 v176, vcc, s49, v174
	v_add_u32_e32 v147, 0xe00, v187
	s_nop 0
	v_addc_co_u32_e32 v177, vcc, 0, v175, vcc
	global_load_dwordx2 v[178:179], v[144:145], off
	s_nop 0
	global_load_dwordx2 v[170:171], v[170:171], off
	s_nop 0
	global_load_dwordx2 v[174:175], v[174:175], off
	s_nop 0
	global_load_dwordx2 v[176:177], v[176:177], off
	v_add_u32_e32 v144, 0xc00, v187
	v_ashrrev_i32_e32 v180, 6, v144
	v_ashrrev_i32_e32 v181, 31, v180
	v_lshlrev_b64 v[144:145], 9, v[180:181]
	v_ashrrev_i32_e32 v184, 6, v147
	v_lshl_add_u64 v[144:145], s[14:15], 0, v[144:145]
	v_ashrrev_i32_e32 v185, 31, v184
	v_lshl_add_u64 v[144:145], v[144:145], 0, v[2:3]
	v_lshlrev_b64 v[188:189], 9, v[184:185]
	v_add_co_u32_e32 v182, vcc, s49, v144
	v_lshl_add_u64 v[188:189], s[14:15], 0, v[188:189]
	s_nop 0
	v_addc_co_u32_e32 v183, vcc, 0, v145, vcc
	v_lshl_add_u64 v[188:189], v[188:189], 0, v[2:3]
	v_add_co_u32_e32 v190, vcc, s49, v188
	v_mad_u64_u32 v[146:147], s[20:21], v146, s52, v[4:5]
	s_nop 0
	v_addc_co_u32_e32 v191, vcc, 0, v189, vcc
	global_load_dwordx2 v[192:193], v[144:145], off
	s_nop 0
	global_load_dwordx2 v[182:183], v[182:183], off
	s_nop 0
	global_load_dwordx2 v[188:189], v[188:189], off
	s_nop 0
	global_load_dwordx2 v[190:191], v[190:191], off
	v_lshl_add_u32 v146, v146, 2, 0
	v_and_b32_e32 v137, 48, v187
	s_waitcnt vmcnt(15)
; __device__ __forceinline__ float bflo(unsigned v) { return __uint_as_float(v << 16); }
; __device__ __forceinline__ float bfhi(unsigned v) { return __uint_as_float(v & 0xffff0000u); }
; __device__ __forceinline__ void phase4(const Params& p, char* shm) {
;     ...
;       for (int b8 = 0; b8 < 2; ++b8) {
;         u32x2 ga[8], gb[8];
; #pragma unroll
;         for (int i = 0; i < 8; ++i) { const int id = tid + (b8 * 8 + i) * NTHR, row = id >> 6, c = id & 63;
;           ga[i] = *reinterpret_cast<const u32x2*>(gsrc + (size_t)row * 4096 + c * 4);
;           gb[i] = *reinterpret_cast<const u32x2*>(gsrc + (size_t)row * 4096 + 2048 + c * 4); }
; #pragma unroll
;         for (int i = 0; i < 8; ++i) { const int id = tid + (b8 * 8 + i) * NTHR, row = id >> 6, c = id & 63;
;           f32x4 rt = { bflo(ga[i][0]) * __builtin_amdgcn_rcpf(bflo(gb[i][0])), bfhi(ga[i][0]) * __builtin_amdgcn_rcpf(bfhi(gb[i][0])),
;                        bflo(ga[i][1]) * __builtin_amdgcn_rcpf(bflo(gb[i][1])), bfhi(ga[i][1]) * __builtin_amdgcn_rcpf(bfhi(gb[i][1])) };
;           *reinterpret_cast<f32x4*>(shm + (row * CF_LD + c * 4) * 4) = rt; }
	v_lshlrev_b32_e32 v194, 16, v148
	s_waitcnt vmcnt(14)
	v_lshlrev_b32_e32 v144, 16, v142
	v_and_b32_e32 v142, 0xffff0000, v142
	v_rcp_f32_e32 v145, v142
	v_lshlrev_b32_e32 v142, 16, v143
	v_rcp_f32_e32 v144, v144
	v_rcp_f32_e32 v196, v142
	v_and_b32_e32 v142, 0xffff0000, v143
	v_rcp_f32_e32 v197, v142
	v_and_b32_e32 v195, 0xffff0000, v148
	v_pk_mul_f32 v[142:143], v[144:145], v[194:195]
	v_lshlrev_b32_e32 v144, 16, v149
	v_and_b32_e32 v145, 0xffff0000, v149
	v_pk_mul_f32 v[144:145], v[196:197], v[144:145]
	ds_write_b128 v146, v[142:145]
	s_waitcnt vmcnt(12)
	v_lshlrev_b32_e32 v142, 16, v152
	v_and_b32_e32 v143, 0xffff0000, v152
	v_rcp_f32_e32 v142, v142
	v_rcp_f32_e32 v143, v143
	v_lshlrev_b32_e32 v146, 16, v153
	v_and_b32_e32 v147, 0xffff0000, v153
	v_rcp_f32_e32 v146, v146
	v_rcp_f32_e32 v147, v147
	v_lshlrev_b32_e32 v144, 16, v154
	v_and_b32_e32 v145, 0xffff0000, v154
	v_pk_mul_f32 v[142:143], v[142:143], v[144:145]
	v_lshlrev_b32_e32 v144, 16, v155
	v_and_b32_e32 v145, 0xffff0000, v155
	v_pk_mul_f32 v[144:145], v[146:147], v[144:145]
	v_mad_u64_u32 v[146:147], s[20:21], v150, s52, v[4:5]
	v_lshl_add_u32 v146, v146, 2, 0
	ds_write_b128 v146, v[142:145]
	s_waitcnt vmcnt(10)
	v_lshlrev_b32_e32 v142, 16, v158
	v_and_b32_e32 v143, 0xffff0000, v158
	v_rcp_f32_e32 v142, v142
	v_rcp_f32_e32 v143, v143
	v_lshlrev_b32_e32 v146, 16, v159
	v_and_b32_e32 v147, 0xffff0000, v159
	v_rcp_f32_e32 v146, v146
	v_rcp_f32_e32 v147, v147
	v_lshlrev_b32_e32 v144, 16, v166
	v_and_b32_e32 v145, 0xffff0000, v166
	v_pk_mul_f32 v[142:143], v[142:143], v[144:145]
	v_lshlrev_b32_e32 v144, 16, v167
	v_and_b32_e32 v145, 0xffff0000, v167
	v_pk_mul_f32 v[144:145], v[146:147], v[144:145]
	v_mad_u64_u32 v[146:147], s[20:21], v156, s52, v[4:5]
	v_lshl_add_u32 v146, v146, 2, 0
	ds_write_b128 v146, v[142:145]
	s_waitcnt vmcnt(8)
	v_lshlrev_b32_e32 v142, 16, v164
	v_and_b32_e32 v143, 0xffff0000, v164
	v_rcp_f32_e32 v142, v142
	v_rcp_f32_e32 v143, v143
	v_lshlrev_b32_e32 v146, 16, v165
	v_and_b32_e32 v147, 0xffff0000, v165
	v_rcp_f32_e32 v146, v146
	v_rcp_f32_e32 v147, v147
	v_lshlrev_b32_e32 v144, 16, v162
	v_and_b32_e32 v145, 0xffff0000, v162
	v_pk_mul_f32 v[142:143], v[142:143], v[144:145]
	v_lshlrev_b32_e32 v144, 16, v163
	v_and_b32_e32 v145, 0xffff0000, v163
	v_pk_mul_f32 v[144:145], v[146:147], v[144:145]
	v_mad_u64_u32 v[146:147], s[20:21], v160, s52, v[4:5]
	v_lshl_add_u32 v146, v146, 2, 0
	ds_write_b128 v146, v[142:145]
	s_waitcnt vmcnt(6)
	v_lshlrev_b32_e32 v142, 16, v170
	v_and_b32_e32 v143, 0xffff0000, v170
	v_rcp_f32_e32 v142, v142
	v_rcp_f32_e32 v143, v143
	v_lshlrev_b32_e32 v146, 16, v171
	v_and_b32_e32 v147, 0xffff0000, v171
	v_rcp_f32_e32 v146, v146
	v_rcp_f32_e32 v147, v147
	v_lshlrev_b32_e32 v144, 16, v178
	v_and_b32_e32 v145, 0xffff0000, v178
	v_pk_mul_f32 v[142:143], v[142:143], v[144:145]
	v_lshlrev_b32_e32 v144, 16, v179
	v_and_b32_e32 v145, 0xffff0000, v179
	v_pk_mul_f32 v[144:145], v[146:147], v[144:145]
	v_mad_u64_u32 v[146:147], s[20:21], v168, s52, v[4:5]
	v_lshl_add_u32 v146, v146, 2, 0
	ds_write_b128 v146, v[142:145]
	s_waitcnt vmcnt(4)
	v_lshlrev_b32_e32 v142, 16, v176
	v_and_b32_e32 v143, 0xffff0000, v176
	v_rcp_f32_e32 v142, v142
	v_rcp_f32_e32 v143, v143
	v_lshlrev_b32_e32 v146, 16, v177
	v_and_b32_e32 v147, 0xffff0000, v177
	v_rcp_f32_e32 v146, v146
	v_rcp_f32_e32 v147, v147
	v_lshlrev_b32_e32 v144, 16, v174
	v_and_b32_e32 v145, 0xffff0000, v174
	v_pk_mul_f32 v[142:143], v[142:143], v[144:145]
	v_lshlrev_b32_e32 v144, 16, v175
	v_and_b32_e32 v145, 0xffff0000, v175
	v_pk_mul_f32 v[144:145], v[146:147], v[144:145]
	v_mad_u64_u32 v[146:147], s[20:21], v172, s52, v[4:5]
	v_lshl_add_u32 v146, v146, 2, 0
	ds_write_b128 v146, v[142:145]
	s_waitcnt vmcnt(2)
	v_lshlrev_b32_e32 v142, 16, v182
	v_and_b32_e32 v143, 0xffff0000, v182
	v_rcp_f32_e32 v142, v142
	v_rcp_f32_e32 v143, v143
	v_lshlrev_b32_e32 v146, 16, v183
	v_and_b32_e32 v147, 0xffff0000, v183
	v_rcp_f32_e32 v146, v146
	v_rcp_f32_e32 v147, v147
	v_lshlrev_b32_e32 v144, 16, v192
	v_and_b32_e32 v145, 0xffff0000, v192
	v_pk_mul_f32 v[142:143], v[142:143], v[144:145]
	v_lshlrev_b32_e32 v144, 16, v193
	v_and_b32_e32 v145, 0xffff0000, v193
	v_pk_mul_f32 v[144:145], v[146:147], v[144:145]
	v_mad_u64_u32 v[146:147], s[20:21], v180, s52, v[4:5]
	v_lshl_add_u32 v146, v146, 2, 0
	ds_write_b128 v146, v[142:145]
	s_waitcnt vmcnt(0)
; __device__ __forceinline__ float bflo(unsigned v) { return __uint_as_float(v << 16); }
; __device__ __forceinline__ float bfhi(unsigned v) { return __uint_as_float(v & 0xffff0000u); }
; __device__ __forceinline__ void phase4(const Params& p, char* shm) {
;     ...
;       for (int b8 = 0; b8 < 2; ++b8) {
;         u32x2 ga[8], gb[8];
; #pragma unroll
;         for (int i = 0; i < 8; ++i) { const int id = tid + (b8 * 8 + i) * NTHR, row = id >> 6, c = id & 63;
;           ga[i] = *reinterpret_cast<const u32x2*>(gsrc + (size_t)row * 4096 + c * 4);
;           gb[i] = *reinterpret_cast<const u32x2*>(gsrc + (size_t)row * 4096 + 2048 + c * 4); }
; #pragma unroll
;         for (int i = 0; i < 8; ++i) { const int id = tid + (b8 * 8 + i) * NTHR, row = id >> 6, c = id & 63;
;           f32x4 rt = { bflo(ga[i][0]) * __builtin_amdgcn_rcpf(bflo(gb[i][0])), bfhi(ga[i][0]) * __builtin_amdgcn_rcpf(bfhi(gb[i][0])),
;                        bflo(ga[i][1]) * __builtin_amdgcn_rcpf(bflo(gb[i][1])), bfhi(ga[i][1]) * __builtin_amdgcn_rcpf(bfhi(gb[i][1])) };
;           *reinterpret_cast<f32x4*>(shm + (row * CF_LD + c * 4) * 4) = rt; }
;       }
;       __syncthreads();
; #pragma unroll
;       for (int bj = 0; bj < 2; ++bj)
; #pragma unroll
;         for (int m = 0; m < 4; ++m)
; #pragma unroll
;           for (int n = 0; n < 2; ++n) acc[ai][bj][m][n] *= *(const f32x4*)(cfb + CF_OFF(bj, m, n));
	v_lshlrev_b32_e32 v142, 16, v190
	v_and_b32_e32 v143, 0xffff0000, v190
	v_rcp_f32_e32 v142, v142
	v_rcp_f32_e32 v143, v143
	v_lshlrev_b32_e32 v146, 16, v191
	v_and_b32_e32 v147, 0xffff0000, v191
	v_rcp_f32_e32 v146, v146
	v_rcp_f32_e32 v147, v147
	v_lshlrev_b32_e32 v144, 16, v188
	v_and_b32_e32 v145, 0xffff0000, v188
	v_pk_mul_f32 v[142:143], v[142:143], v[144:145]
	v_lshlrev_b32_e32 v144, 16, v189
	v_and_b32_e32 v145, 0xffff0000, v189
	v_pk_mul_f32 v[144:145], v[146:147], v[144:145]
	v_mad_u64_u32 v[146:147], s[20:21], v184, s52, v[4:5]
	v_lshl_add_u32 v146, v146, 2, 0
	ds_write_b128 v146, v[142:145]
	v_add_u32_e32 v142, 0x1000, v187
	v_ashrrev_i32_e32 v146, 6, v142
	v_ashrrev_i32_e32 v147, 31, v146
	v_lshlrev_b64 v[142:143], 9, v[146:147]
	v_lshl_add_u64 v[142:143], s[14:15], 0, v[142:143]
	v_lshl_add_u64 v[142:143], v[142:143], 0, v[2:3]
	v_add_co_u32_e32 v144, vcc, s49, v142
	v_add_u32_e32 v147, 0x1600, v187
	s_nop 0
	v_addc_co_u32_e32 v145, vcc, 0, v143, vcc
	global_load_dwordx2 v[148:149], v[142:143], off
	s_nop 0
	global_load_dwordx2 v[142:143], v[144:145], off
	v_add_u32_e32 v144, 0x1200, v187
	v_ashrrev_i32_e32 v150, 6, v144
	v_ashrrev_i32_e32 v151, 31, v150
	v_lshlrev_b64 v[144:145], 9, v[150:151]
	v_lshl_add_u64 v[144:145], s[14:15], 0, v[144:145]
	v_lshl_add_u64 v[144:145], v[144:145], 0, v[2:3]
	v_add_co_u32_e32 v152, vcc, s49, v144
	v_ashrrev_i32_e32 v160, 6, v147
	s_nop 0
	v_addc_co_u32_e32 v153, vcc, 0, v145, vcc
	global_load_dwordx2 v[154:155], v[144:145], off
	s_nop 0
	global_load_dwordx2 v[152:153], v[152:153], off
	v_add_u32_e32 v144, 0x1400, v187
	v_ashrrev_i32_e32 v156, 6, v144
	v_ashrrev_i32_e32 v157, 31, v156
	v_lshlrev_b64 v[144:145], 9, v[156:157]
	v_lshl_add_u64 v[144:145], s[14:15], 0, v[144:145]
	v_ashrrev_i32_e32 v161, 31, v160
	v_lshl_add_u64 v[144:145], v[144:145], 0, v[2:3]
	v_lshlrev_b64 v[162:163], 9, v[160:161]
	v_add_co_u32_e32 v158, vcc, s49, v144
	v_lshl_add_u64 v[162:163], s[14:15], 0, v[162:163]
	s_nop 0
	v_addc_co_u32_e32 v159, vcc, 0, v145, vcc
	v_lshl_add_u64 v[162:163], v[162:163], 0, v[2:3]
	v_add_co_u32_e32 v164, vcc, s49, v162
	v_add_u32_e32 v147, 0x1a00, v187
	s_nop 0
	v_addc_co_u32_e32 v165, vcc, 0, v163, vcc
	global_load_dwordx2 v[166:167], v[144:145], off
	s_nop 0
	global_load_dwordx2 v[158:159], v[158:159], off
	s_nop 0
	global_load_dwordx2 v[162:163], v[162:163], off
	s_nop 0
	global_load_dwordx2 v[164:165], v[164:165], off
	v_add_u32_e32 v144, 0x1800, v187
	v_ashrrev_i32_e32 v168, 6, v144
	v_ashrrev_i32_e32 v169, 31, v168
	v_lshlrev_b64 v[144:145], 9, v[168:169]
	v_ashrrev_i32_e32 v172, 6, v147
	v_lshl_add_u64 v[144:145], s[14:15], 0, v[144:145]
	v_ashrrev_i32_e32 v173, 31, v172
	v_lshl_add_u64 v[144:145], v[144:145], 0, v[2:3]
	v_lshlrev_b64 v[174:175], 9, v[172:173]
	v_add_co_u32_e32 v170, vcc, s49, v144
	v_lshl_add_u64 v[174:175], s[14:15], 0, v[174:175]
	s_nop 0
	v_addc_co_u32_e32 v171, vcc, 0, v145, vcc
	v_lshl_add_u64 v[174:175], v[174:175], 0, v[2:3]
	v_add_co_u32_e32 v176, vcc, s49, v174
	v_add_u32_e32 v147, 0x1e00, v187
	s_nop 0
	v_addc_co_u32_e32 v177, vcc, 0, v175, vcc
	global_load_dwordx2 v[178:179], v[144:145], off
	s_nop 0
	global_load_dwordx2 v[170:171], v[170:171], off
	s_nop 0
	global_load_dwordx2 v[174:175], v[174:175], off
	s_nop 0
	global_load_dwordx2 v[176:177], v[176:177], off
	v_add_u32_e32 v144, 0x1c00, v187
	v_ashrrev_i32_e32 v180, 6, v144
	v_ashrrev_i32_e32 v181, 31, v180
	v_lshlrev_b64 v[144:145], 9, v[180:181]
	v_ashrrev_i32_e32 v184, 6, v147
	v_lshl_add_u64 v[144:145], s[14:15], 0, v[144:145]
	v_ashrrev_i32_e32 v185, 31, v184
	v_lshl_add_u64 v[144:145], v[144:145], 0, v[2:3]
	v_lshlrev_b64 v[188:189], 9, v[184:185]
	v_add_co_u32_e32 v182, vcc, s49, v144
	v_lshl_add_u64 v[188:189], s[14:15], 0, v[188:189]
	s_nop 0
	v_addc_co_u32_e32 v183, vcc, 0, v145, vcc
	v_lshl_add_u64 v[188:189], v[188:189], 0, v[2:3]
	v_add_co_u32_e32 v190, vcc, s49, v188
	v_mad_u64_u32 v[146:147], s[20:21], v146, s52, v[4:5]
	s_nop 0
	v_addc_co_u32_e32 v191, vcc, 0, v189, vcc
	global_load_dwordx2 v[192:193], v[144:145], off
	s_nop 0
	global_load_dwordx2 v[182:183], v[182:183], off
	s_nop 0
	global_load_dwordx2 v[188:189], v[188:189], off
	s_nop 0
	global_load_dwordx2 v[190:191], v[190:191], off
	v_pk_mul_f32 v[74:75], v[74:75], v[134:135]
	v_pk_mul_f32 v[72:73], v[72:73], v[140:141]
	v_pk_mul_f32 v[70:71], v[70:71], v[138:139]
	s_waitcnt vmcnt(15)
	v_lshlrev_b32_e32 v194, 16, v148
	s_waitcnt vmcnt(14)
	v_lshlrev_b32_e32 v2, 16, v142
	v_rcp_f32_e32 v144, v2
	v_and_b32_e32 v2, 0xffff0000, v142
	v_rcp_f32_e32 v145, v2
	v_lshlrev_b32_e32 v2, 16, v143
	v_rcp_f32_e32 v196, v2
	v_and_b32_e32 v2, 0xffff0000, v143
	v_rcp_f32_e32 v197, v2
	v_and_b32_e32 v195, 0xffff0000, v148
	v_pk_mul_f32 v[142:143], v[144:145], v[194:195]
	v_lshlrev_b32_e32 v144, 16, v149
	v_and_b32_e32 v145, 0xffff0000, v149
	v_pk_mul_f32 v[144:145], v[196:197], v[144:145]
	v_lshl_add_u32 v2, v146, 2, 0
	ds_write_b128 v2, v[142:145]
	s_waitcnt vmcnt(12)
	v_lshlrev_b32_e32 v2, 16, v152
	v_rcp_f32_e32 v142, v2
	v_and_b32_e32 v2, 0xffff0000, v152
	v_rcp_f32_e32 v143, v2
	v_lshlrev_b32_e32 v2, 16, v153
	v_rcp_f32_e32 v146, v2
	v_and_b32_e32 v2, 0xffff0000, v153
	v_rcp_f32_e32 v147, v2
	v_lshlrev_b32_e32 v144, 16, v154
	v_and_b32_e32 v145, 0xffff0000, v154
	v_pk_mul_f32 v[142:143], v[142:143], v[144:145]
	v_lshlrev_b32_e32 v144, 16, v155
	v_and_b32_e32 v145, 0xffff0000, v155
	v_pk_mul_f32 v[144:145], v[146:147], v[144:145]
	v_mad_u64_u32 v[146:147], s[20:21], v150, s52, v[4:5]
	v_lshl_add_u32 v2, v146, 2, 0
	ds_write_b128 v2, v[142:145]
	s_waitcnt vmcnt(10)
; __device__ __forceinline__ float bflo(unsigned v) { return __uint_as_float(v << 16); }
; __device__ __forceinline__ float bfhi(unsigned v) { return __uint_as_float(v & 0xffff0000u); }
; __device__ __forceinline__ void phase4(const Params& p, char* shm) {
;     ...
;         for (int i = 0; i < 8; ++i) { const int id = tid + (b8 * 8 + i) * NTHR, row = id >> 6, c = id & 63;
;           f32x4 rt = { bflo(ga[i][0]) * __builtin_amdgcn_rcpf(bflo(gb[i][0])), bfhi(ga[i][0]) * __builtin_amdgcn_rcpf(bfhi(gb[i][0])),
;                        bflo(ga[i][1]) * __builtin_amdgcn_rcpf(bflo(gb[i][1])), bfhi(ga[i][1]) * __builtin_amdgcn_rcpf(bfhi(gb[i][1])) };
;           *reinterpret_cast<f32x4*>(shm + (row * CF_LD + c * 4) * 4) = rt; }
;       }
;       __syncthreads();
; #pragma unroll
;       for (int bj = 0; bj < 2; ++bj)
; #pragma unroll
;         for (int m = 0; m < 4; ++m)
; #pragma unroll
;           for (int n = 0; n < 2; ++n) acc[ai][bj][m][n] *= *(const f32x4*)(cfb + CF_OFF(bj, m, n));
;       __syncthreads();
	v_lshlrev_b32_e32 v2, 16, v158
	v_rcp_f32_e32 v142, v2
	v_and_b32_e32 v2, 0xffff0000, v158
	v_rcp_f32_e32 v143, v2
	v_lshlrev_b32_e32 v2, 16, v159
	v_rcp_f32_e32 v146, v2
	v_and_b32_e32 v2, 0xffff0000, v159
	v_rcp_f32_e32 v147, v2
	v_lshlrev_b32_e32 v144, 16, v166
	v_and_b32_e32 v145, 0xffff0000, v166
	v_pk_mul_f32 v[142:143], v[142:143], v[144:145]
	v_lshlrev_b32_e32 v144, 16, v167
	v_and_b32_e32 v145, 0xffff0000, v167
	v_pk_mul_f32 v[144:145], v[146:147], v[144:145]
	v_mad_u64_u32 v[146:147], s[20:21], v156, s52, v[4:5]
	v_lshl_add_u32 v2, v146, 2, 0
	ds_write_b128 v2, v[142:145]
	s_waitcnt vmcnt(8)
	v_lshlrev_b32_e32 v2, 16, v164
	v_rcp_f32_e32 v142, v2
	v_and_b32_e32 v2, 0xffff0000, v164
	v_rcp_f32_e32 v143, v2
	v_lshlrev_b32_e32 v2, 16, v165
	v_rcp_f32_e32 v146, v2
	v_and_b32_e32 v2, 0xffff0000, v165
	v_rcp_f32_e32 v147, v2
	v_lshlrev_b32_e32 v144, 16, v162
	v_and_b32_e32 v145, 0xffff0000, v162
	v_pk_mul_f32 v[142:143], v[142:143], v[144:145]
	v_lshlrev_b32_e32 v144, 16, v163
	v_and_b32_e32 v145, 0xffff0000, v163
	v_pk_mul_f32 v[144:145], v[146:147], v[144:145]
	v_mad_u64_u32 v[146:147], s[20:21], v160, s52, v[4:5]
	v_lshl_add_u32 v2, v146, 2, 0
	ds_write_b128 v2, v[142:145]
	s_waitcnt vmcnt(6)
	v_lshlrev_b32_e32 v2, 16, v170
	v_rcp_f32_e32 v142, v2
	v_and_b32_e32 v2, 0xffff0000, v170
	v_rcp_f32_e32 v143, v2
	v_lshlrev_b32_e32 v2, 16, v171
	v_rcp_f32_e32 v146, v2
	v_and_b32_e32 v2, 0xffff0000, v171
	v_rcp_f32_e32 v147, v2
	v_lshlrev_b32_e32 v144, 16, v178
	v_and_b32_e32 v145, 0xffff0000, v178
	v_pk_mul_f32 v[142:143], v[142:143], v[144:145]
	v_lshlrev_b32_e32 v144, 16, v179
	v_and_b32_e32 v145, 0xffff0000, v179
	v_pk_mul_f32 v[144:145], v[146:147], v[144:145]
	v_mad_u64_u32 v[146:147], s[20:21], v168, s52, v[4:5]
	v_lshl_add_u32 v2, v146, 2, 0
	ds_write_b128 v2, v[142:145]
	s_waitcnt vmcnt(4)
	v_lshlrev_b32_e32 v2, 16, v176
	v_rcp_f32_e32 v142, v2
	v_and_b32_e32 v2, 0xffff0000, v176
	v_rcp_f32_e32 v143, v2
	v_lshlrev_b32_e32 v2, 16, v177
	v_rcp_f32_e32 v146, v2
	v_and_b32_e32 v2, 0xffff0000, v177
	v_rcp_f32_e32 v147, v2
	v_lshlrev_b32_e32 v144, 16, v174
	v_and_b32_e32 v145, 0xffff0000, v174
	v_pk_mul_f32 v[142:143], v[142:143], v[144:145]
	v_lshlrev_b32_e32 v144, 16, v175
	v_and_b32_e32 v145, 0xffff0000, v175
	v_pk_mul_f32 v[144:145], v[146:147], v[144:145]
	v_mad_u64_u32 v[146:147], s[20:21], v172, s52, v[4:5]
	v_lshl_add_u32 v2, v146, 2, 0
	ds_write_b128 v2, v[142:145]
	s_waitcnt vmcnt(2)
	v_lshlrev_b32_e32 v2, 16, v182
	v_rcp_f32_e32 v142, v2
	v_and_b32_e32 v2, 0xffff0000, v182
	v_rcp_f32_e32 v143, v2
	v_lshlrev_b32_e32 v2, 16, v183
	v_rcp_f32_e32 v146, v2
	v_and_b32_e32 v2, 0xffff0000, v183
	v_rcp_f32_e32 v147, v2
	v_lshlrev_b32_e32 v144, 16, v192
	v_and_b32_e32 v145, 0xffff0000, v192
	v_pk_mul_f32 v[142:143], v[142:143], v[144:145]
	v_lshlrev_b32_e32 v144, 16, v193
	v_and_b32_e32 v145, 0xffff0000, v193
	v_pk_mul_f32 v[144:145], v[146:147], v[144:145]
	v_mad_u64_u32 v[146:147], s[20:21], v180, s52, v[4:5]
	v_lshl_add_u32 v2, v146, 2, 0
	ds_write_b128 v2, v[142:145]
	s_waitcnt vmcnt(0)
	v_lshlrev_b32_e32 v2, 16, v190
	v_rcp_f32_e32 v142, v2
	v_and_b32_e32 v2, 0xffff0000, v190
	v_rcp_f32_e32 v143, v2
	v_lshlrev_b32_e32 v2, 16, v191
	v_rcp_f32_e32 v146, v2
	v_and_b32_e32 v2, 0xffff0000, v191
	v_rcp_f32_e32 v147, v2
	v_lshlrev_b32_e32 v144, 16, v188
	v_and_b32_e32 v145, 0xffff0000, v188
	v_pk_mul_f32 v[142:143], v[142:143], v[144:145]
	v_lshlrev_b32_e32 v144, 16, v189
	v_and_b32_e32 v145, 0xffff0000, v189
	v_pk_mul_f32 v[144:145], v[146:147], v[144:145]
	v_mad_u64_u32 v[146:147], s[20:21], v184, s52, v[4:5]
	v_lshl_add_u32 v2, v146, 2, 0
	ds_write_b128 v2, v[142:145]
	v_add_lshl_u32 v2, v5, v136, 2
	v_add3_u32 v2, 0, v137, v2
	s_waitcnt lgkmcnt(0)
	s_barrier
	ds_read_b128 v[142:145], v2
	ds_read_b128 v[134:137], v2 offset:64
	ds_read_b128 v[138:141], v2 offset:16640
	s_waitcnt lgkmcnt(2)
	v_pk_mul_f32 v[68:69], v[68:69], v[144:145]
	v_pk_mul_f32 v[66:67], v[66:67], v[142:143]
	ds_read_b128 v[142:145], v2 offset:16704
	s_waitcnt lgkmcnt(2)
	v_pk_mul_f32 v[64:65], v[64:65], v[136:137]
	v_pk_mul_f32 v[62:63], v[62:63], v[134:135]
	s_waitcnt lgkmcnt(1)
	v_pk_mul_f32 v[60:61], v[60:61], v[140:141]
	ds_read_b128 v[134:137], v2 offset:33280
	v_pk_mul_f32 v[58:59], v[58:59], v[138:139]
	s_waitcnt lgkmcnt(1)
	v_pk_mul_f32 v[56:57], v[56:57], v[144:145]
	ds_read_b128 v[138:141], v2 offset:33344
	v_pk_mul_f32 v[54:55], v[54:55], v[142:143]
	ds_read_b128 v[142:145], v2 offset:49920
	s_waitcnt lgkmcnt(2)
	v_pk_mul_f32 v[52:53], v[52:53], v[136:137]
	v_pk_mul_f32 v[50:51], v[50:51], v[134:135]
	s_waitcnt lgkmcnt(1)
	v_pk_mul_f32 v[48:49], v[48:49], v[140:141]
	ds_read_b128 v[134:137], v2 offset:49984
	v_pk_mul_f32 v[46:47], v[46:47], v[138:139]
	s_waitcnt lgkmcnt(1)
	v_pk_mul_f32 v[44:45], v[44:45], v[144:145]
	ds_read_b128 v[138:141], v2 offset:512
	v_pk_mul_f32 v[42:43], v[42:43], v[142:143]
	ds_read_b128 v[142:145], v2 offset:576
	s_waitcnt lgkmcnt(2)
	v_pk_mul_f32 v[40:41], v[40:41], v[136:137]
	v_pk_mul_f32 v[38:39], v[38:39], v[134:135]
	s_waitcnt lgkmcnt(1)
	v_pk_mul_f32 v[36:37], v[36:37], v[140:141]
	ds_read_b128 v[134:137], v2 offset:17152
	v_pk_mul_f32 v[34:35], v[34:35], v[138:139]
	s_waitcnt lgkmcnt(1)
	v_pk_mul_f32 v[32:33], v[32:33], v[144:145]
	ds_read_b128 v[138:141], v2 offset:17216
	v_pk_mul_f32 v[30:31], v[30:31], v[142:143]
	ds_read_b128 v[142:145], v2 offset:33792
	s_waitcnt lgkmcnt(2)
	v_pk_mul_f32 v[28:29], v[28:29], v[136:137]
	v_pk_mul_f32 v[26:27], v[26:27], v[134:135]
	s_waitcnt lgkmcnt(1)
	v_pk_mul_f32 v[24:25], v[24:25], v[140:141]
	v_pk_mul_f32 v[22:23], v[22:23], v[138:139]
	ds_read_b128 v[134:137], v2 offset:33856
	s_waitcnt lgkmcnt(1)
	v_pk_mul_f32 v[20:21], v[20:21], v[144:145]
	ds_read_b128 v[138:141], v2 offset:50432
	v_pk_mul_f32 v[18:19], v[18:19], v[142:143]
	ds_read_b128 v[142:145], v2 offset:50496
	s_waitcnt lgkmcnt(2)
	v_pk_mul_f32 v[16:17], v[16:17], v[136:137]
	v_pk_mul_f32 v[14:15], v[14:15], v[134:135]
	s_waitcnt lgkmcnt(1)
	v_pk_mul_f32 v[12:13], v[12:13], v[140:141]
	v_pk_mul_f32 v[10:11], v[10:11], v[138:139]
	s_waitcnt lgkmcnt(0)
	v_pk_mul_f32 v[8:9], v[8:9], v[144:145]
	v_pk_mul_f32 v[6:7], v[6:7], v[142:143]
	s_barrier
	s_branch .LBB0_450
; __device__ __forceinline__ void phase4(const Params& p, char* shm) {
;     ...
;     GEMM_IDS;
;     char* const ctb = CT_BASE(shm);
;     { const u16* gsrc = Gates + brow * 4096 + 2048 + bcol;
; #pragma unroll
;       for (int b8 = 0; b8 < 2; ++b8) {
;         u32x4 gv[8];
; #pragma unroll
;         for (int i = 0; i < 8; ++i) { const int id = tid + (b8 * 8 + i) * NTHR, row = id >> 5, c = id & 31;
;           gv[i] = *reinterpret_cast<const u32x4*>(gsrc + (size_t)row * 4096 + c * 8); }
; #pragma unroll
;         for (int i = 0; i < 8; ++i) { const int id = tid + (b8 * 8 + i) * NTHR, row = id >> 5, c = id & 31;
;           *reinterpret_cast<u32x4*>(shm + (row * CT_LD + c * 8) * 2) = gv[i]; }
;       }
;     }
;     __syncthreads();
.LBB0_459:
	v_mov_b32_e32 v5, v1
	s_add_u32 s8, s24, s8
	s_addc_u32 s9, s25, s9
	s_lshl_b32 s12, s63, 1
	v_lshlrev_b32_e32 v2, 3, v5
	s_lshl_b32 s98, s63, 9
	s_add_u32 s8, s8, s98
	v_and_b32_e32 v4, 0xf8, v2
	s_addc_u32 s9, s9, 0
	v_lshlrev_b32_e32 v2, 1, v4
	v_lshl_add_u64 v[134:135], s[8:9], 0, v[2:3]
	v_add_u32_e32 v2, 0x200, v5
	v_ashrrev_i32_e32 v200, 5, v5
	v_ashrrev_i32_e32 v202, 5, v2
	v_ashrrev_i32_e32 v201, 31, v200
	v_ashrrev_i32_e32 v203, 31, v202
	v_add_u32_e32 v2, 0x400, v5
	v_lshl_add_u64 v[196:197], v[134:135], 0, s[4:5]
	v_lshlrev_b64 v[134:135], 9, v[200:201]
	v_lshlrev_b64 v[136:137], 9, v[202:203]
	v_ashrrev_i32_e32 v204, 5, v2
	v_add_u32_e32 v2, 0x600, v5
	v_lshl_add_u64 v[134:135], v[196:197], 0, v[134:135]
	v_lshl_add_u64 v[138:139], v[196:197], 0, v[136:137]
	v_ashrrev_i32_e32 v206, 5, v2
	v_add_u32_e32 v2, 0x800, v5
	global_load_dwordx4 v[134:137], v[134:135], off
	s_nop 0
	global_load_dwordx4 v[138:141], v[138:139], off
	v_ashrrev_i32_e32 v205, 31, v204
	v_ashrrev_i32_e32 v207, 31, v206
	v_ashrrev_i32_e32 v208, 5, v2
	v_add_u32_e32 v2, 0xa00, v5
	v_lshlrev_b64 v[142:143], 9, v[204:205]
	v_lshlrev_b64 v[144:145], 9, v[206:207]
	v_ashrrev_i32_e32 v210, 5, v2
	v_add_u32_e32 v2, 0xc00, v5
	v_lshl_add_u64 v[142:143], v[196:197], 0, v[142:143]
	v_lshl_add_u64 v[146:147], v[196:197], 0, v[144:145]
	v_ashrrev_i32_e32 v209, 31, v208
	v_ashrrev_i32_e32 v211, 31, v210
	v_ashrrev_i32_e32 v212, 5, v2
	v_add_u32_e32 v2, 0xe00, v5
	global_load_dwordx4 v[142:145], v[142:143], off
	s_nop 0
	global_load_dwordx4 v[146:149], v[146:147], off
	v_lshlrev_b64 v[150:151], 9, v[208:209]
	v_lshlrev_b64 v[152:153], 9, v[210:211]
	v_ashrrev_i32_e32 v214, 5, v2
	v_add_u32_e32 v2, 0x1000, v5
	v_lshl_add_u64 v[150:151], v[196:197], 0, v[150:151]
	v_lshl_add_u64 v[154:155], v[196:197], 0, v[152:153]
	v_ashrrev_i32_e32 v213, 31, v212
	v_ashrrev_i32_e32 v215, 31, v214
	v_ashrrev_i32_e32 v216, 5, v2
	v_add_u32_e32 v2, 0x1200, v5
	global_load_dwordx4 v[150:153], v[150:151], off
	s_nop 0
	global_load_dwordx4 v[154:157], v[154:155], off
	v_lshlrev_b64 v[158:159], 9, v[212:213]
	v_lshlrev_b64 v[160:161], 9, v[214:215]
	v_ashrrev_i32_e32 v218, 5, v2
	v_add_u32_e32 v2, 0x1400, v5
	v_lshl_add_u64 v[158:159], v[196:197], 0, v[158:159]
	v_lshl_add_u64 v[162:163], v[196:197], 0, v[160:161]
	v_ashrrev_i32_e32 v217, 31, v216
	v_ashrrev_i32_e32 v219, 31, v218
	v_ashrrev_i32_e32 v220, 5, v2
	v_add_u32_e32 v2, 0x1600, v5
	global_load_dwordx4 v[158:161], v[158:159], off
	s_nop 0
	global_load_dwordx4 v[162:165], v[162:163], off
	v_lshlrev_b64 v[166:167], 9, v[216:217]
	v_lshlrev_b64 v[168:169], 9, v[218:219]
	v_ashrrev_i32_e32 v222, 5, v2
	v_add_u32_e32 v2, 0x1800, v5
	v_lshl_add_u64 v[166:167], v[196:197], 0, v[166:167]
	v_lshl_add_u64 v[170:171], v[196:197], 0, v[168:169]
	v_ashrrev_i32_e32 v221, 31, v220
	v_ashrrev_i32_e32 v223, 31, v222
	v_ashrrev_i32_e32 v224, 5, v2
	v_add_u32_e32 v2, 0x1a00, v5
	global_load_dwordx4 v[166:169], v[166:167], off
	s_nop 0
	global_load_dwordx4 v[170:173], v[170:171], off
	v_lshlrev_b64 v[174:175], 9, v[220:221]
	v_lshlrev_b64 v[176:177], 9, v[222:223]
	v_ashrrev_i32_e32 v226, 5, v2
	v_add_u32_e32 v2, 0x1c00, v5
	v_lshl_add_u64 v[174:175], v[196:197], 0, v[174:175]
	v_lshl_add_u64 v[178:179], v[196:197], 0, v[176:177]
	v_ashrrev_i32_e32 v225, 31, v224
	v_ashrrev_i32_e32 v227, 31, v226
	v_ashrrev_i32_e32 v228, 5, v2
	v_add_u32_e32 v2, 0x1e00, v5
	global_load_dwordx4 v[174:177], v[174:175], off
	s_nop 0
	global_load_dwordx4 v[178:181], v[178:179], off
	v_lshlrev_b64 v[182:183], 9, v[224:225]
	v_lshlrev_b64 v[184:185], 9, v[226:227]
	v_ashrrev_i32_e32 v229, 31, v228
	v_ashrrev_i32_e32 v230, 5, v2
	v_lshl_add_u64 v[182:183], v[196:197], 0, v[182:183]
	v_lshl_add_u64 v[188:189], v[196:197], 0, v[184:185]
	v_lshlrev_b64 v[192:193], 9, v[228:229]
	v_ashrrev_i32_e32 v231, 31, v230
	global_load_dwordx4 v[182:185], v[182:183], off
	s_nop 0
	global_load_dwordx4 v[188:191], v[188:189], off
	v_lshl_add_u64 v[192:193], v[196:197], 0, v[192:193]
	v_lshlrev_b64 v[198:199], 9, v[230:231]
	global_load_dwordx4 v[192:195], v[192:193], off
	v_lshl_add_u64 v[196:197], v[196:197], 0, v[198:199]
	global_load_dwordx4 v[196:199], v[196:197], off
	v_and_b32_e32 v2, 15, v5
	v_lshrrev_b32_e32 v187, 2, v5
	v_and_or_b32 v201, v187, s54, v2
	v_lshrrev_b32_e32 v2, 1, v5
	v_and_b32_e32 v2, 0x60, v2
	v_and_or_b32 v2, v187, 12, v2
	v_mad_u64_u32 v[232:233], s[8:9], v201, s55, v[2:3]
	v_mad_u64_u32 v[200:201], s[8:9], v200, s55, v[4:5]
	v_lshl_add_u32 v2, v200, 1, 0
	s_waitcnt vmcnt(15)
	ds_write_b128 v2, v[134:137]
	v_mad_u64_u32 v[134:135], s[8:9], v202, s55, v[4:5]
	v_lshl_add_u32 v2, v134, 1, 0
	v_mad_u64_u32 v[134:135], s[8:9], v204, s55, v[4:5]
	s_waitcnt vmcnt(14)
	ds_write_b128 v2, v[138:141]
	v_lshl_add_u32 v2, v134, 1, 0
	v_mad_u64_u32 v[134:135], s[8:9], v206, s55, v[4:5]
	s_waitcnt vmcnt(13)
	ds_write_b128 v2, v[142:145]
	v_lshl_add_u32 v2, v134, 1, 0
	v_mad_u64_u32 v[134:135], s[8:9], v208, s55, v[4:5]
	s_waitcnt vmcnt(12)
	ds_write_b128 v2, v[146:149]
	v_lshl_add_u32 v2, v134, 1, 0
	v_mad_u64_u32 v[134:135], s[8:9], v210, s55, v[4:5]
	s_waitcnt vmcnt(11)
	ds_write_b128 v2, v[150:153]
	v_lshl_add_u32 v2, v134, 1, 0
	v_mad_u64_u32 v[134:135], s[8:9], v212, s55, v[4:5]
	s_waitcnt vmcnt(10)
	ds_write_b128 v2, v[154:157]
	v_lshl_add_u32 v2, v134, 1, 0
	v_mad_u64_u32 v[134:135], s[8:9], v214, s55, v[4:5]
	s_waitcnt vmcnt(9)
	ds_write_b128 v2, v[158:161]
	v_lshl_add_u32 v2, v134, 1, 0
	v_mad_u64_u32 v[134:135], s[8:9], v216, s55, v[4:5]
	s_waitcnt vmcnt(8)
	ds_write_b128 v2, v[162:165]
	v_lshl_add_u32 v2, v134, 1, 0
	v_mad_u64_u32 v[134:135], s[8:9], v218, s55, v[4:5]
	s_waitcnt vmcnt(7)
	ds_write_b128 v2, v[166:169]
	v_lshl_add_u32 v2, v134, 1, 0
	v_mad_u64_u32 v[134:135], s[8:9], v220, s55, v[4:5]
	s_waitcnt vmcnt(6)
	ds_write_b128 v2, v[170:173]
	v_lshl_add_u32 v2, v134, 1, 0
	v_mad_u64_u32 v[134:135], s[8:9], v222, s55, v[4:5]
	s_waitcnt vmcnt(5)
	ds_write_b128 v2, v[174:177]
	v_lshl_add_u32 v2, v134, 1, 0
	v_mad_u64_u32 v[134:135], s[8:9], v224, s55, v[4:5]
	s_waitcnt vmcnt(4)
	ds_write_b128 v2, v[178:181]
	v_lshl_add_u32 v2, v134, 1, 0
	v_mad_u64_u32 v[134:135], s[8:9], v226, s55, v[4:5]
	s_waitcnt vmcnt(3)
	ds_write_b128 v2, v[182:185]
	v_lshl_add_u32 v2, v134, 1, 0
	v_mad_u64_u32 v[134:135], s[8:9], v228, s55, v[4:5]
	s_waitcnt vmcnt(2)
	ds_write_b128 v2, v[188:191]
	v_lshl_add_u32 v2, v134, 1, 0
	v_mad_u64_u32 v[4:5], s[8:9], v230, s55, v[4:5]
	s_waitcnt vmcnt(1)
	ds_write_b128 v2, v[192:195]
	v_lshl_add_u32 v2, v4, 1, 0
	s_waitcnt vmcnt(0)
	ds_write_b128 v2, v[196:199]
	v_lshl_add_u32 v2, v232, 1, 0
	s_waitcnt lgkmcnt(0)
	s_barrier
; __device__ __forceinline__ float bflo(unsigned v) { return __uint_as_float(v << 16); }
; __device__ __forceinline__ float bfhi(unsigned v) { return __uint_as_float(v & 0xffff0000u); }
; #define FOR_FRAG(ai, bj, m, n) _Pragma("unroll") for (int ai = 0; ai < 2; ++ai) _Pragma("unroll") for (int bj = 0; bj < 2; ++bj) \
;   _Pragma("unroll") for (int m = 0; m < 4; ++m) _Pragma("unroll") for (int n = 0; n < 2; ++n)
; __device__ __forceinline__ u32x2 pack4(float a, float b, float c, float d) { return u32x2{cvtpk(a, b), cvtpk(c, d)}; }
; __device__ __forceinline__ void phase4(const Params& p, char* shm) {
;     ...
;     FOR_FRAG(ai, bj, m, n) { u32x2* q = (u32x2*)(ctb + CT_OFF(ai, bj, m, n)); const u32x2 g = *q; const f32x4 v = acc[ai][bj][m][n];
;       *q = pack4(v[0] * bflo(g[0]), v[1] * bfhi(g[0]), v[2] * bflo(g[1]), v[3] * bfhi(g[1])); }
	ds_read_b64 v[4:5], v2
	s_waitcnt lgkmcnt(0)
	v_lshlrev_b32_e32 v134, 16, v4
	v_and_b32_e32 v4, 0xffff0000, v4
	v_mul_f32_e32 v4, v131, v4
	v_lshlrev_b32_e32 v131, 16, v5
	v_and_b32_e32 v5, 0xffff0000, v5
	v_mul_f32_e32 v130, v130, v134
	v_mul_f32_e32 v131, v132, v131
	v_mul_f32_e32 v5, v133, v5
	s_nop 0
	v_cvt_pk_bf16_f32 v4, v130, v4
	s_nop 0
	v_cvt_pk_bf16_f32 v5, v131, v5
	ds_read_b64 v[130:131], v2 offset:32
	ds_write_b64 v2, v[4:5]
	s_waitcnt lgkmcnt(1)
	v_lshlrev_b32_e32 v4, 16, v130
	v_and_b32_e32 v5, 0xffff0000, v130
	v_mul_f32_e32 v4, v126, v4
	v_mul_f32_e32 v5, v127, v5
	v_lshlrev_b32_e32 v126, 16, v131
	v_and_b32_e32 v127, 0xffff0000, v131
	v_mul_f32_e32 v126, v128, v126
	v_mul_f32_e32 v127, v129, v127
	s_nop 0
	v_cvt_pk_bf16_f32 v4, v4, v5
	s_nop 0
	v_cvt_pk_bf16_f32 v5, v126, v127
	ds_read_b64 v[126:127], v2 offset:8448
	ds_write_b64 v2, v[4:5] offset:32
	s_waitcnt lgkmcnt(1)
	v_lshlrev_b32_e32 v4, 16, v126
	v_and_b32_e32 v5, 0xffff0000, v126
	v_mul_f32_e32 v4, v122, v4
	v_mul_f32_e32 v5, v123, v5
	v_lshlrev_b32_e32 v122, 16, v127
	v_and_b32_e32 v123, 0xffff0000, v127
	v_mul_f32_e32 v122, v124, v122
	v_mul_f32_e32 v123, v125, v123
	s_nop 0
	v_cvt_pk_bf16_f32 v4, v4, v5
	s_nop 0
	v_cvt_pk_bf16_f32 v5, v122, v123
	ds_read_b64 v[122:123], v2 offset:8480
	ds_write_b64 v2, v[4:5] offset:8448
	s_waitcnt lgkmcnt(1)
	v_lshlrev_b32_e32 v4, 16, v122
	v_and_b32_e32 v5, 0xffff0000, v122
	v_mul_f32_e32 v4, v118, v4
	v_mul_f32_e32 v5, v119, v5
	v_lshlrev_b32_e32 v118, 16, v123
	v_and_b32_e32 v119, 0xffff0000, v123
	v_mul_f32_e32 v118, v120, v118
	v_mul_f32_e32 v119, v121, v119
	s_nop 0
	v_cvt_pk_bf16_f32 v4, v4, v5
	s_nop 0
	v_cvt_pk_bf16_f32 v5, v118, v119
	ds_read_b64 v[118:119], v2 offset:16896
	ds_write_b64 v2, v[4:5] offset:8480
	s_waitcnt lgkmcnt(1)
	v_lshlrev_b32_e32 v4, 16, v118
	v_and_b32_e32 v5, 0xffff0000, v118
	v_mul_f32_e32 v4, v114, v4
	v_mul_f32_e32 v5, v115, v5
	v_lshlrev_b32_e32 v114, 16, v119
	v_and_b32_e32 v115, 0xffff0000, v119
	v_mul_f32_e32 v114, v116, v114
	v_mul_f32_e32 v115, v117, v115
	s_nop 0
	v_cvt_pk_bf16_f32 v4, v4, v5
	s_nop 0
	v_cvt_pk_bf16_f32 v5, v114, v115
	ds_read_b64 v[114:115], v2 offset:16928
	ds_write_b64 v2, v[4:5] offset:16896
	s_waitcnt lgkmcnt(1)
	v_lshlrev_b32_e32 v4, 16, v114
	v_and_b32_e32 v5, 0xffff0000, v114
	v_mul_f32_e32 v4, v110, v4
	v_mul_f32_e32 v5, v111, v5
	v_lshlrev_b32_e32 v110, 16, v115
	v_and_b32_e32 v111, 0xffff0000, v115
	v_mul_f32_e32 v110, v112, v110
	v_mul_f32_e32 v111, v113, v111
	s_nop 0
	v_cvt_pk_bf16_f32 v4, v4, v5
	s_nop 0
	v_cvt_pk_bf16_f32 v5, v110, v111
	ds_read_b64 v[110:111], v2 offset:25344
	ds_write_b64 v2, v[4:5] offset:16928
	s_waitcnt lgkmcnt(1)
	v_lshlrev_b32_e32 v4, 16, v110
	v_and_b32_e32 v5, 0xffff0000, v110
	v_mul_f32_e32 v4, v106, v4
	v_mul_f32_e32 v5, v107, v5
	v_lshlrev_b32_e32 v106, 16, v111
	v_and_b32_e32 v107, 0xffff0000, v111
	v_mul_f32_e32 v106, v108, v106
	v_mul_f32_e32 v107, v109, v107
	s_nop 0
	v_cvt_pk_bf16_f32 v4, v4, v5
	s_nop 0
	v_cvt_pk_bf16_f32 v5, v106, v107
	ds_read_b64 v[106:107], v2 offset:25376
	ds_write_b64 v2, v[4:5] offset:25344
	s_waitcnt lgkmcnt(1)
	v_lshlrev_b32_e32 v4, 16, v106
	v_and_b32_e32 v5, 0xffff0000, v106
	v_mul_f32_e32 v4, v102, v4
	v_mul_f32_e32 v5, v103, v5
	v_lshlrev_b32_e32 v102, 16, v107
	v_and_b32_e32 v103, 0xffff0000, v107
	v_mul_f32_e32 v102, v104, v102
	v_mul_f32_e32 v103, v105, v103
	s_nop 0
	v_cvt_pk_bf16_f32 v4, v4, v5
	s_nop 0
	v_cvt_pk_bf16_f32 v5, v102, v103
	ds_read_b64 v[102:103], v2 offset:256
	ds_write_b64 v2, v[4:5] offset:25376
	s_waitcnt lgkmcnt(1)
	v_lshlrev_b32_e32 v4, 16, v102
	v_and_b32_e32 v5, 0xffff0000, v102
	v_mul_f32_e32 v4, v98, v4
	v_mul_f32_e32 v5, v99, v5
	v_lshlrev_b32_e32 v98, 16, v103
	v_and_b32_e32 v99, 0xffff0000, v103
	v_mul_f32_e32 v98, v100, v98
	v_mul_f32_e32 v99, v101, v99
	s_nop 0
	v_cvt_pk_bf16_f32 v4, v4, v5
	s_nop 0
	v_cvt_pk_bf16_f32 v5, v98, v99
	ds_read_b64 v[98:99], v2 offset:288
	ds_write_b64 v2, v[4:5] offset:256
	s_waitcnt lgkmcnt(1)
	v_lshlrev_b32_e32 v4, 16, v98
	v_and_b32_e32 v5, 0xffff0000, v98
	v_mul_f32_e32 v4, v94, v4
	v_mul_f32_e32 v5, v95, v5
	v_lshlrev_b32_e32 v94, 16, v99
	v_and_b32_e32 v95, 0xffff0000, v99
	v_mul_f32_e32 v94, v96, v94
	v_mul_f32_e32 v95, v97, v95
	s_nop 0
	v_cvt_pk_bf16_f32 v4, v4, v5
	s_nop 0
	v_cvt_pk_bf16_f32 v5, v94, v95
	ds_read_b64 v[94:95], v2 offset:8704
	ds_write_b64 v2, v[4:5] offset:288
	s_waitcnt lgkmcnt(1)
	v_lshlrev_b32_e32 v4, 16, v94
	v_and_b32_e32 v5, 0xffff0000, v94
	v_mul_f32_e32 v4, v90, v4
	v_mul_f32_e32 v5, v91, v5
	v_lshlrev_b32_e32 v90, 16, v95
	v_and_b32_e32 v91, 0xffff0000, v95
	v_mul_f32_e32 v90, v92, v90
	v_mul_f32_e32 v91, v93, v91
	s_nop 0
	v_cvt_pk_bf16_f32 v4, v4, v5
	s_nop 0
	v_cvt_pk_bf16_f32 v5, v90, v91
	ds_read_b64 v[90:91], v2 offset:8736
	ds_write_b64 v2, v[4:5] offset:8704
	s_waitcnt lgkmcnt(1)
	v_lshlrev_b32_e32 v4, 16, v90
	v_and_b32_e32 v5, 0xffff0000, v90
	v_mul_f32_e32 v4, v86, v4
	v_mul_f32_e32 v5, v87, v5
	v_lshlrev_b32_e32 v86, 16, v91
	v_and_b32_e32 v87, 0xffff0000, v91
	v_mul_f32_e32 v86, v88, v86
	v_mul_f32_e32 v87, v89, v87
	s_nop 0
	v_cvt_pk_bf16_f32 v4, v4, v5
	s_nop 0
	v_cvt_pk_bf16_f32 v5, v86, v87
	ds_read_b64 v[86:87], v2 offset:17152
	ds_write_b64 v2, v[4:5] offset:8736
	s_waitcnt lgkmcnt(1)
	v_lshlrev_b32_e32 v4, 16, v86
	v_and_b32_e32 v5, 0xffff0000, v86
	v_mul_f32_e32 v4, v82, v4
	v_mul_f32_e32 v5, v83, v5
	v_lshlrev_b32_e32 v82, 16, v87
	v_and_b32_e32 v83, 0xffff0000, v87
	v_mul_f32_e32 v82, v84, v82
	v_mul_f32_e32 v83, v85, v83
	s_nop 0
	v_cvt_pk_bf16_f32 v4, v4, v5
	s_nop 0
	v_cvt_pk_bf16_f32 v5, v82, v83
	ds_read_b64 v[82:83], v2 offset:17184
	ds_write_b64 v2, v[4:5] offset:17152
	s_waitcnt lgkmcnt(1)
; __device__ __forceinline__ float bflo(unsigned v) { return __uint_as_float(v << 16); }
; __device__ __forceinline__ float bfhi(unsigned v) { return __uint_as_float(v & 0xffff0000u); }
; #define FOR_FRAG(ai, bj, m, n) _Pragma("unroll") for (int ai = 0; ai < 2; ++ai) _Pragma("unroll") for (int bj = 0; bj < 2; ++bj) \
;   _Pragma("unroll") for (int m = 0; m < 4; ++m) _Pragma("unroll") for (int n = 0; n < 2; ++n)
; __device__ __forceinline__ u32x2 pack4(float a, float b, float c, float d) { return u32x2{cvtpk(a, b), cvtpk(c, d)}; }
; __device__ __forceinline__ void phase4(const Params& p, char* shm) {
;     ...
;     FOR_FRAG(ai, bj, m, n) { u32x2* q = (u32x2*)(ctb + CT_OFF(ai, bj, m, n)); const u32x2 g = *q; const f32x4 v = acc[ai][bj][m][n];
;       *q = pack4(v[0] * bflo(g[0]), v[1] * bfhi(g[0]), v[2] * bflo(g[1]), v[3] * bfhi(g[1])); }
	v_lshlrev_b32_e32 v4, 16, v82
	v_and_b32_e32 v5, 0xffff0000, v82
	v_mul_f32_e32 v4, v78, v4
	v_mul_f32_e32 v5, v79, v5
	v_lshlrev_b32_e32 v78, 16, v83
	v_and_b32_e32 v79, 0xffff0000, v83
	v_mul_f32_e32 v78, v80, v78
	v_mul_f32_e32 v79, v81, v79
	s_nop 0
	v_cvt_pk_bf16_f32 v4, v4, v5
	s_nop 0
	v_cvt_pk_bf16_f32 v5, v78, v79
	ds_read_b64 v[78:79], v2 offset:25600
	ds_write_b64 v2, v[4:5] offset:17184
	s_waitcnt lgkmcnt(1)
	v_lshlrev_b32_e32 v4, 16, v78
	v_and_b32_e32 v5, 0xffff0000, v78
	v_mul_f32_e32 v4, v74, v4
	v_mul_f32_e32 v5, v75, v5
	v_lshlrev_b32_e32 v74, 16, v79
	v_and_b32_e32 v75, 0xffff0000, v79
	v_mul_f32_e32 v74, v76, v74
	v_mul_f32_e32 v75, v77, v75
	s_nop 0
	v_cvt_pk_bf16_f32 v4, v4, v5
	s_nop 0
	v_cvt_pk_bf16_f32 v5, v74, v75
	ds_read_b64 v[74:75], v2 offset:25632
	ds_write_b64 v2, v[4:5] offset:25600
	s_waitcnt lgkmcnt(1)
	v_lshlrev_b32_e32 v4, 16, v74
	v_and_b32_e32 v5, 0xffff0000, v74
	v_mul_f32_e32 v4, v70, v4
	v_mul_f32_e32 v5, v71, v5
	v_lshlrev_b32_e32 v70, 16, v75
	v_and_b32_e32 v71, 0xffff0000, v75
	v_mul_f32_e32 v70, v72, v70
	v_mul_f32_e32 v71, v73, v71
	v_add_u32_e32 v72, 0x10800, v2
	s_nop 0
	v_cvt_pk_bf16_f32 v4, v4, v5
	s_nop 0
	v_cvt_pk_bf16_f32 v5, v70, v71
	ds_read_b64 v[70:71], v72
	ds_write_b64 v2, v[4:5] offset:25632
	s_waitcnt lgkmcnt(1)
	v_lshlrev_b32_e32 v4, 16, v70
	v_and_b32_e32 v5, 0xffff0000, v70
	v_mul_f32_e32 v4, v66, v4
	v_mul_f32_e32 v5, v67, v5
	v_lshlrev_b32_e32 v66, 16, v71
	v_and_b32_e32 v67, 0xffff0000, v71
	v_mul_f32_e32 v66, v68, v66
	v_mul_f32_e32 v67, v69, v67
	v_add_u32_e32 v68, 0x10820, v2
	s_nop 0
	v_cvt_pk_bf16_f32 v4, v4, v5
	s_nop 0
	v_cvt_pk_bf16_f32 v5, v66, v67
	ds_read_b64 v[66:67], v68
	ds_write_b64 v72, v[4:5]
	s_waitcnt lgkmcnt(1)
	v_lshlrev_b32_e32 v4, 16, v66
	v_and_b32_e32 v5, 0xffff0000, v66
	v_mul_f32_e32 v4, v62, v4
	v_mul_f32_e32 v5, v63, v5
	v_lshlrev_b32_e32 v62, 16, v67
	v_and_b32_e32 v63, 0xffff0000, v67
	v_mul_f32_e32 v62, v64, v62
	v_mul_f32_e32 v63, v65, v63
	v_add_u32_e32 v64, 0x12900, v2
	s_nop 0
	v_cvt_pk_bf16_f32 v4, v4, v5
	s_nop 0
	v_cvt_pk_bf16_f32 v5, v62, v63
	ds_read_b64 v[62:63], v64
	ds_write_b64 v68, v[4:5]
	s_waitcnt lgkmcnt(1)
	v_lshlrev_b32_e32 v4, 16, v62
	v_and_b32_e32 v5, 0xffff0000, v62
	v_mul_f32_e32 v4, v58, v4
	v_mul_f32_e32 v5, v59, v5
	v_lshlrev_b32_e32 v58, 16, v63
	v_and_b32_e32 v59, 0xffff0000, v63
	v_mul_f32_e32 v58, v60, v58
	v_mul_f32_e32 v59, v61, v59
	v_add_u32_e32 v60, 0x12920, v2
	s_nop 0
	v_cvt_pk_bf16_f32 v4, v4, v5
	s_nop 0
	v_cvt_pk_bf16_f32 v5, v58, v59
	ds_read_b64 v[58:59], v60
	ds_write_b64 v64, v[4:5]
	s_waitcnt lgkmcnt(1)
	v_lshlrev_b32_e32 v4, 16, v58
	v_and_b32_e32 v5, 0xffff0000, v58
	v_mul_f32_e32 v4, v54, v4
	v_mul_f32_e32 v5, v55, v5
	v_lshlrev_b32_e32 v54, 16, v59
	v_and_b32_e32 v55, 0xffff0000, v59
	v_mul_f32_e32 v54, v56, v54
	v_mul_f32_e32 v55, v57, v55
	v_add_u32_e32 v56, 0x14a00, v2
	s_nop 0
	v_cvt_pk_bf16_f32 v4, v4, v5
	s_nop 0
	v_cvt_pk_bf16_f32 v5, v54, v55
	ds_read_b64 v[54:55], v56
	ds_write_b64 v60, v[4:5]
	s_waitcnt lgkmcnt(1)
	v_lshlrev_b32_e32 v4, 16, v54
	v_and_b32_e32 v5, 0xffff0000, v54
	v_mul_f32_e32 v4, v50, v4
	v_mul_f32_e32 v5, v51, v5
	v_lshlrev_b32_e32 v50, 16, v55
	v_and_b32_e32 v51, 0xffff0000, v55
	v_mul_f32_e32 v50, v52, v50
	v_mul_f32_e32 v51, v53, v51
	v_add_u32_e32 v52, 0x14a20, v2
	s_nop 0
	v_cvt_pk_bf16_f32 v4, v4, v5
	s_nop 0
	v_cvt_pk_bf16_f32 v5, v50, v51
	ds_read_b64 v[50:51], v52
	ds_write_b64 v56, v[4:5]
	s_waitcnt lgkmcnt(1)
	v_lshlrev_b32_e32 v4, 16, v50
	v_and_b32_e32 v5, 0xffff0000, v50
	v_mul_f32_e32 v4, v46, v4
	v_mul_f32_e32 v5, v47, v5
	v_lshlrev_b32_e32 v46, 16, v51
	v_and_b32_e32 v47, 0xffff0000, v51
	v_mul_f32_e32 v46, v48, v46
	v_mul_f32_e32 v47, v49, v47
	v_add_u32_e32 v48, 0x16b00, v2
	s_nop 0
	v_cvt_pk_bf16_f32 v4, v4, v5
	s_nop 0
	v_cvt_pk_bf16_f32 v5, v46, v47
	ds_read_b64 v[46:47], v48
	ds_write_b64 v52, v[4:5]
	s_waitcnt lgkmcnt(1)
	v_lshlrev_b32_e32 v4, 16, v46
	v_and_b32_e32 v5, 0xffff0000, v46
	v_mul_f32_e32 v4, v42, v4
	v_mul_f32_e32 v5, v43, v5
	v_lshlrev_b32_e32 v42, 16, v47
	v_and_b32_e32 v43, 0xffff0000, v47
	v_mul_f32_e32 v42, v44, v42
	v_mul_f32_e32 v43, v45, v43
	v_add_u32_e32 v44, 0x16b20, v2
	s_nop 0
	v_cvt_pk_bf16_f32 v4, v4, v5
	s_nop 0
	v_cvt_pk_bf16_f32 v5, v42, v43
	ds_read_b64 v[42:43], v44
	ds_write_b64 v48, v[4:5]
	s_waitcnt lgkmcnt(1)
; __device__ __forceinline__ float bflo(unsigned v) { return __uint_as_float(v << 16); }
; __device__ __forceinline__ float bfhi(unsigned v) { return __uint_as_float(v & 0xffff0000u); }
; __device__ __forceinline__ int opq(int x) { asm volatile("" : "+v"(x)); return x; }
; #define FOR_FRAG(ai, bj, m, n) _Pragma("unroll") for (int ai = 0; ai < 2; ++ai) _Pragma("unroll") for (int bj = 0; bj < 2; ++bj) \
;   _Pragma("unroll") for (int m = 0; m < 4; ++m) _Pragma("unroll") for (int n = 0; n < 2; ++n)
; __device__ __forceinline__ u32x2 pack4(float a, float b, float c, float d) { return u32x2{cvtpk(a, b), cvtpk(c, d)}; }
; __device__ __forceinline__ void ct_store(const char* shm, u16* __restrict__ dst, const int ldd, const int cl2, const int lcol0) {
;   const int n = 256 << cl2;
; #pragma unroll 4
;   for (int id = opq((int)threadIdx.x); id < n; id += NTHR) {
;     const int row = id >> cl2, c = id & ((1 << cl2) - 1);
;     const u32x4 v = *reinterpret_cast<const u32x4*>(shm + (row * CT_LD + lcol0 + c * 8) * 2);
;     *reinterpret_cast<u32x4*>(dst + (size_t)row * ldd + c * 8) = v;
; __device__ __forceinline__ void phase4(const Params& p, char* shm) {
;     ...
;     FOR_FRAG(ai, bj, m, n) { u32x2* q = (u32x2*)(ctb + CT_OFF(ai, bj, m, n)); const u32x2 g = *q; const f32x4 v = acc[ai][bj][m][n];
;       *q = pack4(v[0] * bflo(g[0]), v[1] * bfhi(g[0]), v[2] * bflo(g[1]), v[3] * bfhi(g[1])); }
;     __syncthreads();
;     ct_store(shm, Mg + brow * DM + bcol, DM, 5, 0);
	v_lshlrev_b32_e32 v4, 16, v42
	v_and_b32_e32 v5, 0xffff0000, v42
	v_mul_f32_e32 v4, v38, v4
	v_mul_f32_e32 v5, v39, v5
	v_lshlrev_b32_e32 v38, 16, v43
	v_and_b32_e32 v39, 0xffff0000, v43
	v_mul_f32_e32 v38, v40, v38
	v_mul_f32_e32 v39, v41, v39
	v_add_u32_e32 v40, 0x10900, v2
	s_nop 0
	v_cvt_pk_bf16_f32 v4, v4, v5
	s_nop 0
	v_cvt_pk_bf16_f32 v5, v38, v39
	ds_read_b64 v[38:39], v40
	ds_write_b64 v44, v[4:5]
	s_waitcnt lgkmcnt(1)
	v_lshlrev_b32_e32 v4, 16, v38
	v_and_b32_e32 v5, 0xffff0000, v38
	v_mul_f32_e32 v4, v34, v4
	v_mul_f32_e32 v5, v35, v5
	v_lshlrev_b32_e32 v34, 16, v39
	v_and_b32_e32 v35, 0xffff0000, v39
	v_mul_f32_e32 v34, v36, v34
	v_mul_f32_e32 v35, v37, v35
	v_add_u32_e32 v36, 0x10920, v2
	s_nop 0
	v_cvt_pk_bf16_f32 v4, v4, v5
	s_nop 0
	v_cvt_pk_bf16_f32 v5, v34, v35
	ds_read_b64 v[34:35], v36
	ds_write_b64 v40, v[4:5]
	s_waitcnt lgkmcnt(1)
	v_lshlrev_b32_e32 v4, 16, v34
	v_and_b32_e32 v5, 0xffff0000, v34
	v_mul_f32_e32 v4, v30, v4
	v_mul_f32_e32 v5, v31, v5
	v_lshlrev_b32_e32 v30, 16, v35
	v_and_b32_e32 v31, 0xffff0000, v35
	v_mul_f32_e32 v30, v32, v30
	v_mul_f32_e32 v31, v33, v31
	v_add_u32_e32 v32, 0x12a00, v2
	s_nop 0
	v_cvt_pk_bf16_f32 v4, v4, v5
	s_nop 0
	v_cvt_pk_bf16_f32 v5, v30, v31
	ds_read_b64 v[30:31], v32
	ds_write_b64 v36, v[4:5]
	s_waitcnt lgkmcnt(1)
	v_lshlrev_b32_e32 v4, 16, v30
	v_and_b32_e32 v5, 0xffff0000, v30
	v_mul_f32_e32 v4, v26, v4
	v_mul_f32_e32 v5, v27, v5
	v_lshlrev_b32_e32 v26, 16, v31
	v_and_b32_e32 v27, 0xffff0000, v31
	v_mul_f32_e32 v26, v28, v26
	v_mul_f32_e32 v27, v29, v27
	v_add_u32_e32 v28, 0x12a20, v2
	s_nop 0
	v_cvt_pk_bf16_f32 v4, v4, v5
	s_nop 0
	v_cvt_pk_bf16_f32 v5, v26, v27
	ds_read_b64 v[26:27], v28
	ds_write_b64 v32, v[4:5]
	s_waitcnt lgkmcnt(1)
	v_lshlrev_b32_e32 v4, 16, v26
	v_and_b32_e32 v5, 0xffff0000, v26
	v_mul_f32_e32 v4, v22, v4
	v_mul_f32_e32 v5, v23, v5
	v_lshlrev_b32_e32 v22, 16, v27
	v_and_b32_e32 v23, 0xffff0000, v27
	v_mul_f32_e32 v22, v24, v22
	v_mul_f32_e32 v23, v25, v23
	v_add_u32_e32 v24, 0x14b00, v2
	s_nop 0
	v_cvt_pk_bf16_f32 v4, v4, v5
	s_nop 0
	v_cvt_pk_bf16_f32 v5, v22, v23
	ds_read_b64 v[22:23], v24
	ds_write_b64 v28, v[4:5]
	s_waitcnt lgkmcnt(1)
	v_lshlrev_b32_e32 v4, 16, v22
	v_and_b32_e32 v5, 0xffff0000, v22
	v_mul_f32_e32 v4, v18, v4
	v_mul_f32_e32 v5, v19, v5
	v_lshlrev_b32_e32 v18, 16, v23
	v_and_b32_e32 v19, 0xffff0000, v23
	v_mul_f32_e32 v18, v20, v18
	v_mul_f32_e32 v19, v21, v19
	v_add_u32_e32 v20, 0x14b20, v2
	s_nop 0
	v_cvt_pk_bf16_f32 v4, v4, v5
	s_nop 0
	v_cvt_pk_bf16_f32 v5, v18, v19
	ds_read_b64 v[18:19], v20
	ds_write_b64 v24, v[4:5]
	s_waitcnt lgkmcnt(1)
	v_lshlrev_b32_e32 v4, 16, v18
	v_and_b32_e32 v5, 0xffff0000, v18
	v_mul_f32_e32 v4, v14, v4
	v_mul_f32_e32 v5, v15, v5
	v_lshlrev_b32_e32 v14, 16, v19
	v_and_b32_e32 v15, 0xffff0000, v19
	v_mul_f32_e32 v14, v16, v14
	v_mul_f32_e32 v15, v17, v15
	v_add_u32_e32 v16, 0x16c00, v2
	s_nop 0
	v_cvt_pk_bf16_f32 v4, v4, v5
	s_nop 0
	v_cvt_pk_bf16_f32 v5, v14, v15
	ds_read_b64 v[14:15], v16
	ds_write_b64 v20, v[4:5]
	v_add_u32_e32 v2, 0x16c20, v2
	s_waitcnt lgkmcnt(1)
	v_lshlrev_b32_e32 v4, 16, v14
	v_and_b32_e32 v5, 0xffff0000, v14
	v_mul_f32_e32 v4, v10, v4
	v_mul_f32_e32 v5, v11, v5
	v_lshlrev_b32_e32 v10, 16, v15
	v_and_b32_e32 v11, 0xffff0000, v15
	v_mul_f32_e32 v10, v12, v10
	v_mul_f32_e32 v11, v13, v11
	s_nop 0
	v_cvt_pk_bf16_f32 v4, v4, v5
	s_nop 0
	v_cvt_pk_bf16_f32 v5, v10, v11
	ds_read_b64 v[10:11], v2
	ds_write_b64 v16, v[4:5]
	s_waitcnt lgkmcnt(1)
	v_lshlrev_b32_e32 v4, 16, v10
	v_mul_f32_e32 v4, v6, v4
	v_and_b32_e32 v5, 0xffff0000, v10
	v_mul_f32_e32 v5, v7, v5
	v_lshlrev_b32_e32 v6, 16, v11
	v_and_b32_e32 v7, 0xffff0000, v11
	s_nop 0
	v_cvt_pk_bf16_f32 v4, v4, v5
	v_mul_f32_e32 v6, v8, v6
	v_mul_f32_e32 v7, v9, v7
	s_nop 0
	v_cvt_pk_bf16_f32 v5, v6, v7
	ds_write_b64 v2, v[4:5]
	v_mov_b32_e32 v4, v1
	s_waitcnt lgkmcnt(0)
	s_barrier
	s_nop 0
	v_cmp_gt_i32_e32 vcc, s45, v4
	s_and_saveexec_b64 s[8:9], vcc
	s_cbranch_execz .LBB0_448
	s_lshl_b64 s[6:7], s[6:7], 20
	v_max_i32_e32 v2, 0x1e00, v4
	s_add_u32 s6, s3, s6
	v_sub_u32_e32 v2, v2, v4
	s_addc_u32 s7, s38, s7
	v_add_u32_e32 v5, 0x1ff, v2
	s_add_u32 s6, s6, s12
	v_and_b32_e32 v2, 0x600, v5
	s_addc_u32 s7, s7, 0
	v_cmp_ne_u32_e32 vcc, s53, v2
	s_and_saveexec_b64 s[12:13], vcc
	s_cbranch_execz .LBB0_464
	v_lshrrev_b32_e32 v2, 9, v5
	v_add_u32_e32 v2, 1, v2
	v_and_b32_e32 v2, 3, v2
	v_lshlrev_b32_e32 v6, 3, v4
	v_sub_u32_e32 v7, 0, v2
	s_mov_b64 s[14:15], 0
